# side-path f32 gemv: 64 weight-row loads per K half issued back to back then one in-order fma chain; scan waits leave stores in flight
# speedup vs baseline: 1.1265x; 1.0112x over previous
.LBB0_91:
	v_readlane_b32 s4, v249, 20
	v_readlane_b32 s5, v249, 21
	v_lshrrev_b32_e32 v5, 2, v54
	v_and_b32_e32 v0, 0x1fff, v54
	v_lshrrev_b32_e32 v4, 3, v54
	v_and_b32_e32 v5, 12, v5
	v_and_b32_e32 v4, 0x70, v4
	v_or_b32_e32 v4, v4, v5
	v_lshlrev_b32_e32 v0, 4, v0
	s_waitcnt lgkmcnt(0)
	v_bfe_u32 v2, v54, 13, 2
	v_ashrrev_i32_e32 v3, 8, v54
	v_and_b32_e32 v3, 0xffffff80, v3
	v_or_b32_e32 v3, v3, v2
	v_lshl_add_u32 v6, v3, 17, v0
	v_lshl_add_u32 v7, v3, 7, v4
	v_lshlrev_b32_e32 v7, 2, v7
	v_mov_b32_e32 v172, 0
	v_mov_b32_e32 v173, 0
	v_mov_b32_e32 v174, 0
	v_mov_b32_e32 v175, 0
	v_mov_b32_e32 v8, v6
	global_load_dwordx4 v[16:19], v8, s[60:61]
	v_add_u32_e32 v9, 0x80000, v6
	global_load_dwordx4 v[20:23], v9, s[60:61]
	v_add_u32_e32 v10, 0x100000, v6
	global_load_dwordx4 v[24:27], v10, s[60:61]
	v_add_u32_e32 v11, 0x180000, v6
	global_load_dwordx4 v[28:31], v11, s[60:61]
	v_add_u32_e32 v12, 0x200000, v6
	global_load_dwordx4 v[32:35], v12, s[60:61]
	v_add_u32_e32 v13, 0x280000, v6
	global_load_dwordx4 v[36:39], v13, s[60:61]
	v_add_u32_e32 v14, 0x300000, v6
	global_load_dwordx4 v[40:43], v14, s[60:61]
	v_add_u32_e32 v15, 0x380000, v6
	global_load_dwordx4 v[44:47], v15, s[60:61]
	v_mov_b32_e32 v164, v7
	global_load_dwordx4 v[96:99], v164, s[4:5]
	v_add_u32_e32 v165, 0x800, v7
	global_load_dwordx4 v[100:103], v165, s[4:5]
	v_add_u32_e32 v166, 0x1000, v7
	global_load_dwordx4 v[104:107], v166, s[4:5]
	v_add_u32_e32 v167, 0x1800, v7
	global_load_dwordx4 v[108:111], v167, s[4:5]
	v_add_u32_e32 v168, 0x2000, v7
	global_load_dwordx4 v[112:115], v168, s[4:5]
	v_add_u32_e32 v169, 0x2800, v7
	global_load_dwordx4 v[116:119], v169, s[4:5]
	v_add_u32_e32 v170, 0x3000, v7
	global_load_dwordx4 v[120:123], v170, s[4:5]
	v_add_u32_e32 v171, 0x3800, v7
	global_load_dwordx4 v[124:127], v171, s[4:5]
	v_add_u32_e32 v88, 0x400000, v6
	global_load_dwordx4 v[56:59], v88, s[60:61]
	v_add_u32_e32 v89, 0x480000, v6
	global_load_dwordx4 v[60:63], v89, s[60:61]
	v_add_u32_e32 v90, 0x500000, v6
	global_load_dwordx4 v[64:67], v90, s[60:61]
	v_add_u32_e32 v91, 0x580000, v6
	global_load_dwordx4 v[68:71], v91, s[60:61]
	v_add_u32_e32 v92, 0x600000, v6
	global_load_dwordx4 v[72:75], v92, s[60:61]
	v_add_u32_e32 v93, 0x680000, v6
	global_load_dwordx4 v[76:79], v93, s[60:61]
	v_add_u32_e32 v94, 0x700000, v6
	global_load_dwordx4 v[80:83], v94, s[60:61]
	v_add_u32_e32 v95, 0x780000, v6
	global_load_dwordx4 v[84:87], v95, s[60:61]
	v_add_u32_e32 v164, 0x4000, v7
	global_load_dwordx4 v[128:131], v164, s[4:5]
	v_add_u32_e32 v165, 0x4800, v7
	global_load_dwordx4 v[132:135], v165, s[4:5]
	v_add_u32_e32 v166, 0x5000, v7
	global_load_dwordx4 v[136:139], v166, s[4:5]
	v_add_u32_e32 v167, 0x5800, v7
	global_load_dwordx4 v[140:143], v167, s[4:5]
	v_add_u32_e32 v168, 0x6000, v7
	global_load_dwordx4 v[144:147], v168, s[4:5]
	v_add_u32_e32 v169, 0x6800, v7
	global_load_dwordx4 v[148:151], v169, s[4:5]
	v_add_u32_e32 v170, 0x7000, v7
	global_load_dwordx4 v[152:155], v170, s[4:5]
	v_add_u32_e32 v171, 0x7800, v7
	global_load_dwordx4 v[156:159], v171, s[4:5]
	s_waitcnt vmcnt(16)
	global_store_dwordx4 v8, v[172:175], s[60:61]
	v_fma_f32 v176, v172, v96, v16
	v_fma_f32 v177, v173, v97, v17
	v_fma_f32 v178, v174, v98, v18
	v_fma_f32 v179, v175, v99, v19
	global_store_dwordx4 v9, v[176:179], s[60:61]
	v_fma_f32 v172, v176, v100, v20
	v_fma_f32 v173, v177, v101, v21
	v_fma_f32 v174, v178, v102, v22
	v_fma_f32 v175, v179, v103, v23
	global_store_dwordx4 v10, v[172:175], s[60:61]
	v_fma_f32 v176, v172, v104, v24
	v_fma_f32 v177, v173, v105, v25
	v_fma_f32 v178, v174, v106, v26
	v_fma_f32 v179, v175, v107, v27
	global_store_dwordx4 v11, v[176:179], s[60:61]
	v_fma_f32 v172, v176, v108, v28
	v_fma_f32 v173, v177, v109, v29
	v_fma_f32 v174, v178, v110, v30
	v_fma_f32 v175, v179, v111, v31
	global_store_dwordx4 v12, v[172:175], s[60:61]
	v_fma_f32 v176, v172, v112, v32
	v_fma_f32 v177, v173, v113, v33
	v_fma_f32 v178, v174, v114, v34
	v_fma_f32 v179, v175, v115, v35
	global_store_dwordx4 v13, v[176:179], s[60:61]
	v_fma_f32 v172, v176, v116, v36
	v_fma_f32 v173, v177, v117, v37
	v_fma_f32 v174, v178, v118, v38
	v_fma_f32 v175, v179, v119, v39
	global_store_dwordx4 v14, v[172:175], s[60:61]
	v_fma_f32 v176, v172, v120, v40
	v_fma_f32 v177, v173, v121, v41
	v_fma_f32 v178, v174, v122, v42
	v_fma_f32 v179, v175, v123, v43
	global_store_dwordx4 v15, v[176:179], s[60:61]
	v_fma_f32 v172, v176, v124, v44
	v_fma_f32 v173, v177, v125, v45
	v_fma_f32 v174, v178, v126, v46
	v_fma_f32 v175, v179, v127, v47
	v_add_u32_e32 v8, 0x800000, v6
	global_load_dwordx4 v[16:19], v8, s[60:61]
	v_add_u32_e32 v9, 0x880000, v6
	global_load_dwordx4 v[20:23], v9, s[60:61]
	v_add_u32_e32 v10, 0x900000, v6
	global_load_dwordx4 v[24:27], v10, s[60:61]
	v_add_u32_e32 v11, 0x980000, v6
	global_load_dwordx4 v[28:31], v11, s[60:61]
	v_add_u32_e32 v12, 0xa00000, v6
	global_load_dwordx4 v[32:35], v12, s[60:61]
	v_add_u32_e32 v13, 0xa80000, v6
	global_load_dwordx4 v[36:39], v13, s[60:61]
	v_add_u32_e32 v14, 0xb00000, v6
	global_load_dwordx4 v[40:43], v14, s[60:61]
	v_add_u32_e32 v15, 0xb80000, v6
	global_load_dwordx4 v[44:47], v15, s[60:61]
	v_add_u32_e32 v164, 0x8000, v7
	global_load_dwordx4 v[96:99], v164, s[4:5]
	v_add_u32_e32 v165, 0x8800, v7
	global_load_dwordx4 v[100:103], v165, s[4:5]
	v_add_u32_e32 v166, 0x9000, v7
	global_load_dwordx4 v[104:107], v166, s[4:5]
	v_add_u32_e32 v167, 0x9800, v7
	global_load_dwordx4 v[108:111], v167, s[4:5]
	v_add_u32_e32 v168, 0xa000, v7
	global_load_dwordx4 v[112:115], v168, s[4:5]
	v_add_u32_e32 v169, 0xa800, v7
	global_load_dwordx4 v[116:119], v169, s[4:5]
	v_add_u32_e32 v170, 0xb000, v7
	global_load_dwordx4 v[120:123], v170, s[4:5]
	v_add_u32_e32 v171, 0xb800, v7
	global_load_dwordx4 v[124:127], v171, s[4:5]
	s_waitcnt vmcnt(24)
	global_store_dwordx4 v88, v[172:175], s[60:61]
	v_fma_f32 v176, v172, v128, v56
	v_fma_f32 v177, v173, v129, v57
	v_fma_f32 v178, v174, v130, v58
	v_fma_f32 v179, v175, v131, v59
	global_store_dwordx4 v89, v[176:179], s[60:61]
	v_fma_f32 v172, v176, v132, v60
	v_fma_f32 v173, v177, v133, v61
	v_fma_f32 v174, v178, v134, v62
	v_fma_f32 v175, v179, v135, v63
	global_store_dwordx4 v90, v[172:175], s[60:61]
	v_fma_f32 v176, v172, v136, v64
	v_fma_f32 v177, v173, v137, v65
	v_fma_f32 v178, v174, v138, v66
	v_fma_f32 v179, v175, v139, v67
	global_store_dwordx4 v91, v[176:179], s[60:61]
	v_fma_f32 v172, v176, v140, v68
	v_fma_f32 v173, v177, v141, v69
	v_fma_f32 v174, v178, v142, v70
	v_fma_f32 v175, v179, v143, v71
	global_store_dwordx4 v92, v[172:175], s[60:61]
	v_fma_f32 v176, v172, v144, v72
	v_fma_f32 v177, v173, v145, v73
	v_fma_f32 v178, v174, v146, v74
	v_fma_f32 v179, v175, v147, v75
	global_store_dwordx4 v93, v[176:179], s[60:61]
	v_fma_f32 v172, v176, v148, v76
	v_fma_f32 v173, v177, v149, v77
	v_fma_f32 v174, v178, v150, v78
	v_fma_f32 v175, v179, v151, v79
	global_store_dwordx4 v94, v[172:175], s[60:61]
	v_fma_f32 v176, v172, v152, v80
	v_fma_f32 v177, v173, v153, v81
	v_fma_f32 v178, v174, v154, v82
	v_fma_f32 v179, v175, v155, v83
	global_store_dwordx4 v95, v[176:179], s[60:61]
	v_fma_f32 v172, v176, v156, v84
	v_fma_f32 v173, v177, v157, v85
	v_fma_f32 v174, v178, v158, v86
	v_fma_f32 v175, v179, v159, v87
	v_add_u32_e32 v88, 0xc00000, v6
	global_load_dwordx4 v[56:59], v88, s[60:61]
	v_add_u32_e32 v89, 0xc80000, v6
	global_load_dwordx4 v[60:63], v89, s[60:61]
	v_add_u32_e32 v90, 0xd00000, v6
	global_load_dwordx4 v[64:67], v90, s[60:61]
	v_add_u32_e32 v91, 0xd80000, v6
	global_load_dwordx4 v[68:71], v91, s[60:61]
	v_add_u32_e32 v92, 0xe00000, v6
	global_load_dwordx4 v[72:75], v92, s[60:61]
	v_add_u32_e32 v93, 0xe80000, v6
	global_load_dwordx4 v[76:79], v93, s[60:61]
	v_add_u32_e32 v94, 0xf00000, v6
	global_load_dwordx4 v[80:83], v94, s[60:61]
	v_add_u32_e32 v95, 0xf80000, v6
	global_load_dwordx4 v[84:87], v95, s[60:61]
	v_add_u32_e32 v164, 0xc000, v7
	global_load_dwordx4 v[128:131], v164, s[4:5]
	v_add_u32_e32 v165, 0xc800, v7
	global_load_dwordx4 v[132:135], v165, s[4:5]
	v_add_u32_e32 v166, 0xd000, v7
	global_load_dwordx4 v[136:139], v166, s[4:5]
	v_add_u32_e32 v167, 0xd800, v7
	global_load_dwordx4 v[140:143], v167, s[4:5]
	v_add_u32_e32 v168, 0xe000, v7
	global_load_dwordx4 v[144:147], v168, s[4:5]
	v_add_u32_e32 v169, 0xe800, v7
	global_load_dwordx4 v[148:151], v169, s[4:5]
	v_add_u32_e32 v170, 0xf000, v7
	global_load_dwordx4 v[152:155], v170, s[4:5]
	v_add_u32_e32 v171, 0xf800, v7
	global_load_dwordx4 v[156:159], v171, s[4:5]
	s_waitcnt vmcnt(24)
	global_store_dwordx4 v8, v[172:175], s[60:61]
	v_fma_f32 v176, v172, v96, v16
	v_fma_f32 v177, v173, v97, v17
	v_fma_f32 v178, v174, v98, v18
	v_fma_f32 v179, v175, v99, v19
	global_store_dwordx4 v9, v[176:179], s[60:61]
	v_fma_f32 v172, v176, v100, v20
	v_fma_f32 v173, v177, v101, v21
	v_fma_f32 v174, v178, v102, v22
	v_fma_f32 v175, v179, v103, v23
	global_store_dwordx4 v10, v[172:175], s[60:61]
	v_fma_f32 v176, v172, v104, v24
	v_fma_f32 v177, v173, v105, v25
	v_fma_f32 v178, v174, v106, v26
	v_fma_f32 v179, v175, v107, v27
	global_store_dwordx4 v11, v[176:179], s[60:61]
	v_fma_f32 v172, v176, v108, v28
	v_fma_f32 v173, v177, v109, v29
	v_fma_f32 v174, v178, v110, v30
	v_fma_f32 v175, v179, v111, v31
	global_store_dwordx4 v12, v[172:175], s[60:61]
	v_fma_f32 v176, v172, v112, v32
	v_fma_f32 v177, v173, v113, v33
	v_fma_f32 v178, v174, v114, v34
	v_fma_f32 v179, v175, v115, v35
	global_store_dwordx4 v13, v[176:179], s[60:61]
	v_fma_f32 v172, v176, v116, v36
	v_fma_f32 v173, v177, v117, v37
	v_fma_f32 v174, v178, v118, v38
	v_fma_f32 v175, v179, v119, v39
	global_store_dwordx4 v14, v[172:175], s[60:61]
	v_fma_f32 v176, v172, v120, v40
	v_fma_f32 v177, v173, v121, v41
	v_fma_f32 v178, v174, v122, v42
	v_fma_f32 v179, v175, v123, v43
	global_store_dwordx4 v15, v[176:179], s[60:61]
	v_fma_f32 v172, v176, v124, v44
	v_fma_f32 v173, v177, v125, v45
	v_fma_f32 v174, v178, v126, v46
	v_fma_f32 v175, v179, v127, v47
	s_waitcnt vmcnt(8)
	global_store_dwordx4 v88, v[172:175], s[60:61]
	v_fma_f32 v176, v172, v128, v56
	v_fma_f32 v177, v173, v129, v57
	v_fma_f32 v178, v174, v130, v58
	v_fma_f32 v179, v175, v131, v59
	global_store_dwordx4 v89, v[176:179], s[60:61]
	v_fma_f32 v172, v176, v132, v60
	v_fma_f32 v173, v177, v133, v61
	v_fma_f32 v174, v178, v134, v62
	v_fma_f32 v175, v179, v135, v63
	global_store_dwordx4 v90, v[172:175], s[60:61]
	v_fma_f32 v176, v172, v136, v64
	v_fma_f32 v177, v173, v137, v65
	v_fma_f32 v178, v174, v138, v66
	v_fma_f32 v179, v175, v139, v67
	global_store_dwordx4 v91, v[176:179], s[60:61]
	v_fma_f32 v172, v176, v140, v68
	v_fma_f32 v173, v177, v141, v69
	v_fma_f32 v174, v178, v142, v70
	v_fma_f32 v175, v179, v143, v71
	global_store_dwordx4 v92, v[172:175], s[60:61]
	v_fma_f32 v176, v172, v144, v72
	v_fma_f32 v177, v173, v145, v73
	v_fma_f32 v178, v174, v146, v74
	v_fma_f32 v179, v175, v147, v75
	global_store_dwordx4 v93, v[176:179], s[60:61]
	v_fma_f32 v172, v176, v148, v76
	v_fma_f32 v173, v177, v149, v77
	v_fma_f32 v174, v178, v150, v78
	v_fma_f32 v175, v179, v151, v79
	global_store_dwordx4 v94, v[172:175], s[60:61]
	v_fma_f32 v176, v172, v152, v80
	v_fma_f32 v177, v173, v153, v81
	v_fma_f32 v178, v174, v154, v82
	v_fma_f32 v179, v175, v155, v83
	global_store_dwordx4 v95, v[176:179], s[60:61]
	v_fma_f32 v172, v176, v156, v84
	v_fma_f32 v173, v177, v157, v85
	v_fma_f32 v174, v178, v158, v86
	v_fma_f32 v175, v179, v159, v87
	v_readlane_b32 s4, v254, 2
	v_readlane_b32 s5, v254, 3
	s_nop 0
	v_add_u32_e32 v54, s4, v54
	v_cmp_lt_i32_e32 vcc, s6, v54
	s_or_b64 s[2:3], vcc, s[2:3]
	s_andn2_b64 exec, exec, s[2:3]
	s_cbranch_execnz .LBB0_91

.LBB0_332:
	v_and_b32_e32 v0, 0x7ff, v8
	v_lshlrev_b32_e32 v0, 4, v0
	s_waitcnt lgkmcnt(0)
	v_bfe_u32 v2, v8, 11, 5
	v_ashrrev_i32_e32 v3, 6, v8
	s_movk_i32 s4, 0xfc00
	v_and_or_b32 v3, v3, s4, v2
	v_lshl_add_u32 v4, v3, 15, v0
	v_lshlrev_b32_e32 v5, 2, v3
	v_mov_b32_e32 v112, 0
	v_mov_b32_e32 v113, 0
	v_mov_b32_e32 v114, 0
	v_mov_b32_e32 v115, 0
	v_mov_b32_e32 v48, v4
	global_load_dwordx4 v[16:19], v48, s[88:89]
	v_add_u32_e32 v49, 0x100000, v4
	global_load_dwordx4 v[20:23], v49, s[88:89]
	v_add_u32_e32 v50, 0x200000, v4
	global_load_dwordx4 v[24:27], v50, s[88:89]
	v_add_u32_e32 v51, 0x300000, v4
	global_load_dwordx4 v[28:31], v51, s[88:89]
	v_add_u32_e32 v52, 0x400000, v4
	global_load_dwordx4 v[32:35], v52, s[88:89]
	v_add_u32_e32 v53, 0x500000, v4
	global_load_dwordx4 v[36:39], v53, s[88:89]
	v_add_u32_e32 v54, 0x600000, v4
	global_load_dwordx4 v[40:43], v54, s[88:89]
	v_add_u32_e32 v55, 0x700000, v4
	global_load_dwordx4 v[44:47], v55, s[88:89]
	global_load_dword v96, v5, s[24:25]
	global_load_dword v97, v5, s[24:25] offset:128
	global_load_dword v98, v5, s[24:25] offset:256
	global_load_dword v99, v5, s[24:25] offset:384
	global_load_dword v100, v5, s[24:25] offset:512
	global_load_dword v101, v5, s[24:25] offset:640
	global_load_dword v102, v5, s[24:25] offset:768
	global_load_dword v103, v5, s[24:25] offset:896
	v_add_u32_e32 v88, 0x800000, v4
	global_load_dwordx4 v[56:59], v88, s[88:89]
	v_add_u32_e32 v89, 0x900000, v4
	global_load_dwordx4 v[60:63], v89, s[88:89]
	v_add_u32_e32 v90, 0xa00000, v4
	global_load_dwordx4 v[64:67], v90, s[88:89]
	v_add_u32_e32 v91, 0xb00000, v4
	global_load_dwordx4 v[68:71], v91, s[88:89]
	v_add_u32_e32 v92, 0xc00000, v4
	global_load_dwordx4 v[72:75], v92, s[88:89]
	v_add_u32_e32 v93, 0xd00000, v4
	global_load_dwordx4 v[76:79], v93, s[88:89]
	v_add_u32_e32 v94, 0xe00000, v4
	global_load_dwordx4 v[80:83], v94, s[88:89]
	v_add_u32_e32 v95, 0xf00000, v4
	global_load_dwordx4 v[84:87], v95, s[88:89]
	global_load_dword v104, v5, s[24:25] offset:1024
	global_load_dword v105, v5, s[24:25] offset:1152
	global_load_dword v106, v5, s[24:25] offset:1280
	global_load_dword v107, v5, s[24:25] offset:1408
	global_load_dword v108, v5, s[24:25] offset:1536
	global_load_dword v109, v5, s[24:25] offset:1664
	global_load_dword v110, v5, s[24:25] offset:1792
	global_load_dword v111, v5, s[24:25] offset:1920
	s_waitcnt vmcnt(16)
	global_store_dwordx4 v48, v[112:115], s[88:89]
	v_fma_f32 v116, v112, v96, v16
	v_fma_f32 v117, v113, v96, v17
	v_fma_f32 v118, v114, v96, v18
	v_fma_f32 v119, v115, v96, v19
	global_store_dwordx4 v49, v[116:119], s[88:89]
	v_fma_f32 v112, v116, v97, v20
	v_fma_f32 v113, v117, v97, v21
	v_fma_f32 v114, v118, v97, v22
	v_fma_f32 v115, v119, v97, v23
	global_store_dwordx4 v50, v[112:115], s[88:89]
	v_fma_f32 v116, v112, v98, v24
	v_fma_f32 v117, v113, v98, v25
	v_fma_f32 v118, v114, v98, v26
	v_fma_f32 v119, v115, v98, v27
	global_store_dwordx4 v51, v[116:119], s[88:89]
	v_fma_f32 v112, v116, v99, v28
	v_fma_f32 v113, v117, v99, v29
	v_fma_f32 v114, v118, v99, v30
	v_fma_f32 v115, v119, v99, v31
	global_store_dwordx4 v52, v[112:115], s[88:89]
	v_fma_f32 v116, v112, v100, v32
	v_fma_f32 v117, v113, v100, v33
	v_fma_f32 v118, v114, v100, v34
	v_fma_f32 v119, v115, v100, v35
	global_store_dwordx4 v53, v[116:119], s[88:89]
	v_fma_f32 v112, v116, v101, v36
	v_fma_f32 v113, v117, v101, v37
	v_fma_f32 v114, v118, v101, v38
	v_fma_f32 v115, v119, v101, v39
	global_store_dwordx4 v54, v[112:115], s[88:89]
	v_fma_f32 v116, v112, v102, v40
	v_fma_f32 v117, v113, v102, v41
	v_fma_f32 v118, v114, v102, v42
	v_fma_f32 v119, v115, v102, v43
	global_store_dwordx4 v55, v[116:119], s[88:89]
	v_fma_f32 v112, v116, v103, v44
	v_fma_f32 v113, v117, v103, v45
	v_fma_f32 v114, v118, v103, v46
	v_fma_f32 v115, v119, v103, v47
	v_add_u32_e32 v48, 0x1000000, v4
	global_load_dwordx4 v[16:19], v48, s[88:89]
	v_add_u32_e32 v49, 0x1100000, v4
	global_load_dwordx4 v[20:23], v49, s[88:89]
	v_add_u32_e32 v50, 0x1200000, v4
	global_load_dwordx4 v[24:27], v50, s[88:89]
	v_add_u32_e32 v51, 0x1300000, v4
	global_load_dwordx4 v[28:31], v51, s[88:89]
	v_add_u32_e32 v52, 0x1400000, v4
	global_load_dwordx4 v[32:35], v52, s[88:89]
	v_add_u32_e32 v53, 0x1500000, v4
	global_load_dwordx4 v[36:39], v53, s[88:89]
	v_add_u32_e32 v54, 0x1600000, v4
	global_load_dwordx4 v[40:43], v54, s[88:89]
	v_add_u32_e32 v55, 0x1700000, v4
	global_load_dwordx4 v[44:47], v55, s[88:89]
	global_load_dword v96, v5, s[24:25] offset:2048
	global_load_dword v97, v5, s[24:25] offset:2176
	global_load_dword v98, v5, s[24:25] offset:2304
	global_load_dword v99, v5, s[24:25] offset:2432
	global_load_dword v100, v5, s[24:25] offset:2560
	global_load_dword v101, v5, s[24:25] offset:2688
	global_load_dword v102, v5, s[24:25] offset:2816
	global_load_dword v103, v5, s[24:25] offset:2944
	s_waitcnt vmcnt(24)
	global_store_dwordx4 v88, v[112:115], s[88:89]
	v_fma_f32 v116, v112, v104, v56
	v_fma_f32 v117, v113, v104, v57
	v_fma_f32 v118, v114, v104, v58
	v_fma_f32 v119, v115, v104, v59
	global_store_dwordx4 v89, v[116:119], s[88:89]
	v_fma_f32 v112, v116, v105, v60
	v_fma_f32 v113, v117, v105, v61
	v_fma_f32 v114, v118, v105, v62
	v_fma_f32 v115, v119, v105, v63
	global_store_dwordx4 v90, v[112:115], s[88:89]
	v_fma_f32 v116, v112, v106, v64
	v_fma_f32 v117, v113, v106, v65
	v_fma_f32 v118, v114, v106, v66
	v_fma_f32 v119, v115, v106, v67
	global_store_dwordx4 v91, v[116:119], s[88:89]
	v_fma_f32 v112, v116, v107, v68
	v_fma_f32 v113, v117, v107, v69
	v_fma_f32 v114, v118, v107, v70
	v_fma_f32 v115, v119, v107, v71
	global_store_dwordx4 v92, v[112:115], s[88:89]
	v_fma_f32 v116, v112, v108, v72
	v_fma_f32 v117, v113, v108, v73
	v_fma_f32 v118, v114, v108, v74
	v_fma_f32 v119, v115, v108, v75
	global_store_dwordx4 v93, v[116:119], s[88:89]
	v_fma_f32 v112, v116, v109, v76
	v_fma_f32 v113, v117, v109, v77
	v_fma_f32 v114, v118, v109, v78
	v_fma_f32 v115, v119, v109, v79
	global_store_dwordx4 v94, v[112:115], s[88:89]
	v_fma_f32 v116, v112, v110, v80
	v_fma_f32 v117, v113, v110, v81
	v_fma_f32 v118, v114, v110, v82
	v_fma_f32 v119, v115, v110, v83
	global_store_dwordx4 v95, v[116:119], s[88:89]
	v_fma_f32 v112, v116, v111, v84
	v_fma_f32 v113, v117, v111, v85
	v_fma_f32 v114, v118, v111, v86
	v_fma_f32 v115, v119, v111, v87
	v_add_u32_e32 v88, 0x1800000, v4
	global_load_dwordx4 v[56:59], v88, s[88:89]
	v_add_u32_e32 v89, 0x1900000, v4
	global_load_dwordx4 v[60:63], v89, s[88:89]
	v_add_u32_e32 v90, 0x1a00000, v4
	global_load_dwordx4 v[64:67], v90, s[88:89]
	v_add_u32_e32 v91, 0x1b00000, v4
	global_load_dwordx4 v[68:71], v91, s[88:89]
	v_add_u32_e32 v92, 0x1c00000, v4
	global_load_dwordx4 v[72:75], v92, s[88:89]
	v_add_u32_e32 v93, 0x1d00000, v4
	global_load_dwordx4 v[76:79], v93, s[88:89]
	v_add_u32_e32 v94, 0x1e00000, v4
	global_load_dwordx4 v[80:83], v94, s[88:89]
	v_add_u32_e32 v95, 0x1f00000, v4
	global_load_dwordx4 v[84:87], v95, s[88:89]
	global_load_dword v104, v5, s[24:25] offset:3072
	global_load_dword v105, v5, s[24:25] offset:3200
	global_load_dword v106, v5, s[24:25] offset:3328
	global_load_dword v107, v5, s[24:25] offset:3456
	global_load_dword v108, v5, s[24:25] offset:3584
	global_load_dword v109, v5, s[24:25] offset:3712
	global_load_dword v110, v5, s[24:25] offset:3840
	global_load_dword v111, v5, s[24:25] offset:3968
	s_waitcnt vmcnt(24)
	global_store_dwordx4 v48, v[112:115], s[88:89]
	v_fma_f32 v116, v112, v96, v16
	v_fma_f32 v117, v113, v96, v17
	v_fma_f32 v118, v114, v96, v18
	v_fma_f32 v119, v115, v96, v19
	global_store_dwordx4 v49, v[116:119], s[88:89]
	v_fma_f32 v112, v116, v97, v20
	v_fma_f32 v113, v117, v97, v21
	v_fma_f32 v114, v118, v97, v22
	v_fma_f32 v115, v119, v97, v23
	global_store_dwordx4 v50, v[112:115], s[88:89]
	v_fma_f32 v116, v112, v98, v24
	v_fma_f32 v117, v113, v98, v25
	v_fma_f32 v118, v114, v98, v26
	v_fma_f32 v119, v115, v98, v27
	global_store_dwordx4 v51, v[116:119], s[88:89]
	v_fma_f32 v112, v116, v99, v28
	v_fma_f32 v113, v117, v99, v29
	v_fma_f32 v114, v118, v99, v30
	v_fma_f32 v115, v119, v99, v31
	global_store_dwordx4 v52, v[112:115], s[88:89]
	v_fma_f32 v116, v112, v100, v32
	v_fma_f32 v117, v113, v100, v33
	v_fma_f32 v118, v114, v100, v34
	v_fma_f32 v119, v115, v100, v35
	global_store_dwordx4 v53, v[116:119], s[88:89]
	v_fma_f32 v112, v116, v101, v36
	v_fma_f32 v113, v117, v101, v37
	v_fma_f32 v114, v118, v101, v38
	v_fma_f32 v115, v119, v101, v39
	global_store_dwordx4 v54, v[112:115], s[88:89]
	v_fma_f32 v116, v112, v102, v40
	v_fma_f32 v117, v113, v102, v41
	v_fma_f32 v118, v114, v102, v42
	v_fma_f32 v119, v115, v102, v43
	global_store_dwordx4 v55, v[116:119], s[88:89]
	v_fma_f32 v112, v116, v103, v44
	v_fma_f32 v113, v117, v103, v45
	v_fma_f32 v114, v118, v103, v46
	v_fma_f32 v115, v119, v103, v47
	s_waitcnt vmcnt(8)
	global_store_dwordx4 v88, v[112:115], s[88:89]
	v_fma_f32 v116, v112, v104, v56
	v_fma_f32 v117, v113, v104, v57
	v_fma_f32 v118, v114, v104, v58
	v_fma_f32 v119, v115, v104, v59
	global_store_dwordx4 v89, v[116:119], s[88:89]
	v_fma_f32 v112, v116, v105, v60
	v_fma_f32 v113, v117, v105, v61
	v_fma_f32 v114, v118, v105, v62
	v_fma_f32 v115, v119, v105, v63
	global_store_dwordx4 v90, v[112:115], s[88:89]
	v_fma_f32 v116, v112, v106, v64
	v_fma_f32 v117, v113, v106, v65
	v_fma_f32 v118, v114, v106, v66
	v_fma_f32 v119, v115, v106, v67
	global_store_dwordx4 v91, v[116:119], s[88:89]
	v_fma_f32 v112, v116, v107, v68
	v_fma_f32 v113, v117, v107, v69
	v_fma_f32 v114, v118, v107, v70
	v_fma_f32 v115, v119, v107, v71
	global_store_dwordx4 v92, v[112:115], s[88:89]
	v_fma_f32 v116, v112, v108, v72
	v_fma_f32 v117, v113, v108, v73
	v_fma_f32 v118, v114, v108, v74
	v_fma_f32 v119, v115, v108, v75
	global_store_dwordx4 v93, v[116:119], s[88:89]
	v_fma_f32 v112, v116, v109, v76
	v_fma_f32 v113, v117, v109, v77
	v_fma_f32 v114, v118, v109, v78
	v_fma_f32 v115, v119, v109, v79
	global_store_dwordx4 v94, v[112:115], s[88:89]
	v_fma_f32 v116, v112, v110, v80
	v_fma_f32 v117, v113, v110, v81
	v_fma_f32 v118, v114, v110, v82
	v_fma_f32 v119, v115, v110, v83
	global_store_dwordx4 v95, v[116:119], s[88:89]
	v_fma_f32 v112, v116, v111, v84
	v_fma_f32 v113, v117, v111, v85
	v_fma_f32 v114, v118, v111, v86
	v_fma_f32 v115, v119, v111, v87
	v_add_u32_e32 v8, s36, v8
	s_mov_b32 s4, 0x1ffff
	v_cmp_lt_i32_e32 vcc, s4, v8
	s_or_b64 s[2:3], vcc, s[2:3]
	s_andn2_b64 exec, exec, s[2:3]
	s_cbranch_execnz .LBB0_332

.LBB0_636:
	v_cndmask_b32_e64 v0, 0, 1, s[0:1]
	v_cmp_ne_u32_e32 vcc, 1, v0
	v_or_b32_e32 v0, s3, v10
	v_lshlrev_b64 v[8:9], 2, v[0:1]
	v_lshl_add_u64 v[12:13], s[8:9], 0, v[8:9]
	v_lshl_add_u64 v[8:9], s[12:13], 0, v[8:9]
	s_mul_i32 s90, s3, 0x3830
	global_load_dword v3, v[12:13], off
	global_load_dword v11, v[8:9], off
	v_lshl_add_u64 v[8:9], s[90:91], 2, v[4:5]
	s_mov_b32 s14, 0xe0c0
	s_mov_b32 s15, 0
	global_load_dword v32, v[8:9], off
	v_lshl_add_u64 v[8:9], v[8:9], 0, s[14:15]
	global_load_dword v34, v[8:9], off
	v_lshl_add_u64 v[8:9], v[8:9], 0, s[14:15]
	global_load_dword v36, v[8:9], off
	v_lshl_add_u64 v[8:9], v[8:9], 0, s[14:15]
	global_load_dword v38, v[8:9], off
	v_lshl_add_u64 v[8:9], v[8:9], 0, s[14:15]
	global_load_dword v40, v[8:9], off
	v_lshl_add_u64 v[8:9], v[8:9], 0, s[14:15]
	global_load_dword v42, v[8:9], off
	v_lshl_add_u64 v[8:9], v[8:9], 0, s[14:15]
	global_load_dword v44, v[8:9], off
	v_lshl_add_u64 v[8:9], v[8:9], 0, s[14:15]
	global_load_dword v46, v[8:9], off
	v_lshl_add_u64 v[8:9], v[8:9], 0, s[14:15]
	global_load_dword v48, v[8:9], off
	v_lshl_add_u64 v[8:9], v[8:9], 0, s[14:15]
	global_load_dword v50, v[8:9], off
	v_lshl_add_u64 v[8:9], v[8:9], 0, s[14:15]
	global_load_dword v52, v[8:9], off
	v_lshl_add_u64 v[8:9], v[8:9], 0, s[14:15]
	global_load_dword v54, v[8:9], off
	v_lshl_add_u64 v[8:9], v[8:9], 0, s[14:15]
	global_load_dword v58, v[8:9], off
	v_lshl_add_u64 v[8:9], v[8:9], 0, s[14:15]
	global_load_dword v60, v[8:9], off
	v_lshl_add_u64 v[8:9], v[8:9], 0, s[14:15]
	global_load_dword v62, v[8:9], off
	v_lshl_add_u64 v[8:9], v[8:9], 0, s[14:15]
	global_load_dword v64, v[8:9], off
	v_lshl_add_u64 v[8:9], v[8:9], 0, s[14:15]
	global_load_dword v66, v[8:9], off
	v_lshl_add_u64 v[8:9], v[8:9], 0, s[14:15]
	global_load_dword v68, v[8:9], off
	v_lshl_add_u64 v[8:9], v[8:9], 0, s[14:15]
	global_load_dword v70, v[8:9], off
	v_lshl_add_u64 v[8:9], v[8:9], 0, s[14:15]
	global_load_dword v72, v[8:9], off
	v_lshl_add_u64 v[8:9], v[8:9], 0, s[14:15]
	global_load_dword v74, v[8:9], off
	v_lshl_add_u64 v[8:9], v[8:9], 0, s[14:15]
	global_load_dword v76, v[8:9], off
	v_lshl_add_u64 v[8:9], v[8:9], 0, s[14:15]
	global_load_dword v78, v[8:9], off
	v_lshl_add_u64 v[8:9], v[8:9], 0, s[14:15]
	global_load_dword v80, v[8:9], off
	v_lshl_add_u64 v[8:9], v[8:9], 0, s[14:15]
	global_load_dword v82, v[8:9], off
	v_lshl_add_u64 v[8:9], v[8:9], 0, s[14:15]
	global_load_dword v84, v[8:9], off
	v_lshl_add_u64 v[8:9], v[8:9], 0, s[14:15]
	global_load_dword v86, v[8:9], off
	v_lshl_add_u64 v[8:9], v[8:9], 0, s[14:15]
	global_load_dword v88, v[8:9], off
	v_lshl_add_u64 v[8:9], v[8:9], 0, s[14:15]
	global_load_dword v90, v[8:9], off
	v_lshl_add_u64 v[8:9], v[8:9], 0, s[14:15]
	global_load_dword v92, v[8:9], off
	v_lshl_add_u64 v[8:9], v[8:9], 0, s[14:15]
	global_load_dword v94, v[8:9], off
	v_lshl_add_u64 v[8:9], v[8:9], 0, s[14:15]
	global_load_dword v96, v[8:9], off
	v_lshl_add_u64 v[8:9], v[8:9], 0, s[14:15]
	global_load_dword v98, v[8:9], off
	v_lshl_add_u64 v[8:9], v[8:9], 0, s[14:15]
	global_load_dword v100, v[8:9], off
	v_lshl_add_u64 v[8:9], v[8:9], 0, s[14:15]
	global_load_dword v102, v[8:9], off
	v_lshl_add_u64 v[8:9], v[8:9], 0, s[14:15]
	global_load_dword v104, v[8:9], off
	v_lshl_add_u64 v[8:9], v[8:9], 0, s[14:15]
	global_load_dword v106, v[8:9], off
	v_lshl_add_u64 v[8:9], v[8:9], 0, s[14:15]
	global_load_dword v108, v[8:9], off
	v_lshl_add_u64 v[8:9], v[8:9], 0, s[14:15]
	global_load_dword v110, v[8:9], off
	v_lshl_add_u64 v[8:9], v[8:9], 0, s[14:15]
	global_load_dword v112, v[8:9], off
	v_lshl_add_u64 v[8:9], v[8:9], 0, s[14:15]
	global_load_dword v114, v[8:9], off
	v_lshl_add_u64 v[8:9], v[8:9], 0, s[14:15]
	global_load_dword v116, v[8:9], off
	v_lshl_add_u64 v[8:9], v[8:9], 0, s[14:15]
	global_load_dword v118, v[8:9], off
	v_lshl_add_u64 v[8:9], v[8:9], 0, s[14:15]
	global_load_dword v120, v[8:9], off
	v_lshl_add_u64 v[8:9], v[8:9], 0, s[14:15]
	global_load_dword v122, v[8:9], off
	v_lshl_add_u64 v[8:9], v[8:9], 0, s[14:15]
	global_load_dword v124, v[8:9], off
	v_lshl_add_u64 v[8:9], v[8:9], 0, s[14:15]
	global_load_dword v126, v[8:9], off
	v_lshl_add_u64 v[8:9], v[8:9], 0, s[14:15]
	global_load_dword v128, v[8:9], off
	v_lshl_add_u64 v[8:9], v[8:9], 0, s[14:15]
	global_load_dword v130, v[8:9], off
	v_lshl_add_u64 v[8:9], v[8:9], 0, s[14:15]
	global_load_dword v132, v[8:9], off
	v_lshl_add_u64 v[8:9], v[8:9], 0, s[14:15]
	global_load_dword v134, v[8:9], off
	v_lshl_add_u64 v[8:9], v[8:9], 0, s[14:15]
	global_load_dword v136, v[8:9], off
	v_lshl_add_u64 v[8:9], v[8:9], 0, s[14:15]
	global_load_dword v138, v[8:9], off
	v_lshl_add_u64 v[8:9], v[8:9], 0, s[14:15]
	global_load_dword v140, v[8:9], off
	v_lshl_add_u64 v[8:9], v[8:9], 0, s[14:15]
	global_load_dword v142, v[8:9], off
	v_lshl_add_u64 v[8:9], v[8:9], 0, s[14:15]
	global_load_dword v144, v[8:9], off
	v_lshl_add_u64 v[8:9], v[8:9], 0, s[14:15]
	global_load_dword v146, v[8:9], off
	v_lshl_add_u64 v[8:9], v[8:9], 0, s[14:15]
	global_load_dword v148, v[8:9], off
	v_lshl_add_u64 v[8:9], v[8:9], 0, s[14:15]
	global_load_dword v150, v[8:9], off
	v_lshl_add_u64 v[8:9], v[8:9], 0, s[14:15]
	global_load_dword v152, v[8:9], off
	v_lshl_add_u64 v[8:9], v[8:9], 0, s[14:15]
	global_load_dword v154, v[8:9], off
	v_lshl_add_u64 v[8:9], v[8:9], 0, s[14:15]
	global_load_dword v156, v[8:9], off
	v_lshl_add_u64 v[8:9], v[8:9], 0, s[14:15]
	global_load_dword v158, v[8:9], off
	v_lshl_add_u64 v[8:9], v[8:9], 0, s[14:15]
	global_load_dword v164, v[8:9], off
	s_mov_b32 s3, 64
	s_and_b64 vcc, exec, vcc
	s_waitcnt vmcnt(63)
	v_readlane_b32 s16, v3, 0
	v_readlane_b32 s17, v11, 0
	v_readlane_b32 s18, v3, 1
	v_readlane_b32 s19, v11, 1
	v_readlane_b32 s20, v3, 2
	v_readlane_b32 s21, v11, 2
	v_pk_fma_f32 v[6:7], v[32:33], s[16:17], v[6:7] op_sel_hi:[0,1,1]
	v_readlane_b32 s22, v3, 3
	v_readlane_b32 s23, v11, 3
	s_waitcnt vmcnt(62)
	v_pk_fma_f32 v[6:7], v[34:35], s[18:19], v[6:7] op_sel_hi:[0,1,1]
	v_readlane_b32 s16, v3, 4
	v_readlane_b32 s17, v11, 4
	s_waitcnt vmcnt(61)
	v_pk_fma_f32 v[6:7], v[36:37], s[20:21], v[6:7] op_sel_hi:[0,1,1]
	v_readlane_b32 s18, v3, 5
	v_readlane_b32 s19, v11, 5
	s_waitcnt vmcnt(60)
	v_pk_fma_f32 v[6:7], v[38:39], s[22:23], v[6:7] op_sel_hi:[0,1,1]
	v_readlane_b32 s20, v3, 6
	v_readlane_b32 s21, v11, 6
	s_waitcnt vmcnt(59)
	v_pk_fma_f32 v[6:7], v[40:41], s[16:17], v[6:7] op_sel_hi:[0,1,1]
	v_readlane_b32 s22, v3, 7
	v_readlane_b32 s23, v11, 7
	s_waitcnt vmcnt(58)
	v_pk_fma_f32 v[6:7], v[42:43], s[18:19], v[6:7] op_sel_hi:[0,1,1]
	v_readlane_b32 s16, v3, 8
	v_readlane_b32 s17, v11, 8
	s_waitcnt vmcnt(57)
	v_pk_fma_f32 v[6:7], v[44:45], s[20:21], v[6:7] op_sel_hi:[0,1,1]
	v_readlane_b32 s18, v3, 9
	v_readlane_b32 s19, v11, 9
	s_waitcnt vmcnt(56)
	v_pk_fma_f32 v[6:7], v[46:47], s[22:23], v[6:7] op_sel_hi:[0,1,1]
	v_readlane_b32 s20, v3, 10
	v_readlane_b32 s21, v11, 10
	s_waitcnt vmcnt(55)
	v_pk_fma_f32 v[6:7], v[48:49], s[16:17], v[6:7] op_sel_hi:[0,1,1]
	v_readlane_b32 s22, v3, 11
	v_readlane_b32 s23, v11, 11
	s_waitcnt vmcnt(54)
	v_pk_fma_f32 v[6:7], v[50:51], s[18:19], v[6:7] op_sel_hi:[0,1,1]
	v_readlane_b32 s16, v3, 12
	v_readlane_b32 s17, v11, 12
	s_waitcnt vmcnt(53)
	v_pk_fma_f32 v[6:7], v[52:53], s[20:21], v[6:7] op_sel_hi:[0,1,1]
	v_readlane_b32 s18, v3, 13
	v_readlane_b32 s19, v11, 13
	s_waitcnt vmcnt(52)
	v_pk_fma_f32 v[6:7], v[54:55], s[22:23], v[6:7] op_sel_hi:[0,1,1]
	v_readlane_b32 s20, v3, 14
	v_readlane_b32 s21, v11, 14
	s_waitcnt vmcnt(51)
	v_pk_fma_f32 v[6:7], v[58:59], s[16:17], v[6:7] op_sel_hi:[0,1,1]
	v_readlane_b32 s22, v3, 15
	v_readlane_b32 s23, v11, 15
	s_waitcnt vmcnt(50)
	v_pk_fma_f32 v[6:7], v[60:61], s[18:19], v[6:7] op_sel_hi:[0,1,1]
	v_readlane_b32 s16, v3, 16
	v_readlane_b32 s17, v11, 16
	s_waitcnt vmcnt(49)
	v_pk_fma_f32 v[6:7], v[62:63], s[20:21], v[6:7] op_sel_hi:[0,1,1]
	v_readlane_b32 s18, v3, 17
	v_readlane_b32 s19, v11, 17
	s_waitcnt vmcnt(48)
	v_pk_fma_f32 v[6:7], v[64:65], s[22:23], v[6:7] op_sel_hi:[0,1,1]
	v_readlane_b32 s20, v3, 18
	v_readlane_b32 s21, v11, 18
	s_waitcnt vmcnt(47)
	v_pk_fma_f32 v[6:7], v[66:67], s[16:17], v[6:7] op_sel_hi:[0,1,1]
	v_readlane_b32 s22, v3, 19
	v_readlane_b32 s23, v11, 19
	s_waitcnt vmcnt(46)
	v_pk_fma_f32 v[6:7], v[68:69], s[18:19], v[6:7] op_sel_hi:[0,1,1]
	v_readlane_b32 s16, v3, 20
	v_readlane_b32 s17, v11, 20
	s_waitcnt vmcnt(45)
	v_pk_fma_f32 v[6:7], v[70:71], s[20:21], v[6:7] op_sel_hi:[0,1,1]
	v_readlane_b32 s18, v3, 21
	v_readlane_b32 s19, v11, 21
	s_waitcnt vmcnt(44)
	v_pk_fma_f32 v[6:7], v[72:73], s[22:23], v[6:7] op_sel_hi:[0,1,1]
	v_readlane_b32 s20, v3, 22
	v_readlane_b32 s21, v11, 22
	s_waitcnt vmcnt(43)
	v_pk_fma_f32 v[6:7], v[74:75], s[16:17], v[6:7] op_sel_hi:[0,1,1]
	v_readlane_b32 s22, v3, 23
	v_readlane_b32 s23, v11, 23
	s_waitcnt vmcnt(42)
	v_pk_fma_f32 v[6:7], v[76:77], s[18:19], v[6:7] op_sel_hi:[0,1,1]
	v_readlane_b32 s16, v3, 24
	v_readlane_b32 s17, v11, 24
	s_waitcnt vmcnt(41)
	v_pk_fma_f32 v[6:7], v[78:79], s[20:21], v[6:7] op_sel_hi:[0,1,1]
	v_readlane_b32 s18, v3, 25
	v_readlane_b32 s19, v11, 25
	s_waitcnt vmcnt(40)
	v_pk_fma_f32 v[6:7], v[80:81], s[22:23], v[6:7] op_sel_hi:[0,1,1]
	v_readlane_b32 s20, v3, 26
	v_readlane_b32 s21, v11, 26
	s_waitcnt vmcnt(39)
	v_pk_fma_f32 v[6:7], v[82:83], s[16:17], v[6:7] op_sel_hi:[0,1,1]
	v_readlane_b32 s22, v3, 27
	v_readlane_b32 s23, v11, 27
	s_waitcnt vmcnt(38)
	v_pk_fma_f32 v[6:7], v[84:85], s[18:19], v[6:7] op_sel_hi:[0,1,1]
	v_readlane_b32 s16, v3, 28
	v_readlane_b32 s17, v11, 28
	s_waitcnt vmcnt(37)
	v_pk_fma_f32 v[6:7], v[86:87], s[20:21], v[6:7] op_sel_hi:[0,1,1]
	v_readlane_b32 s18, v3, 29
	v_readlane_b32 s19, v11, 29
	s_waitcnt vmcnt(36)
	v_pk_fma_f32 v[6:7], v[88:89], s[22:23], v[6:7] op_sel_hi:[0,1,1]
	v_readlane_b32 s20, v3, 30
	v_readlane_b32 s21, v11, 30
	s_waitcnt vmcnt(35)
	v_pk_fma_f32 v[6:7], v[90:91], s[16:17], v[6:7] op_sel_hi:[0,1,1]
	v_readlane_b32 s22, v3, 31
	v_readlane_b32 s23, v11, 31
	s_waitcnt vmcnt(34)
	v_pk_fma_f32 v[6:7], v[92:93], s[18:19], v[6:7] op_sel_hi:[0,1,1]
	v_readlane_b32 s16, v3, 32
	v_readlane_b32 s17, v11, 32
	s_waitcnt vmcnt(33)
	v_pk_fma_f32 v[6:7], v[94:95], s[20:21], v[6:7] op_sel_hi:[0,1,1]
	v_readlane_b32 s18, v3, 33
	v_readlane_b32 s19, v11, 33
	s_waitcnt vmcnt(32)
	v_pk_fma_f32 v[6:7], v[96:97], s[22:23], v[6:7] op_sel_hi:[0,1,1]
	v_readlane_b32 s20, v3, 34
	v_readlane_b32 s21, v11, 34
	s_waitcnt vmcnt(31)
	v_pk_fma_f32 v[6:7], v[98:99], s[16:17], v[6:7] op_sel_hi:[0,1,1]
	v_readlane_b32 s22, v3, 35
	v_readlane_b32 s23, v11, 35
	s_waitcnt vmcnt(30)
	v_pk_fma_f32 v[6:7], v[100:101], s[18:19], v[6:7] op_sel_hi:[0,1,1]
	v_readlane_b32 s16, v3, 36
	v_readlane_b32 s17, v11, 36
	s_waitcnt vmcnt(29)
	v_pk_fma_f32 v[6:7], v[102:103], s[20:21], v[6:7] op_sel_hi:[0,1,1]
	v_readlane_b32 s18, v3, 37
	v_readlane_b32 s19, v11, 37
	s_waitcnt vmcnt(28)
	v_pk_fma_f32 v[6:7], v[104:105], s[22:23], v[6:7] op_sel_hi:[0,1,1]
	v_readlane_b32 s20, v3, 38
	v_readlane_b32 s21, v11, 38
	s_waitcnt vmcnt(27)
	v_pk_fma_f32 v[6:7], v[106:107], s[16:17], v[6:7] op_sel_hi:[0,1,1]
	v_readlane_b32 s22, v3, 39
	v_readlane_b32 s23, v11, 39
	s_waitcnt vmcnt(26)
	v_pk_fma_f32 v[6:7], v[108:109], s[18:19], v[6:7] op_sel_hi:[0,1,1]
	v_readlane_b32 s16, v3, 40
	v_readlane_b32 s17, v11, 40
	s_waitcnt vmcnt(25)
	v_pk_fma_f32 v[6:7], v[110:111], s[20:21], v[6:7] op_sel_hi:[0,1,1]
	v_readlane_b32 s18, v3, 41
	v_readlane_b32 s19, v11, 41
	s_waitcnt vmcnt(24)
	v_pk_fma_f32 v[6:7], v[112:113], s[22:23], v[6:7] op_sel_hi:[0,1,1]
	v_readlane_b32 s20, v3, 42
	v_readlane_b32 s21, v11, 42
	s_waitcnt vmcnt(23)
	v_pk_fma_f32 v[6:7], v[114:115], s[16:17], v[6:7] op_sel_hi:[0,1,1]
	v_readlane_b32 s22, v3, 43
	v_readlane_b32 s23, v11, 43
	s_waitcnt vmcnt(22)
	v_pk_fma_f32 v[6:7], v[116:117], s[18:19], v[6:7] op_sel_hi:[0,1,1]
	v_readlane_b32 s16, v3, 44
	v_readlane_b32 s17, v11, 44
	s_waitcnt vmcnt(21)
	v_pk_fma_f32 v[6:7], v[118:119], s[20:21], v[6:7] op_sel_hi:[0,1,1]
	v_readlane_b32 s18, v3, 45
	v_readlane_b32 s19, v11, 45
	s_waitcnt vmcnt(20)
	v_pk_fma_f32 v[6:7], v[120:121], s[22:23], v[6:7] op_sel_hi:[0,1,1]
	v_readlane_b32 s20, v3, 46
	v_readlane_b32 s21, v11, 46
	s_waitcnt vmcnt(19)
	v_pk_fma_f32 v[6:7], v[122:123], s[16:17], v[6:7] op_sel_hi:[0,1,1]
	v_readlane_b32 s22, v3, 47
	v_readlane_b32 s23, v11, 47
	s_waitcnt vmcnt(18)
	v_pk_fma_f32 v[6:7], v[124:125], s[18:19], v[6:7] op_sel_hi:[0,1,1]
	v_readlane_b32 s16, v3, 48
	v_readlane_b32 s17, v11, 48
	s_waitcnt vmcnt(17)
	v_pk_fma_f32 v[6:7], v[126:127], s[20:21], v[6:7] op_sel_hi:[0,1,1]
	v_readlane_b32 s18, v3, 49
	v_readlane_b32 s19, v11, 49
	s_waitcnt vmcnt(16)
	v_pk_fma_f32 v[6:7], v[128:129], s[22:23], v[6:7] op_sel_hi:[0,1,1]
	v_readlane_b32 s20, v3, 50
	v_readlane_b32 s21, v11, 50
	s_waitcnt vmcnt(15)
	v_pk_fma_f32 v[6:7], v[130:131], s[16:17], v[6:7] op_sel_hi:[0,1,1]
	v_readlane_b32 s22, v3, 51
	v_readlane_b32 s23, v11, 51
	s_waitcnt vmcnt(14)
	v_pk_fma_f32 v[6:7], v[132:133], s[18:19], v[6:7] op_sel_hi:[0,1,1]
	v_readlane_b32 s16, v3, 52
	v_readlane_b32 s17, v11, 52
	s_waitcnt vmcnt(13)
	v_pk_fma_f32 v[6:7], v[134:135], s[20:21], v[6:7] op_sel_hi:[0,1,1]
	v_readlane_b32 s18, v3, 53
	v_readlane_b32 s19, v11, 53
	s_waitcnt vmcnt(12)
	v_pk_fma_f32 v[6:7], v[136:137], s[22:23], v[6:7] op_sel_hi:[0,1,1]
	v_readlane_b32 s20, v3, 54
	v_readlane_b32 s21, v11, 54
	s_waitcnt vmcnt(11)
	v_pk_fma_f32 v[6:7], v[138:139], s[16:17], v[6:7] op_sel_hi:[0,1,1]
	v_readlane_b32 s22, v3, 55
	v_readlane_b32 s23, v11, 55
	s_waitcnt vmcnt(10)
	v_pk_fma_f32 v[6:7], v[140:141], s[18:19], v[6:7] op_sel_hi:[0,1,1]
	v_readlane_b32 s16, v3, 56
	v_readlane_b32 s17, v11, 56
	s_waitcnt vmcnt(9)
	v_pk_fma_f32 v[6:7], v[142:143], s[20:21], v[6:7] op_sel_hi:[0,1,1]
	v_readlane_b32 s18, v3, 57
	v_readlane_b32 s19, v11, 57
	s_waitcnt vmcnt(8)
	v_pk_fma_f32 v[6:7], v[144:145], s[22:23], v[6:7] op_sel_hi:[0,1,1]
	v_readlane_b32 s20, v3, 58
	v_readlane_b32 s21, v11, 58
	s_waitcnt vmcnt(7)
	v_pk_fma_f32 v[6:7], v[146:147], s[16:17], v[6:7] op_sel_hi:[0,1,1]
	v_readlane_b32 s22, v3, 59
	v_readlane_b32 s23, v11, 59
	s_waitcnt vmcnt(6)
	v_pk_fma_f32 v[6:7], v[148:149], s[18:19], v[6:7] op_sel_hi:[0,1,1]
	v_readlane_b32 s16, v3, 60
	v_readlane_b32 s17, v11, 60
	s_waitcnt vmcnt(5)
	v_pk_fma_f32 v[6:7], v[150:151], s[20:21], v[6:7] op_sel_hi:[0,1,1]
	v_readlane_b32 s18, v3, 61
	v_readlane_b32 s19, v11, 61
	s_waitcnt vmcnt(4)
	v_pk_fma_f32 v[6:7], v[152:153], s[22:23], v[6:7] op_sel_hi:[0,1,1]
	v_readlane_b32 s20, v3, 62
	v_readlane_b32 s21, v11, 62
	s_waitcnt vmcnt(3)
	v_pk_fma_f32 v[6:7], v[154:155], s[16:17], v[6:7] op_sel_hi:[0,1,1]
	v_readlane_b32 s22, v3, 63
	v_readlane_b32 s23, v11, 63
	s_waitcnt vmcnt(2)
	v_pk_fma_f32 v[6:7], v[156:157], s[18:19], v[6:7] op_sel_hi:[0,1,1]
	s_waitcnt vmcnt(1)
	v_pk_fma_f32 v[6:7], v[158:159], s[20:21], v[6:7] op_sel_hi:[0,1,1]
	s_waitcnt vmcnt(0)
	v_pk_fma_f32 v[6:7], v[164:165], s[22:23], v[6:7] op_sel_hi:[0,1,1]
	s_mov_b64 s[0:1], 0
	s_cbranch_vccz .LBB0_636
	v_readlane_b32 s2, v254, 51
	v_readlane_b32 s3, v254, 52
	s_and_saveexec_b64 s[0:1], s[2:3]
	s_cbranch_execz .LBB0_634
	v_ashrrev_i32_e32 v3, 31, v2
	v_readlane_b32 s4, v250, 30
	v_lshlrev_b64 v[2:3], 2, v[2:3]
	v_readlane_b32 s5, v250, 31
	s_nop 1
	v_lshl_add_u64 v[4:5], s[4:5], 0, v[2:3]
	v_readlane_b32 s4, v249, 18
	v_readlane_b32 s5, v249, 19
	s_nop 1
	v_lshl_add_u64 v[2:3], s[4:5], 0, v[2:3]
	global_atomic_add_f32 v[2:3], v6, off
	global_atomic_add_f32 v[4:5], v7, off
	s_branch .LBB0_634

.LBB0_668:
	v_cndmask_b32_e64 v0, 0, 1, s[0:1]
	v_cmp_ne_u32_e32 vcc, 1, v0
	v_or_b32_e32 v0, s11, v10
	v_lshlrev_b64 v[8:9], 2, v[0:1]
	s_lshl_b32 s90, s11, 10
	v_lshl_add_u64 v[12:13], s[2:3], 0, v[8:9]
	v_lshl_add_u64 v[8:9], s[4:5], 0, v[8:9]
	global_load_dword v3, v[12:13], off
	global_load_dword v11, v[8:9], off
	v_lshl_add_u64 v[8:9], s[90:91], 2, v[4:5]
	s_mov_b32 s14, 0x1000
	s_mov_b32 s15, 0
	global_load_dword v32, v[8:9], off
	v_lshl_add_u64 v[8:9], v[8:9], 0, s[14:15]
	global_load_dword v34, v[8:9], off
	v_lshl_add_u64 v[8:9], v[8:9], 0, s[14:15]
	global_load_dword v36, v[8:9], off
	v_lshl_add_u64 v[8:9], v[8:9], 0, s[14:15]
	global_load_dword v38, v[8:9], off
	v_lshl_add_u64 v[8:9], v[8:9], 0, s[14:15]
	global_load_dword v40, v[8:9], off
	v_lshl_add_u64 v[8:9], v[8:9], 0, s[14:15]
	global_load_dword v42, v[8:9], off
	v_lshl_add_u64 v[8:9], v[8:9], 0, s[14:15]
	global_load_dword v44, v[8:9], off
	v_lshl_add_u64 v[8:9], v[8:9], 0, s[14:15]
	global_load_dword v46, v[8:9], off
	v_lshl_add_u64 v[8:9], v[8:9], 0, s[14:15]
	global_load_dword v48, v[8:9], off
	v_lshl_add_u64 v[8:9], v[8:9], 0, s[14:15]
	global_load_dword v50, v[8:9], off
	v_lshl_add_u64 v[8:9], v[8:9], 0, s[14:15]
	global_load_dword v52, v[8:9], off
	v_lshl_add_u64 v[8:9], v[8:9], 0, s[14:15]
	global_load_dword v54, v[8:9], off
	v_lshl_add_u64 v[8:9], v[8:9], 0, s[14:15]
	global_load_dword v58, v[8:9], off
	v_lshl_add_u64 v[8:9], v[8:9], 0, s[14:15]
	global_load_dword v60, v[8:9], off
	v_lshl_add_u64 v[8:9], v[8:9], 0, s[14:15]
	global_load_dword v62, v[8:9], off
	v_lshl_add_u64 v[8:9], v[8:9], 0, s[14:15]
	global_load_dword v64, v[8:9], off
	v_lshl_add_u64 v[8:9], v[8:9], 0, s[14:15]
	global_load_dword v66, v[8:9], off
	v_lshl_add_u64 v[8:9], v[8:9], 0, s[14:15]
	global_load_dword v68, v[8:9], off
	v_lshl_add_u64 v[8:9], v[8:9], 0, s[14:15]
	global_load_dword v70, v[8:9], off
	v_lshl_add_u64 v[8:9], v[8:9], 0, s[14:15]
	global_load_dword v72, v[8:9], off
	v_lshl_add_u64 v[8:9], v[8:9], 0, s[14:15]
	global_load_dword v74, v[8:9], off
	v_lshl_add_u64 v[8:9], v[8:9], 0, s[14:15]
	global_load_dword v76, v[8:9], off
	v_lshl_add_u64 v[8:9], v[8:9], 0, s[14:15]
	global_load_dword v78, v[8:9], off
	v_lshl_add_u64 v[8:9], v[8:9], 0, s[14:15]
	global_load_dword v80, v[8:9], off
	v_lshl_add_u64 v[8:9], v[8:9], 0, s[14:15]
	global_load_dword v82, v[8:9], off
	v_lshl_add_u64 v[8:9], v[8:9], 0, s[14:15]
	global_load_dword v84, v[8:9], off
	v_lshl_add_u64 v[8:9], v[8:9], 0, s[14:15]
	global_load_dword v86, v[8:9], off
	v_lshl_add_u64 v[8:9], v[8:9], 0, s[14:15]
	global_load_dword v88, v[8:9], off
	v_lshl_add_u64 v[8:9], v[8:9], 0, s[14:15]
	global_load_dword v90, v[8:9], off
	v_lshl_add_u64 v[8:9], v[8:9], 0, s[14:15]
	global_load_dword v92, v[8:9], off
	v_lshl_add_u64 v[8:9], v[8:9], 0, s[14:15]
	global_load_dword v94, v[8:9], off
	v_lshl_add_u64 v[8:9], v[8:9], 0, s[14:15]
	global_load_dword v96, v[8:9], off
	v_lshl_add_u64 v[8:9], v[8:9], 0, s[14:15]
	global_load_dword v98, v[8:9], off
	v_lshl_add_u64 v[8:9], v[8:9], 0, s[14:15]
	global_load_dword v100, v[8:9], off
	v_lshl_add_u64 v[8:9], v[8:9], 0, s[14:15]
	global_load_dword v102, v[8:9], off
	v_lshl_add_u64 v[8:9], v[8:9], 0, s[14:15]
	global_load_dword v104, v[8:9], off
	v_lshl_add_u64 v[8:9], v[8:9], 0, s[14:15]
	global_load_dword v106, v[8:9], off
	v_lshl_add_u64 v[8:9], v[8:9], 0, s[14:15]
	global_load_dword v108, v[8:9], off
	v_lshl_add_u64 v[8:9], v[8:9], 0, s[14:15]
	global_load_dword v110, v[8:9], off
	v_lshl_add_u64 v[8:9], v[8:9], 0, s[14:15]
	global_load_dword v112, v[8:9], off
	v_lshl_add_u64 v[8:9], v[8:9], 0, s[14:15]
	global_load_dword v114, v[8:9], off
	v_lshl_add_u64 v[8:9], v[8:9], 0, s[14:15]
	global_load_dword v116, v[8:9], off
	v_lshl_add_u64 v[8:9], v[8:9], 0, s[14:15]
	global_load_dword v118, v[8:9], off
	v_lshl_add_u64 v[8:9], v[8:9], 0, s[14:15]
	global_load_dword v120, v[8:9], off
	v_lshl_add_u64 v[8:9], v[8:9], 0, s[14:15]
	global_load_dword v122, v[8:9], off
	v_lshl_add_u64 v[8:9], v[8:9], 0, s[14:15]
	global_load_dword v124, v[8:9], off
	v_lshl_add_u64 v[8:9], v[8:9], 0, s[14:15]
	global_load_dword v126, v[8:9], off
	v_lshl_add_u64 v[8:9], v[8:9], 0, s[14:15]
	global_load_dword v128, v[8:9], off
	v_lshl_add_u64 v[8:9], v[8:9], 0, s[14:15]
	global_load_dword v130, v[8:9], off
	v_lshl_add_u64 v[8:9], v[8:9], 0, s[14:15]
	global_load_dword v132, v[8:9], off
	v_lshl_add_u64 v[8:9], v[8:9], 0, s[14:15]
	global_load_dword v134, v[8:9], off
	v_lshl_add_u64 v[8:9], v[8:9], 0, s[14:15]
	global_load_dword v136, v[8:9], off
	v_lshl_add_u64 v[8:9], v[8:9], 0, s[14:15]
	global_load_dword v138, v[8:9], off
	v_lshl_add_u64 v[8:9], v[8:9], 0, s[14:15]
	global_load_dword v140, v[8:9], off
	v_lshl_add_u64 v[8:9], v[8:9], 0, s[14:15]
	global_load_dword v142, v[8:9], off
	v_lshl_add_u64 v[8:9], v[8:9], 0, s[14:15]
	global_load_dword v144, v[8:9], off
	v_lshl_add_u64 v[8:9], v[8:9], 0, s[14:15]
	global_load_dword v146, v[8:9], off
	v_lshl_add_u64 v[8:9], v[8:9], 0, s[14:15]
	global_load_dword v148, v[8:9], off
	v_lshl_add_u64 v[8:9], v[8:9], 0, s[14:15]
	global_load_dword v150, v[8:9], off
	v_lshl_add_u64 v[8:9], v[8:9], 0, s[14:15]
	global_load_dword v152, v[8:9], off
	v_lshl_add_u64 v[8:9], v[8:9], 0, s[14:15]
	global_load_dword v154, v[8:9], off
	v_lshl_add_u64 v[8:9], v[8:9], 0, s[14:15]
	global_load_dword v156, v[8:9], off
	v_lshl_add_u64 v[8:9], v[8:9], 0, s[14:15]
	global_load_dword v158, v[8:9], off
	v_lshl_add_u64 v[8:9], v[8:9], 0, s[14:15]
	global_load_dword v164, v[8:9], off
	s_mov_b32 s11, 64
	s_and_b64 vcc, exec, vcc
	s_waitcnt vmcnt(63)
	v_readlane_b32 s16, v3, 0
	v_readlane_b32 s17, v11, 0
	v_readlane_b32 s18, v3, 1
	v_readlane_b32 s19, v11, 1
	v_readlane_b32 s20, v3, 2
	v_readlane_b32 s21, v11, 2
	v_pk_fma_f32 v[6:7], v[32:33], s[16:17], v[6:7] op_sel_hi:[0,1,1]
	v_readlane_b32 s22, v3, 3
	v_readlane_b32 s23, v11, 3
	s_waitcnt vmcnt(62)
	v_pk_fma_f32 v[6:7], v[34:35], s[18:19], v[6:7] op_sel_hi:[0,1,1]
	v_readlane_b32 s16, v3, 4
	v_readlane_b32 s17, v11, 4
	s_waitcnt vmcnt(61)
	v_pk_fma_f32 v[6:7], v[36:37], s[20:21], v[6:7] op_sel_hi:[0,1,1]
	v_readlane_b32 s18, v3, 5
	v_readlane_b32 s19, v11, 5
	s_waitcnt vmcnt(60)
	v_pk_fma_f32 v[6:7], v[38:39], s[22:23], v[6:7] op_sel_hi:[0,1,1]
	v_readlane_b32 s20, v3, 6
	v_readlane_b32 s21, v11, 6
	s_waitcnt vmcnt(59)
	v_pk_fma_f32 v[6:7], v[40:41], s[16:17], v[6:7] op_sel_hi:[0,1,1]
	v_readlane_b32 s22, v3, 7
	v_readlane_b32 s23, v11, 7
	s_waitcnt vmcnt(58)
	v_pk_fma_f32 v[6:7], v[42:43], s[18:19], v[6:7] op_sel_hi:[0,1,1]
	v_readlane_b32 s16, v3, 8
	v_readlane_b32 s17, v11, 8
	s_waitcnt vmcnt(57)
	v_pk_fma_f32 v[6:7], v[44:45], s[20:21], v[6:7] op_sel_hi:[0,1,1]
	v_readlane_b32 s18, v3, 9
	v_readlane_b32 s19, v11, 9
	s_waitcnt vmcnt(56)
	v_pk_fma_f32 v[6:7], v[46:47], s[22:23], v[6:7] op_sel_hi:[0,1,1]
	v_readlane_b32 s20, v3, 10
	v_readlane_b32 s21, v11, 10
	s_waitcnt vmcnt(55)
	v_pk_fma_f32 v[6:7], v[48:49], s[16:17], v[6:7] op_sel_hi:[0,1,1]
	v_readlane_b32 s22, v3, 11
	v_readlane_b32 s23, v11, 11
	s_waitcnt vmcnt(54)
	v_pk_fma_f32 v[6:7], v[50:51], s[18:19], v[6:7] op_sel_hi:[0,1,1]
	v_readlane_b32 s16, v3, 12
	v_readlane_b32 s17, v11, 12
	s_waitcnt vmcnt(53)
	v_pk_fma_f32 v[6:7], v[52:53], s[20:21], v[6:7] op_sel_hi:[0,1,1]
	v_readlane_b32 s18, v3, 13
	v_readlane_b32 s19, v11, 13
	s_waitcnt vmcnt(52)
	v_pk_fma_f32 v[6:7], v[54:55], s[22:23], v[6:7] op_sel_hi:[0,1,1]
	v_readlane_b32 s20, v3, 14
	v_readlane_b32 s21, v11, 14
	s_waitcnt vmcnt(51)
	v_pk_fma_f32 v[6:7], v[58:59], s[16:17], v[6:7] op_sel_hi:[0,1,1]
	v_readlane_b32 s22, v3, 15
	v_readlane_b32 s23, v11, 15
	s_waitcnt vmcnt(50)
	v_pk_fma_f32 v[6:7], v[60:61], s[18:19], v[6:7] op_sel_hi:[0,1,1]
	v_readlane_b32 s16, v3, 16
	v_readlane_b32 s17, v11, 16
	s_waitcnt vmcnt(49)
	v_pk_fma_f32 v[6:7], v[62:63], s[20:21], v[6:7] op_sel_hi:[0,1,1]
	v_readlane_b32 s18, v3, 17
	v_readlane_b32 s19, v11, 17
	s_waitcnt vmcnt(48)
	v_pk_fma_f32 v[6:7], v[64:65], s[22:23], v[6:7] op_sel_hi:[0,1,1]
	v_readlane_b32 s20, v3, 18
	v_readlane_b32 s21, v11, 18
	s_waitcnt vmcnt(47)
	v_pk_fma_f32 v[6:7], v[66:67], s[16:17], v[6:7] op_sel_hi:[0,1,1]
	v_readlane_b32 s22, v3, 19
	v_readlane_b32 s23, v11, 19
	s_waitcnt vmcnt(46)
	v_pk_fma_f32 v[6:7], v[68:69], s[18:19], v[6:7] op_sel_hi:[0,1,1]
	v_readlane_b32 s16, v3, 20
	v_readlane_b32 s17, v11, 20
	s_waitcnt vmcnt(45)
	v_pk_fma_f32 v[6:7], v[70:71], s[20:21], v[6:7] op_sel_hi:[0,1,1]
	v_readlane_b32 s18, v3, 21
	v_readlane_b32 s19, v11, 21
	s_waitcnt vmcnt(44)
	v_pk_fma_f32 v[6:7], v[72:73], s[22:23], v[6:7] op_sel_hi:[0,1,1]
	v_readlane_b32 s20, v3, 22
	v_readlane_b32 s21, v11, 22
	s_waitcnt vmcnt(43)
	v_pk_fma_f32 v[6:7], v[74:75], s[16:17], v[6:7] op_sel_hi:[0,1,1]
	v_readlane_b32 s22, v3, 23
	v_readlane_b32 s23, v11, 23
	s_waitcnt vmcnt(42)
	v_pk_fma_f32 v[6:7], v[76:77], s[18:19], v[6:7] op_sel_hi:[0,1,1]
	v_readlane_b32 s16, v3, 24
	v_readlane_b32 s17, v11, 24
	s_waitcnt vmcnt(41)
	v_pk_fma_f32 v[6:7], v[78:79], s[20:21], v[6:7] op_sel_hi:[0,1,1]
	v_readlane_b32 s18, v3, 25
	v_readlane_b32 s19, v11, 25
	s_waitcnt vmcnt(40)
	v_pk_fma_f32 v[6:7], v[80:81], s[22:23], v[6:7] op_sel_hi:[0,1,1]
	v_readlane_b32 s20, v3, 26
	v_readlane_b32 s21, v11, 26
	s_waitcnt vmcnt(39)
	v_pk_fma_f32 v[6:7], v[82:83], s[16:17], v[6:7] op_sel_hi:[0,1,1]
	v_readlane_b32 s22, v3, 27
	v_readlane_b32 s23, v11, 27
	s_waitcnt vmcnt(38)
	v_pk_fma_f32 v[6:7], v[84:85], s[18:19], v[6:7] op_sel_hi:[0,1,1]
	v_readlane_b32 s16, v3, 28
	v_readlane_b32 s17, v11, 28
	s_waitcnt vmcnt(37)
	v_pk_fma_f32 v[6:7], v[86:87], s[20:21], v[6:7] op_sel_hi:[0,1,1]
	v_readlane_b32 s18, v3, 29
	v_readlane_b32 s19, v11, 29
	s_waitcnt vmcnt(36)
	v_pk_fma_f32 v[6:7], v[88:89], s[22:23], v[6:7] op_sel_hi:[0,1,1]
	v_readlane_b32 s20, v3, 30
	v_readlane_b32 s21, v11, 30
	s_waitcnt vmcnt(35)
	v_pk_fma_f32 v[6:7], v[90:91], s[16:17], v[6:7] op_sel_hi:[0,1,1]
	v_readlane_b32 s22, v3, 31
	v_readlane_b32 s23, v11, 31
	s_waitcnt vmcnt(34)
	v_pk_fma_f32 v[6:7], v[92:93], s[18:19], v[6:7] op_sel_hi:[0,1,1]
	v_readlane_b32 s16, v3, 32
	v_readlane_b32 s17, v11, 32
	s_waitcnt vmcnt(33)
	v_pk_fma_f32 v[6:7], v[94:95], s[20:21], v[6:7] op_sel_hi:[0,1,1]
	v_readlane_b32 s18, v3, 33
	v_readlane_b32 s19, v11, 33
	s_waitcnt vmcnt(32)
	v_pk_fma_f32 v[6:7], v[96:97], s[22:23], v[6:7] op_sel_hi:[0,1,1]
	v_readlane_b32 s20, v3, 34
	v_readlane_b32 s21, v11, 34
	s_waitcnt vmcnt(31)
	v_pk_fma_f32 v[6:7], v[98:99], s[16:17], v[6:7] op_sel_hi:[0,1,1]
	v_readlane_b32 s22, v3, 35
	v_readlane_b32 s23, v11, 35
	s_waitcnt vmcnt(30)
	v_pk_fma_f32 v[6:7], v[100:101], s[18:19], v[6:7] op_sel_hi:[0,1,1]
	v_readlane_b32 s16, v3, 36
	v_readlane_b32 s17, v11, 36
	s_waitcnt vmcnt(29)
	v_pk_fma_f32 v[6:7], v[102:103], s[20:21], v[6:7] op_sel_hi:[0,1,1]
	v_readlane_b32 s18, v3, 37
	v_readlane_b32 s19, v11, 37
	s_waitcnt vmcnt(28)
	v_pk_fma_f32 v[6:7], v[104:105], s[22:23], v[6:7] op_sel_hi:[0,1,1]
	v_readlane_b32 s20, v3, 38
	v_readlane_b32 s21, v11, 38
	s_waitcnt vmcnt(27)
	v_pk_fma_f32 v[6:7], v[106:107], s[16:17], v[6:7] op_sel_hi:[0,1,1]
	v_readlane_b32 s22, v3, 39
	v_readlane_b32 s23, v11, 39
	s_waitcnt vmcnt(26)
	v_pk_fma_f32 v[6:7], v[108:109], s[18:19], v[6:7] op_sel_hi:[0,1,1]
	v_readlane_b32 s16, v3, 40
	v_readlane_b32 s17, v11, 40
	s_waitcnt vmcnt(25)
	v_pk_fma_f32 v[6:7], v[110:111], s[20:21], v[6:7] op_sel_hi:[0,1,1]
	v_readlane_b32 s18, v3, 41
	v_readlane_b32 s19, v11, 41
	s_waitcnt vmcnt(24)
	v_pk_fma_f32 v[6:7], v[112:113], s[22:23], v[6:7] op_sel_hi:[0,1,1]
	v_readlane_b32 s20, v3, 42
	v_readlane_b32 s21, v11, 42
	s_waitcnt vmcnt(23)
	v_pk_fma_f32 v[6:7], v[114:115], s[16:17], v[6:7] op_sel_hi:[0,1,1]
	v_readlane_b32 s22, v3, 43
	v_readlane_b32 s23, v11, 43
	s_waitcnt vmcnt(22)
	v_pk_fma_f32 v[6:7], v[116:117], s[18:19], v[6:7] op_sel_hi:[0,1,1]
	v_readlane_b32 s16, v3, 44
	v_readlane_b32 s17, v11, 44
	s_waitcnt vmcnt(21)
	v_pk_fma_f32 v[6:7], v[118:119], s[20:21], v[6:7] op_sel_hi:[0,1,1]
	v_readlane_b32 s18, v3, 45
	v_readlane_b32 s19, v11, 45
	s_waitcnt vmcnt(20)
	v_pk_fma_f32 v[6:7], v[120:121], s[22:23], v[6:7] op_sel_hi:[0,1,1]
	v_readlane_b32 s20, v3, 46
	v_readlane_b32 s21, v11, 46
	s_waitcnt vmcnt(19)
	v_pk_fma_f32 v[6:7], v[122:123], s[16:17], v[6:7] op_sel_hi:[0,1,1]
	v_readlane_b32 s22, v3, 47
	v_readlane_b32 s23, v11, 47
	s_waitcnt vmcnt(18)
	v_pk_fma_f32 v[6:7], v[124:125], s[18:19], v[6:7] op_sel_hi:[0,1,1]
	v_readlane_b32 s16, v3, 48
	v_readlane_b32 s17, v11, 48
	s_waitcnt vmcnt(17)
	v_pk_fma_f32 v[6:7], v[126:127], s[20:21], v[6:7] op_sel_hi:[0,1,1]
	v_readlane_b32 s18, v3, 49
	v_readlane_b32 s19, v11, 49
	s_waitcnt vmcnt(16)
	v_pk_fma_f32 v[6:7], v[128:129], s[22:23], v[6:7] op_sel_hi:[0,1,1]
	v_readlane_b32 s20, v3, 50
	v_readlane_b32 s21, v11, 50
	s_waitcnt vmcnt(15)
	v_pk_fma_f32 v[6:7], v[130:131], s[16:17], v[6:7] op_sel_hi:[0,1,1]
	v_readlane_b32 s22, v3, 51
	v_readlane_b32 s23, v11, 51
	s_waitcnt vmcnt(14)
	v_pk_fma_f32 v[6:7], v[132:133], s[18:19], v[6:7] op_sel_hi:[0,1,1]
	v_readlane_b32 s16, v3, 52
	v_readlane_b32 s17, v11, 52
	s_waitcnt vmcnt(13)
	v_pk_fma_f32 v[6:7], v[134:135], s[20:21], v[6:7] op_sel_hi:[0,1,1]
	v_readlane_b32 s18, v3, 53
	v_readlane_b32 s19, v11, 53
	s_waitcnt vmcnt(12)
	v_pk_fma_f32 v[6:7], v[136:137], s[22:23], v[6:7] op_sel_hi:[0,1,1]
	v_readlane_b32 s20, v3, 54
	v_readlane_b32 s21, v11, 54
	s_waitcnt vmcnt(11)
	v_pk_fma_f32 v[6:7], v[138:139], s[16:17], v[6:7] op_sel_hi:[0,1,1]
	v_readlane_b32 s22, v3, 55
	v_readlane_b32 s23, v11, 55
	s_waitcnt vmcnt(10)
	v_pk_fma_f32 v[6:7], v[140:141], s[18:19], v[6:7] op_sel_hi:[0,1,1]
	v_readlane_b32 s16, v3, 56
	v_readlane_b32 s17, v11, 56
	s_waitcnt vmcnt(9)
	v_pk_fma_f32 v[6:7], v[142:143], s[20:21], v[6:7] op_sel_hi:[0,1,1]
	v_readlane_b32 s18, v3, 57
	v_readlane_b32 s19, v11, 57
	s_waitcnt vmcnt(8)
	v_pk_fma_f32 v[6:7], v[144:145], s[22:23], v[6:7] op_sel_hi:[0,1,1]
	v_readlane_b32 s20, v3, 58
	v_readlane_b32 s21, v11, 58
	s_waitcnt vmcnt(7)
	v_pk_fma_f32 v[6:7], v[146:147], s[16:17], v[6:7] op_sel_hi:[0,1,1]
	v_readlane_b32 s22, v3, 59
	v_readlane_b32 s23, v11, 59
	s_waitcnt vmcnt(6)
	v_pk_fma_f32 v[6:7], v[148:149], s[18:19], v[6:7] op_sel_hi:[0,1,1]
	v_readlane_b32 s16, v3, 60
	v_readlane_b32 s17, v11, 60
	s_waitcnt vmcnt(5)
	v_pk_fma_f32 v[6:7], v[150:151], s[20:21], v[6:7] op_sel_hi:[0,1,1]
	v_readlane_b32 s18, v3, 61
	v_readlane_b32 s19, v11, 61
	s_waitcnt vmcnt(4)
	v_pk_fma_f32 v[6:7], v[152:153], s[22:23], v[6:7] op_sel_hi:[0,1,1]
	v_readlane_b32 s20, v3, 62
	v_readlane_b32 s21, v11, 62
	s_waitcnt vmcnt(3)
	v_pk_fma_f32 v[6:7], v[154:155], s[16:17], v[6:7] op_sel_hi:[0,1,1]
	v_readlane_b32 s22, v3, 63
	v_readlane_b32 s23, v11, 63
	s_waitcnt vmcnt(2)
	v_pk_fma_f32 v[6:7], v[156:157], s[18:19], v[6:7] op_sel_hi:[0,1,1]
	s_waitcnt vmcnt(1)
	v_pk_fma_f32 v[6:7], v[158:159], s[20:21], v[6:7] op_sel_hi:[0,1,1]
	s_waitcnt vmcnt(0)
	v_pk_fma_f32 v[6:7], v[164:165], s[22:23], v[6:7] op_sel_hi:[0,1,1]
	s_mov_b64 s[0:1], 0
	s_cbranch_vccz .LBB0_668
	s_and_saveexec_b64 s[0:1], s[6:7]
	v_readlane_b32 s4, v250, 34
	v_readlane_b32 s5, v250, 35
	s_cbranch_execz .LBB0_666
	v_ashrrev_i32_e32 v3, 31, v2
	v_readlane_b32 s2, v250, 40
	v_lshlrev_b64 v[2:3], 2, v[2:3]
	v_readlane_b32 s3, v250, 41
	s_nop 1
	v_lshl_add_u64 v[4:5], s[2:3], 0, v[2:3]
	v_lshl_add_u64 v[2:3], s[4:5], 0, v[2:3]
	global_atomic_add_f32 v[2:3], v6, off
	global_atomic_add_f32 v[4:5], v7, off
	s_branch .LBB0_666

.LBB0_698:
	v_cndmask_b32_e64 v0, 0, 1, s[0:1]
	v_cmp_ne_u32_e32 vcc, 1, v0
	v_or_b32_e32 v0, s2, v10
	v_lshlrev_b64 v[8:9], 2, v[0:1]
	s_lshl_b32 s90, s2, 12
	v_lshl_add_u64 v[12:13], s[10:11], 0, v[8:9]
	v_lshl_add_u64 v[8:9], s[12:13], 0, v[8:9]
	global_load_dword v0, v[12:13], off
	global_load_dword v3, v[8:9], off
	v_lshl_add_u64 v[8:9], s[90:91], 2, v[4:5]
	s_mov_b32 s14, 0x4000
	s_mov_b32 s15, 0
	global_load_dword v32, v[8:9], off
	v_lshl_add_u64 v[8:9], v[8:9], 0, s[14:15]
	global_load_dword v34, v[8:9], off
	v_lshl_add_u64 v[8:9], v[8:9], 0, s[14:15]
	global_load_dword v36, v[8:9], off
	v_lshl_add_u64 v[8:9], v[8:9], 0, s[14:15]
	global_load_dword v38, v[8:9], off
	v_lshl_add_u64 v[8:9], v[8:9], 0, s[14:15]
	global_load_dword v40, v[8:9], off
	v_lshl_add_u64 v[8:9], v[8:9], 0, s[14:15]
	global_load_dword v42, v[8:9], off
	v_lshl_add_u64 v[8:9], v[8:9], 0, s[14:15]
	global_load_dword v44, v[8:9], off
	v_lshl_add_u64 v[8:9], v[8:9], 0, s[14:15]
	global_load_dword v46, v[8:9], off
	v_lshl_add_u64 v[8:9], v[8:9], 0, s[14:15]
	global_load_dword v48, v[8:9], off
	v_lshl_add_u64 v[8:9], v[8:9], 0, s[14:15]
	global_load_dword v50, v[8:9], off
	v_lshl_add_u64 v[8:9], v[8:9], 0, s[14:15]
	global_load_dword v52, v[8:9], off
	v_lshl_add_u64 v[8:9], v[8:9], 0, s[14:15]
	global_load_dword v54, v[8:9], off
	v_lshl_add_u64 v[8:9], v[8:9], 0, s[14:15]
	global_load_dword v58, v[8:9], off
	v_lshl_add_u64 v[8:9], v[8:9], 0, s[14:15]
	global_load_dword v60, v[8:9], off
	v_lshl_add_u64 v[8:9], v[8:9], 0, s[14:15]
	global_load_dword v62, v[8:9], off
	v_lshl_add_u64 v[8:9], v[8:9], 0, s[14:15]
	global_load_dword v64, v[8:9], off
	v_lshl_add_u64 v[8:9], v[8:9], 0, s[14:15]
	global_load_dword v66, v[8:9], off
	v_lshl_add_u64 v[8:9], v[8:9], 0, s[14:15]
	global_load_dword v68, v[8:9], off
	v_lshl_add_u64 v[8:9], v[8:9], 0, s[14:15]
	global_load_dword v70, v[8:9], off
	v_lshl_add_u64 v[8:9], v[8:9], 0, s[14:15]
	global_load_dword v72, v[8:9], off
	v_lshl_add_u64 v[8:9], v[8:9], 0, s[14:15]
	global_load_dword v74, v[8:9], off
	v_lshl_add_u64 v[8:9], v[8:9], 0, s[14:15]
	global_load_dword v76, v[8:9], off
	v_lshl_add_u64 v[8:9], v[8:9], 0, s[14:15]
	global_load_dword v78, v[8:9], off
	v_lshl_add_u64 v[8:9], v[8:9], 0, s[14:15]
	global_load_dword v80, v[8:9], off
	v_lshl_add_u64 v[8:9], v[8:9], 0, s[14:15]
	global_load_dword v82, v[8:9], off
	v_lshl_add_u64 v[8:9], v[8:9], 0, s[14:15]
	global_load_dword v84, v[8:9], off
	v_lshl_add_u64 v[8:9], v[8:9], 0, s[14:15]
	global_load_dword v86, v[8:9], off
	v_lshl_add_u64 v[8:9], v[8:9], 0, s[14:15]
	global_load_dword v88, v[8:9], off
	v_lshl_add_u64 v[8:9], v[8:9], 0, s[14:15]
	global_load_dword v90, v[8:9], off
	v_lshl_add_u64 v[8:9], v[8:9], 0, s[14:15]
	global_load_dword v92, v[8:9], off
	v_lshl_add_u64 v[8:9], v[8:9], 0, s[14:15]
	global_load_dword v94, v[8:9], off
	v_lshl_add_u64 v[8:9], v[8:9], 0, s[14:15]
	global_load_dword v96, v[8:9], off
	v_lshl_add_u64 v[8:9], v[8:9], 0, s[14:15]
	global_load_dword v98, v[8:9], off
	v_lshl_add_u64 v[8:9], v[8:9], 0, s[14:15]
	global_load_dword v100, v[8:9], off
	v_lshl_add_u64 v[8:9], v[8:9], 0, s[14:15]
	global_load_dword v102, v[8:9], off
	v_lshl_add_u64 v[8:9], v[8:9], 0, s[14:15]
	global_load_dword v104, v[8:9], off
	v_lshl_add_u64 v[8:9], v[8:9], 0, s[14:15]
	global_load_dword v106, v[8:9], off
	v_lshl_add_u64 v[8:9], v[8:9], 0, s[14:15]
	global_load_dword v108, v[8:9], off
	v_lshl_add_u64 v[8:9], v[8:9], 0, s[14:15]
	global_load_dword v110, v[8:9], off
	v_lshl_add_u64 v[8:9], v[8:9], 0, s[14:15]
	global_load_dword v112, v[8:9], off
	v_lshl_add_u64 v[8:9], v[8:9], 0, s[14:15]
	global_load_dword v114, v[8:9], off
	v_lshl_add_u64 v[8:9], v[8:9], 0, s[14:15]
	global_load_dword v116, v[8:9], off
	v_lshl_add_u64 v[8:9], v[8:9], 0, s[14:15]
	global_load_dword v118, v[8:9], off
	v_lshl_add_u64 v[8:9], v[8:9], 0, s[14:15]
	global_load_dword v120, v[8:9], off
	v_lshl_add_u64 v[8:9], v[8:9], 0, s[14:15]
	global_load_dword v122, v[8:9], off
	v_lshl_add_u64 v[8:9], v[8:9], 0, s[14:15]
	global_load_dword v124, v[8:9], off
	v_lshl_add_u64 v[8:9], v[8:9], 0, s[14:15]
	global_load_dword v126, v[8:9], off
	v_lshl_add_u64 v[8:9], v[8:9], 0, s[14:15]
	global_load_dword v128, v[8:9], off
	v_lshl_add_u64 v[8:9], v[8:9], 0, s[14:15]
	global_load_dword v130, v[8:9], off
	v_lshl_add_u64 v[8:9], v[8:9], 0, s[14:15]
	global_load_dword v132, v[8:9], off
	v_lshl_add_u64 v[8:9], v[8:9], 0, s[14:15]
	global_load_dword v134, v[8:9], off
	v_lshl_add_u64 v[8:9], v[8:9], 0, s[14:15]
	global_load_dword v136, v[8:9], off
	v_lshl_add_u64 v[8:9], v[8:9], 0, s[14:15]
	global_load_dword v138, v[8:9], off
	v_lshl_add_u64 v[8:9], v[8:9], 0, s[14:15]
	global_load_dword v140, v[8:9], off
	v_lshl_add_u64 v[8:9], v[8:9], 0, s[14:15]
	global_load_dword v142, v[8:9], off
	v_lshl_add_u64 v[8:9], v[8:9], 0, s[14:15]
	global_load_dword v144, v[8:9], off
	v_lshl_add_u64 v[8:9], v[8:9], 0, s[14:15]
	global_load_dword v146, v[8:9], off
	v_lshl_add_u64 v[8:9], v[8:9], 0, s[14:15]
	global_load_dword v148, v[8:9], off
	v_lshl_add_u64 v[8:9], v[8:9], 0, s[14:15]
	global_load_dword v150, v[8:9], off
	v_lshl_add_u64 v[8:9], v[8:9], 0, s[14:15]
	global_load_dword v152, v[8:9], off
	v_lshl_add_u64 v[8:9], v[8:9], 0, s[14:15]
	global_load_dword v154, v[8:9], off
	v_lshl_add_u64 v[8:9], v[8:9], 0, s[14:15]
	global_load_dword v156, v[8:9], off
	v_lshl_add_u64 v[8:9], v[8:9], 0, s[14:15]
	global_load_dword v158, v[8:9], off
	v_lshl_add_u64 v[8:9], v[8:9], 0, s[14:15]
	global_load_dword v164, v[8:9], off
	s_and_b64 vcc, exec, vcc
	s_mov_b32 s2, 64
	s_waitcnt vmcnt(63)
	v_readlane_b32 s16, v0, 0
	v_readlane_b32 s17, v3, 0
	v_readlane_b32 s18, v0, 1
	v_readlane_b32 s19, v3, 1
	v_readlane_b32 s20, v0, 2
	v_readlane_b32 s21, v3, 2
	v_pk_fma_f32 v[6:7], v[32:33], s[16:17], v[6:7] op_sel_hi:[0,1,1]
	v_readlane_b32 s22, v0, 3
	v_readlane_b32 s23, v3, 3
	s_waitcnt vmcnt(62)
	v_pk_fma_f32 v[6:7], v[34:35], s[18:19], v[6:7] op_sel_hi:[0,1,1]
	v_readlane_b32 s16, v0, 4
	v_readlane_b32 s17, v3, 4
	s_waitcnt vmcnt(61)
	v_pk_fma_f32 v[6:7], v[36:37], s[20:21], v[6:7] op_sel_hi:[0,1,1]
	v_readlane_b32 s18, v0, 5
	v_readlane_b32 s19, v3, 5
	s_waitcnt vmcnt(60)
	v_pk_fma_f32 v[6:7], v[38:39], s[22:23], v[6:7] op_sel_hi:[0,1,1]
	v_readlane_b32 s20, v0, 6
	v_readlane_b32 s21, v3, 6
	s_waitcnt vmcnt(59)
	v_pk_fma_f32 v[6:7], v[40:41], s[16:17], v[6:7] op_sel_hi:[0,1,1]
	v_readlane_b32 s22, v0, 7
	v_readlane_b32 s23, v3, 7
	s_waitcnt vmcnt(58)
	v_pk_fma_f32 v[6:7], v[42:43], s[18:19], v[6:7] op_sel_hi:[0,1,1]
	v_readlane_b32 s16, v0, 8
	v_readlane_b32 s17, v3, 8
	s_waitcnt vmcnt(57)
	v_pk_fma_f32 v[6:7], v[44:45], s[20:21], v[6:7] op_sel_hi:[0,1,1]
	v_readlane_b32 s18, v0, 9
	v_readlane_b32 s19, v3, 9
	s_waitcnt vmcnt(56)
	v_pk_fma_f32 v[6:7], v[46:47], s[22:23], v[6:7] op_sel_hi:[0,1,1]
	v_readlane_b32 s20, v0, 10
	v_readlane_b32 s21, v3, 10
	s_waitcnt vmcnt(55)
	v_pk_fma_f32 v[6:7], v[48:49], s[16:17], v[6:7] op_sel_hi:[0,1,1]
	v_readlane_b32 s22, v0, 11
	v_readlane_b32 s23, v3, 11
	s_waitcnt vmcnt(54)
	v_pk_fma_f32 v[6:7], v[50:51], s[18:19], v[6:7] op_sel_hi:[0,1,1]
	v_readlane_b32 s16, v0, 12
	v_readlane_b32 s17, v3, 12
	s_waitcnt vmcnt(53)
	v_pk_fma_f32 v[6:7], v[52:53], s[20:21], v[6:7] op_sel_hi:[0,1,1]
	v_readlane_b32 s18, v0, 13
	v_readlane_b32 s19, v3, 13
	s_waitcnt vmcnt(52)
	v_pk_fma_f32 v[6:7], v[54:55], s[22:23], v[6:7] op_sel_hi:[0,1,1]
	v_readlane_b32 s20, v0, 14
	v_readlane_b32 s21, v3, 14
	s_waitcnt vmcnt(51)
	v_pk_fma_f32 v[6:7], v[58:59], s[16:17], v[6:7] op_sel_hi:[0,1,1]
	v_readlane_b32 s22, v0, 15
	v_readlane_b32 s23, v3, 15
	s_waitcnt vmcnt(50)
	v_pk_fma_f32 v[6:7], v[60:61], s[18:19], v[6:7] op_sel_hi:[0,1,1]
	v_readlane_b32 s16, v0, 16
	v_readlane_b32 s17, v3, 16
	s_waitcnt vmcnt(49)
	v_pk_fma_f32 v[6:7], v[62:63], s[20:21], v[6:7] op_sel_hi:[0,1,1]
	v_readlane_b32 s18, v0, 17
	v_readlane_b32 s19, v3, 17
	s_waitcnt vmcnt(48)
	v_pk_fma_f32 v[6:7], v[64:65], s[22:23], v[6:7] op_sel_hi:[0,1,1]
	v_readlane_b32 s20, v0, 18
	v_readlane_b32 s21, v3, 18
	s_waitcnt vmcnt(47)
	v_pk_fma_f32 v[6:7], v[66:67], s[16:17], v[6:7] op_sel_hi:[0,1,1]
	v_readlane_b32 s22, v0, 19
	v_readlane_b32 s23, v3, 19
	s_waitcnt vmcnt(46)
	v_pk_fma_f32 v[6:7], v[68:69], s[18:19], v[6:7] op_sel_hi:[0,1,1]
	v_readlane_b32 s16, v0, 20
	v_readlane_b32 s17, v3, 20
	s_waitcnt vmcnt(45)
	v_pk_fma_f32 v[6:7], v[70:71], s[20:21], v[6:7] op_sel_hi:[0,1,1]
	v_readlane_b32 s18, v0, 21
	v_readlane_b32 s19, v3, 21
	s_waitcnt vmcnt(44)
	v_pk_fma_f32 v[6:7], v[72:73], s[22:23], v[6:7] op_sel_hi:[0,1,1]
	v_readlane_b32 s20, v0, 22
	v_readlane_b32 s21, v3, 22
	s_waitcnt vmcnt(43)
	v_pk_fma_f32 v[6:7], v[74:75], s[16:17], v[6:7] op_sel_hi:[0,1,1]
	v_readlane_b32 s22, v0, 23
	v_readlane_b32 s23, v3, 23
	s_waitcnt vmcnt(42)
	v_pk_fma_f32 v[6:7], v[76:77], s[18:19], v[6:7] op_sel_hi:[0,1,1]
	v_readlane_b32 s16, v0, 24
	v_readlane_b32 s17, v3, 24
	s_waitcnt vmcnt(41)
	v_pk_fma_f32 v[6:7], v[78:79], s[20:21], v[6:7] op_sel_hi:[0,1,1]
	v_readlane_b32 s18, v0, 25
	v_readlane_b32 s19, v3, 25
	s_waitcnt vmcnt(40)
	v_pk_fma_f32 v[6:7], v[80:81], s[22:23], v[6:7] op_sel_hi:[0,1,1]
	v_readlane_b32 s20, v0, 26
	v_readlane_b32 s21, v3, 26
	s_waitcnt vmcnt(39)
	v_pk_fma_f32 v[6:7], v[82:83], s[16:17], v[6:7] op_sel_hi:[0,1,1]
	v_readlane_b32 s22, v0, 27
	v_readlane_b32 s23, v3, 27
	s_waitcnt vmcnt(38)
	v_pk_fma_f32 v[6:7], v[84:85], s[18:19], v[6:7] op_sel_hi:[0,1,1]
	v_readlane_b32 s16, v0, 28
	v_readlane_b32 s17, v3, 28
	s_waitcnt vmcnt(37)
	v_pk_fma_f32 v[6:7], v[86:87], s[20:21], v[6:7] op_sel_hi:[0,1,1]
	v_readlane_b32 s18, v0, 29
	v_readlane_b32 s19, v3, 29
	s_waitcnt vmcnt(36)
	v_pk_fma_f32 v[6:7], v[88:89], s[22:23], v[6:7] op_sel_hi:[0,1,1]
	v_readlane_b32 s20, v0, 30
	v_readlane_b32 s21, v3, 30
	s_waitcnt vmcnt(35)
	v_pk_fma_f32 v[6:7], v[90:91], s[16:17], v[6:7] op_sel_hi:[0,1,1]
	v_readlane_b32 s22, v0, 31
	v_readlane_b32 s23, v3, 31
	s_waitcnt vmcnt(34)
	v_pk_fma_f32 v[6:7], v[92:93], s[18:19], v[6:7] op_sel_hi:[0,1,1]
	v_readlane_b32 s16, v0, 32
	v_readlane_b32 s17, v3, 32
	s_waitcnt vmcnt(33)
	v_pk_fma_f32 v[6:7], v[94:95], s[20:21], v[6:7] op_sel_hi:[0,1,1]
	v_readlane_b32 s18, v0, 33
	v_readlane_b32 s19, v3, 33
	s_waitcnt vmcnt(32)
	v_pk_fma_f32 v[6:7], v[96:97], s[22:23], v[6:7] op_sel_hi:[0,1,1]
	v_readlane_b32 s20, v0, 34
	v_readlane_b32 s21, v3, 34
	s_waitcnt vmcnt(31)
	v_pk_fma_f32 v[6:7], v[98:99], s[16:17], v[6:7] op_sel_hi:[0,1,1]
	v_readlane_b32 s22, v0, 35
	v_readlane_b32 s23, v3, 35
	s_waitcnt vmcnt(30)
	v_pk_fma_f32 v[6:7], v[100:101], s[18:19], v[6:7] op_sel_hi:[0,1,1]
	v_readlane_b32 s16, v0, 36
	v_readlane_b32 s17, v3, 36
	s_waitcnt vmcnt(29)
	v_pk_fma_f32 v[6:7], v[102:103], s[20:21], v[6:7] op_sel_hi:[0,1,1]
	v_readlane_b32 s18, v0, 37
	v_readlane_b32 s19, v3, 37
	s_waitcnt vmcnt(28)
	v_pk_fma_f32 v[6:7], v[104:105], s[22:23], v[6:7] op_sel_hi:[0,1,1]
	v_readlane_b32 s20, v0, 38
	v_readlane_b32 s21, v3, 38
	s_waitcnt vmcnt(27)
	v_pk_fma_f32 v[6:7], v[106:107], s[16:17], v[6:7] op_sel_hi:[0,1,1]
	v_readlane_b32 s22, v0, 39
	v_readlane_b32 s23, v3, 39
	s_waitcnt vmcnt(26)
	v_pk_fma_f32 v[6:7], v[108:109], s[18:19], v[6:7] op_sel_hi:[0,1,1]
	v_readlane_b32 s16, v0, 40
	v_readlane_b32 s17, v3, 40
	s_waitcnt vmcnt(25)
	v_pk_fma_f32 v[6:7], v[110:111], s[20:21], v[6:7] op_sel_hi:[0,1,1]
	v_readlane_b32 s18, v0, 41
	v_readlane_b32 s19, v3, 41
	s_waitcnt vmcnt(24)
	v_pk_fma_f32 v[6:7], v[112:113], s[22:23], v[6:7] op_sel_hi:[0,1,1]
	v_readlane_b32 s20, v0, 42
	v_readlane_b32 s21, v3, 42
	s_waitcnt vmcnt(23)
	v_pk_fma_f32 v[6:7], v[114:115], s[16:17], v[6:7] op_sel_hi:[0,1,1]
	v_readlane_b32 s22, v0, 43
	v_readlane_b32 s23, v3, 43
	s_waitcnt vmcnt(22)
	v_pk_fma_f32 v[6:7], v[116:117], s[18:19], v[6:7] op_sel_hi:[0,1,1]
	v_readlane_b32 s16, v0, 44
	v_readlane_b32 s17, v3, 44
	s_waitcnt vmcnt(21)
	v_pk_fma_f32 v[6:7], v[118:119], s[20:21], v[6:7] op_sel_hi:[0,1,1]
	v_readlane_b32 s18, v0, 45
	v_readlane_b32 s19, v3, 45
	s_waitcnt vmcnt(20)
	v_pk_fma_f32 v[6:7], v[120:121], s[22:23], v[6:7] op_sel_hi:[0,1,1]
	v_readlane_b32 s20, v0, 46
	v_readlane_b32 s21, v3, 46
	s_waitcnt vmcnt(19)
	v_pk_fma_f32 v[6:7], v[122:123], s[16:17], v[6:7] op_sel_hi:[0,1,1]
	v_readlane_b32 s22, v0, 47
	v_readlane_b32 s23, v3, 47
	s_waitcnt vmcnt(18)
	v_pk_fma_f32 v[6:7], v[124:125], s[18:19], v[6:7] op_sel_hi:[0,1,1]
	v_readlane_b32 s16, v0, 48
	v_readlane_b32 s17, v3, 48
	s_waitcnt vmcnt(17)
	v_pk_fma_f32 v[6:7], v[126:127], s[20:21], v[6:7] op_sel_hi:[0,1,1]
	v_readlane_b32 s18, v0, 49
	v_readlane_b32 s19, v3, 49
	s_waitcnt vmcnt(16)
	v_pk_fma_f32 v[6:7], v[128:129], s[22:23], v[6:7] op_sel_hi:[0,1,1]
	v_readlane_b32 s20, v0, 50
	v_readlane_b32 s21, v3, 50
	s_waitcnt vmcnt(15)
	v_pk_fma_f32 v[6:7], v[130:131], s[16:17], v[6:7] op_sel_hi:[0,1,1]
	v_readlane_b32 s22, v0, 51
	v_readlane_b32 s23, v3, 51
	s_waitcnt vmcnt(14)
	v_pk_fma_f32 v[6:7], v[132:133], s[18:19], v[6:7] op_sel_hi:[0,1,1]
	v_readlane_b32 s16, v0, 52
	v_readlane_b32 s17, v3, 52
	s_waitcnt vmcnt(13)
	v_pk_fma_f32 v[6:7], v[134:135], s[20:21], v[6:7] op_sel_hi:[0,1,1]
	v_readlane_b32 s18, v0, 53
	v_readlane_b32 s19, v3, 53
	s_waitcnt vmcnt(12)
	v_pk_fma_f32 v[6:7], v[136:137], s[22:23], v[6:7] op_sel_hi:[0,1,1]
	v_readlane_b32 s20, v0, 54
	v_readlane_b32 s21, v3, 54
	s_waitcnt vmcnt(11)
	v_pk_fma_f32 v[6:7], v[138:139], s[16:17], v[6:7] op_sel_hi:[0,1,1]
	v_readlane_b32 s22, v0, 55
	v_readlane_b32 s23, v3, 55
	s_waitcnt vmcnt(10)
	v_pk_fma_f32 v[6:7], v[140:141], s[18:19], v[6:7] op_sel_hi:[0,1,1]
	v_readlane_b32 s16, v0, 56
	v_readlane_b32 s17, v3, 56
	s_waitcnt vmcnt(9)
	v_pk_fma_f32 v[6:7], v[142:143], s[20:21], v[6:7] op_sel_hi:[0,1,1]
	v_readlane_b32 s18, v0, 57
	v_readlane_b32 s19, v3, 57
	s_waitcnt vmcnt(8)
	v_pk_fma_f32 v[6:7], v[144:145], s[22:23], v[6:7] op_sel_hi:[0,1,1]
	v_readlane_b32 s20, v0, 58
	v_readlane_b32 s21, v3, 58
	s_waitcnt vmcnt(7)
	v_pk_fma_f32 v[6:7], v[146:147], s[16:17], v[6:7] op_sel_hi:[0,1,1]
	v_readlane_b32 s22, v0, 59
	v_readlane_b32 s23, v3, 59
	s_waitcnt vmcnt(6)
	v_pk_fma_f32 v[6:7], v[148:149], s[18:19], v[6:7] op_sel_hi:[0,1,1]
	v_readlane_b32 s16, v0, 60
	v_readlane_b32 s17, v3, 60
	s_waitcnt vmcnt(5)
	v_pk_fma_f32 v[6:7], v[150:151], s[20:21], v[6:7] op_sel_hi:[0,1,1]
	v_readlane_b32 s18, v0, 61
	v_readlane_b32 s19, v3, 61
	s_waitcnt vmcnt(4)
	v_pk_fma_f32 v[6:7], v[152:153], s[22:23], v[6:7] op_sel_hi:[0,1,1]
	v_readlane_b32 s20, v0, 62
	v_readlane_b32 s21, v3, 62
	s_waitcnt vmcnt(3)
	v_pk_fma_f32 v[6:7], v[154:155], s[16:17], v[6:7] op_sel_hi:[0,1,1]
	v_readlane_b32 s22, v0, 63
	v_readlane_b32 s23, v3, 63
	s_waitcnt vmcnt(2)
	v_pk_fma_f32 v[6:7], v[156:157], s[18:19], v[6:7] op_sel_hi:[0,1,1]
	s_waitcnt vmcnt(1)
	v_pk_fma_f32 v[6:7], v[158:159], s[20:21], v[6:7] op_sel_hi:[0,1,1]
	s_waitcnt vmcnt(0)
	v_pk_fma_f32 v[6:7], v[164:165], s[22:23], v[6:7] op_sel_hi:[0,1,1]
	s_mov_b64 s[0:1], 0
	s_cbranch_vccz .LBB0_698
	s_and_saveexec_b64 s[0:1], s[6:7]
	s_cbranch_execz .LBB0_696
	v_ashrrev_i32_e32 v3, 31, v2
	v_readlane_b32 s2, v250, 54
	v_lshlrev_b64 v[2:3], 2, v[2:3]
	v_readlane_b32 s3, v250, 55
	s_nop 1
	v_lshl_add_u64 v[4:5], s[2:3], 0, v[2:3]
	v_readlane_b32 s2, v250, 42
	v_readlane_b32 s3, v250, 43
	s_nop 1
	v_lshl_add_u64 v[2:3], s[2:3], 0, v[2:3]
	global_atomic_add_f32 v[2:3], v6, off
	global_atomic_add_f32 v[4:5], v7, off
	s_branch .LBB0_696

.LBB0_722:
	v_cndmask_b32_e64 v0, 0, 1, s[0:1]
	v_cmp_ne_u32_e32 vcc, 1, v0
	v_or_b32_e32 v0, s11, v10
	v_lshlrev_b64 v[8:9], 2, v[0:1]
	s_lshl_b32 s90, s11, 10
	v_lshl_add_u64 v[12:13], s[2:3], 0, v[8:9]
	v_lshl_add_u64 v[8:9], s[4:5], 0, v[8:9]
	global_load_dword v3, v[12:13], off
	global_load_dword v11, v[8:9], off
	v_lshl_add_u64 v[8:9], s[90:91], 2, v[4:5]
	s_mov_b32 s14, 0x1000
	s_mov_b32 s15, 0
	global_load_dword v32, v[8:9], off
	v_lshl_add_u64 v[8:9], v[8:9], 0, s[14:15]
	global_load_dword v34, v[8:9], off
	v_lshl_add_u64 v[8:9], v[8:9], 0, s[14:15]
	global_load_dword v36, v[8:9], off
	v_lshl_add_u64 v[8:9], v[8:9], 0, s[14:15]
	global_load_dword v38, v[8:9], off
	v_lshl_add_u64 v[8:9], v[8:9], 0, s[14:15]
	global_load_dword v40, v[8:9], off
	v_lshl_add_u64 v[8:9], v[8:9], 0, s[14:15]
	global_load_dword v42, v[8:9], off
	v_lshl_add_u64 v[8:9], v[8:9], 0, s[14:15]
	global_load_dword v44, v[8:9], off
	v_lshl_add_u64 v[8:9], v[8:9], 0, s[14:15]
	global_load_dword v46, v[8:9], off
	v_lshl_add_u64 v[8:9], v[8:9], 0, s[14:15]
	global_load_dword v48, v[8:9], off
	v_lshl_add_u64 v[8:9], v[8:9], 0, s[14:15]
	global_load_dword v50, v[8:9], off
	v_lshl_add_u64 v[8:9], v[8:9], 0, s[14:15]
	global_load_dword v52, v[8:9], off
	v_lshl_add_u64 v[8:9], v[8:9], 0, s[14:15]
	global_load_dword v54, v[8:9], off
	v_lshl_add_u64 v[8:9], v[8:9], 0, s[14:15]
	global_load_dword v58, v[8:9], off
	v_lshl_add_u64 v[8:9], v[8:9], 0, s[14:15]
	global_load_dword v60, v[8:9], off
	v_lshl_add_u64 v[8:9], v[8:9], 0, s[14:15]
	global_load_dword v62, v[8:9], off
	v_lshl_add_u64 v[8:9], v[8:9], 0, s[14:15]
	global_load_dword v64, v[8:9], off
	v_lshl_add_u64 v[8:9], v[8:9], 0, s[14:15]
	global_load_dword v66, v[8:9], off
	v_lshl_add_u64 v[8:9], v[8:9], 0, s[14:15]
	global_load_dword v68, v[8:9], off
	v_lshl_add_u64 v[8:9], v[8:9], 0, s[14:15]
	global_load_dword v70, v[8:9], off
	v_lshl_add_u64 v[8:9], v[8:9], 0, s[14:15]
	global_load_dword v72, v[8:9], off
	v_lshl_add_u64 v[8:9], v[8:9], 0, s[14:15]
	global_load_dword v74, v[8:9], off
	v_lshl_add_u64 v[8:9], v[8:9], 0, s[14:15]
	global_load_dword v76, v[8:9], off
	v_lshl_add_u64 v[8:9], v[8:9], 0, s[14:15]
	global_load_dword v78, v[8:9], off
	v_lshl_add_u64 v[8:9], v[8:9], 0, s[14:15]
	global_load_dword v80, v[8:9], off
	v_lshl_add_u64 v[8:9], v[8:9], 0, s[14:15]
	global_load_dword v82, v[8:9], off
	v_lshl_add_u64 v[8:9], v[8:9], 0, s[14:15]
	global_load_dword v84, v[8:9], off
	v_lshl_add_u64 v[8:9], v[8:9], 0, s[14:15]
	global_load_dword v86, v[8:9], off
	v_lshl_add_u64 v[8:9], v[8:9], 0, s[14:15]
	global_load_dword v88, v[8:9], off
	v_lshl_add_u64 v[8:9], v[8:9], 0, s[14:15]
	global_load_dword v90, v[8:9], off
	v_lshl_add_u64 v[8:9], v[8:9], 0, s[14:15]
	global_load_dword v92, v[8:9], off
	v_lshl_add_u64 v[8:9], v[8:9], 0, s[14:15]
	global_load_dword v94, v[8:9], off
	v_lshl_add_u64 v[8:9], v[8:9], 0, s[14:15]
	global_load_dword v96, v[8:9], off
	v_lshl_add_u64 v[8:9], v[8:9], 0, s[14:15]
	global_load_dword v98, v[8:9], off
	v_lshl_add_u64 v[8:9], v[8:9], 0, s[14:15]
	global_load_dword v100, v[8:9], off
	v_lshl_add_u64 v[8:9], v[8:9], 0, s[14:15]
	global_load_dword v102, v[8:9], off
	v_lshl_add_u64 v[8:9], v[8:9], 0, s[14:15]
	global_load_dword v104, v[8:9], off
	v_lshl_add_u64 v[8:9], v[8:9], 0, s[14:15]
	global_load_dword v106, v[8:9], off
	v_lshl_add_u64 v[8:9], v[8:9], 0, s[14:15]
	global_load_dword v108, v[8:9], off
	v_lshl_add_u64 v[8:9], v[8:9], 0, s[14:15]
	global_load_dword v110, v[8:9], off
	v_lshl_add_u64 v[8:9], v[8:9], 0, s[14:15]
	global_load_dword v112, v[8:9], off
	v_lshl_add_u64 v[8:9], v[8:9], 0, s[14:15]
	global_load_dword v114, v[8:9], off
	v_lshl_add_u64 v[8:9], v[8:9], 0, s[14:15]
	global_load_dword v116, v[8:9], off
	v_lshl_add_u64 v[8:9], v[8:9], 0, s[14:15]
	global_load_dword v118, v[8:9], off
	v_lshl_add_u64 v[8:9], v[8:9], 0, s[14:15]
	global_load_dword v120, v[8:9], off
	v_lshl_add_u64 v[8:9], v[8:9], 0, s[14:15]
	global_load_dword v122, v[8:9], off
	v_lshl_add_u64 v[8:9], v[8:9], 0, s[14:15]
	global_load_dword v124, v[8:9], off
	v_lshl_add_u64 v[8:9], v[8:9], 0, s[14:15]
	global_load_dword v126, v[8:9], off
	v_lshl_add_u64 v[8:9], v[8:9], 0, s[14:15]
	global_load_dword v128, v[8:9], off
	v_lshl_add_u64 v[8:9], v[8:9], 0, s[14:15]
	global_load_dword v130, v[8:9], off
	v_lshl_add_u64 v[8:9], v[8:9], 0, s[14:15]
	global_load_dword v132, v[8:9], off
	v_lshl_add_u64 v[8:9], v[8:9], 0, s[14:15]
	global_load_dword v134, v[8:9], off
	v_lshl_add_u64 v[8:9], v[8:9], 0, s[14:15]
	global_load_dword v136, v[8:9], off
	v_lshl_add_u64 v[8:9], v[8:9], 0, s[14:15]
	global_load_dword v138, v[8:9], off
	v_lshl_add_u64 v[8:9], v[8:9], 0, s[14:15]
	global_load_dword v140, v[8:9], off
	v_lshl_add_u64 v[8:9], v[8:9], 0, s[14:15]
	global_load_dword v142, v[8:9], off
	v_lshl_add_u64 v[8:9], v[8:9], 0, s[14:15]
	global_load_dword v144, v[8:9], off
	v_lshl_add_u64 v[8:9], v[8:9], 0, s[14:15]
	global_load_dword v146, v[8:9], off
	v_lshl_add_u64 v[8:9], v[8:9], 0, s[14:15]
	global_load_dword v148, v[8:9], off
	v_lshl_add_u64 v[8:9], v[8:9], 0, s[14:15]
	global_load_dword v150, v[8:9], off
	v_lshl_add_u64 v[8:9], v[8:9], 0, s[14:15]
	global_load_dword v152, v[8:9], off
	v_lshl_add_u64 v[8:9], v[8:9], 0, s[14:15]
	global_load_dword v154, v[8:9], off
	v_lshl_add_u64 v[8:9], v[8:9], 0, s[14:15]
	global_load_dword v156, v[8:9], off
	v_lshl_add_u64 v[8:9], v[8:9], 0, s[14:15]
	global_load_dword v158, v[8:9], off
	v_lshl_add_u64 v[8:9], v[8:9], 0, s[14:15]
	global_load_dword v164, v[8:9], off
	s_mov_b32 s11, 64
	s_and_b64 vcc, exec, vcc
	s_waitcnt vmcnt(63)
	v_readlane_b32 s16, v3, 0
	v_readlane_b32 s17, v11, 0
	v_readlane_b32 s18, v3, 1
	v_readlane_b32 s19, v11, 1
	v_readlane_b32 s20, v3, 2
	v_readlane_b32 s21, v11, 2
	v_pk_fma_f32 v[6:7], v[32:33], s[16:17], v[6:7] op_sel_hi:[0,1,1]
	v_readlane_b32 s22, v3, 3
	v_readlane_b32 s23, v11, 3
	s_waitcnt vmcnt(62)
	v_pk_fma_f32 v[6:7], v[34:35], s[18:19], v[6:7] op_sel_hi:[0,1,1]
	v_readlane_b32 s16, v3, 4
	v_readlane_b32 s17, v11, 4
	s_waitcnt vmcnt(61)
	v_pk_fma_f32 v[6:7], v[36:37], s[20:21], v[6:7] op_sel_hi:[0,1,1]
	v_readlane_b32 s18, v3, 5
	v_readlane_b32 s19, v11, 5
	s_waitcnt vmcnt(60)
	v_pk_fma_f32 v[6:7], v[38:39], s[22:23], v[6:7] op_sel_hi:[0,1,1]
	v_readlane_b32 s20, v3, 6
	v_readlane_b32 s21, v11, 6
	s_waitcnt vmcnt(59)
	v_pk_fma_f32 v[6:7], v[40:41], s[16:17], v[6:7] op_sel_hi:[0,1,1]
	v_readlane_b32 s22, v3, 7
	v_readlane_b32 s23, v11, 7
	s_waitcnt vmcnt(58)
	v_pk_fma_f32 v[6:7], v[42:43], s[18:19], v[6:7] op_sel_hi:[0,1,1]
	v_readlane_b32 s16, v3, 8
	v_readlane_b32 s17, v11, 8
	s_waitcnt vmcnt(57)
	v_pk_fma_f32 v[6:7], v[44:45], s[20:21], v[6:7] op_sel_hi:[0,1,1]
	v_readlane_b32 s18, v3, 9
	v_readlane_b32 s19, v11, 9
	s_waitcnt vmcnt(56)
	v_pk_fma_f32 v[6:7], v[46:47], s[22:23], v[6:7] op_sel_hi:[0,1,1]
	v_readlane_b32 s20, v3, 10
	v_readlane_b32 s21, v11, 10
	s_waitcnt vmcnt(55)
	v_pk_fma_f32 v[6:7], v[48:49], s[16:17], v[6:7] op_sel_hi:[0,1,1]
	v_readlane_b32 s22, v3, 11
	v_readlane_b32 s23, v11, 11
	s_waitcnt vmcnt(54)
	v_pk_fma_f32 v[6:7], v[50:51], s[18:19], v[6:7] op_sel_hi:[0,1,1]
	v_readlane_b32 s16, v3, 12
	v_readlane_b32 s17, v11, 12
	s_waitcnt vmcnt(53)
	v_pk_fma_f32 v[6:7], v[52:53], s[20:21], v[6:7] op_sel_hi:[0,1,1]
	v_readlane_b32 s18, v3, 13
	v_readlane_b32 s19, v11, 13
	s_waitcnt vmcnt(52)
	v_pk_fma_f32 v[6:7], v[54:55], s[22:23], v[6:7] op_sel_hi:[0,1,1]
	v_readlane_b32 s20, v3, 14
	v_readlane_b32 s21, v11, 14
	s_waitcnt vmcnt(51)
	v_pk_fma_f32 v[6:7], v[58:59], s[16:17], v[6:7] op_sel_hi:[0,1,1]
	v_readlane_b32 s22, v3, 15
	v_readlane_b32 s23, v11, 15
	s_waitcnt vmcnt(50)
	v_pk_fma_f32 v[6:7], v[60:61], s[18:19], v[6:7] op_sel_hi:[0,1,1]
	v_readlane_b32 s16, v3, 16
	v_readlane_b32 s17, v11, 16
	s_waitcnt vmcnt(49)
	v_pk_fma_f32 v[6:7], v[62:63], s[20:21], v[6:7] op_sel_hi:[0,1,1]
	v_readlane_b32 s18, v3, 17
	v_readlane_b32 s19, v11, 17
	s_waitcnt vmcnt(48)
	v_pk_fma_f32 v[6:7], v[64:65], s[22:23], v[6:7] op_sel_hi:[0,1,1]
	v_readlane_b32 s20, v3, 18
	v_readlane_b32 s21, v11, 18
	s_waitcnt vmcnt(47)
	v_pk_fma_f32 v[6:7], v[66:67], s[16:17], v[6:7] op_sel_hi:[0,1,1]
	v_readlane_b32 s22, v3, 19
	v_readlane_b32 s23, v11, 19
	s_waitcnt vmcnt(46)
	v_pk_fma_f32 v[6:7], v[68:69], s[18:19], v[6:7] op_sel_hi:[0,1,1]
	v_readlane_b32 s16, v3, 20
	v_readlane_b32 s17, v11, 20
	s_waitcnt vmcnt(45)
	v_pk_fma_f32 v[6:7], v[70:71], s[20:21], v[6:7] op_sel_hi:[0,1,1]
	v_readlane_b32 s18, v3, 21
	v_readlane_b32 s19, v11, 21
	s_waitcnt vmcnt(44)
	v_pk_fma_f32 v[6:7], v[72:73], s[22:23], v[6:7] op_sel_hi:[0,1,1]
	v_readlane_b32 s20, v3, 22
	v_readlane_b32 s21, v11, 22
	s_waitcnt vmcnt(43)
	v_pk_fma_f32 v[6:7], v[74:75], s[16:17], v[6:7] op_sel_hi:[0,1,1]
	v_readlane_b32 s22, v3, 23
	v_readlane_b32 s23, v11, 23
	s_waitcnt vmcnt(42)
	v_pk_fma_f32 v[6:7], v[76:77], s[18:19], v[6:7] op_sel_hi:[0,1,1]
	v_readlane_b32 s16, v3, 24
	v_readlane_b32 s17, v11, 24
	s_waitcnt vmcnt(41)
	v_pk_fma_f32 v[6:7], v[78:79], s[20:21], v[6:7] op_sel_hi:[0,1,1]
	v_readlane_b32 s18, v3, 25
	v_readlane_b32 s19, v11, 25
	s_waitcnt vmcnt(40)
	v_pk_fma_f32 v[6:7], v[80:81], s[22:23], v[6:7] op_sel_hi:[0,1,1]
	v_readlane_b32 s20, v3, 26
	v_readlane_b32 s21, v11, 26
	s_waitcnt vmcnt(39)
	v_pk_fma_f32 v[6:7], v[82:83], s[16:17], v[6:7] op_sel_hi:[0,1,1]
	v_readlane_b32 s22, v3, 27
	v_readlane_b32 s23, v11, 27
	s_waitcnt vmcnt(38)
	v_pk_fma_f32 v[6:7], v[84:85], s[18:19], v[6:7] op_sel_hi:[0,1,1]
	v_readlane_b32 s16, v3, 28
	v_readlane_b32 s17, v11, 28
	s_waitcnt vmcnt(37)
	v_pk_fma_f32 v[6:7], v[86:87], s[20:21], v[6:7] op_sel_hi:[0,1,1]
	v_readlane_b32 s18, v3, 29
	v_readlane_b32 s19, v11, 29
	s_waitcnt vmcnt(36)
	v_pk_fma_f32 v[6:7], v[88:89], s[22:23], v[6:7] op_sel_hi:[0,1,1]
	v_readlane_b32 s20, v3, 30
	v_readlane_b32 s21, v11, 30
	s_waitcnt vmcnt(35)
	v_pk_fma_f32 v[6:7], v[90:91], s[16:17], v[6:7] op_sel_hi:[0,1,1]
	v_readlane_b32 s22, v3, 31
	v_readlane_b32 s23, v11, 31
	s_waitcnt vmcnt(34)
	v_pk_fma_f32 v[6:7], v[92:93], s[18:19], v[6:7] op_sel_hi:[0,1,1]
	v_readlane_b32 s16, v3, 32
	v_readlane_b32 s17, v11, 32
	s_waitcnt vmcnt(33)
	v_pk_fma_f32 v[6:7], v[94:95], s[20:21], v[6:7] op_sel_hi:[0,1,1]
	v_readlane_b32 s18, v3, 33
	v_readlane_b32 s19, v11, 33
	s_waitcnt vmcnt(32)
	v_pk_fma_f32 v[6:7], v[96:97], s[22:23], v[6:7] op_sel_hi:[0,1,1]
	v_readlane_b32 s20, v3, 34
	v_readlane_b32 s21, v11, 34
	s_waitcnt vmcnt(31)
	v_pk_fma_f32 v[6:7], v[98:99], s[16:17], v[6:7] op_sel_hi:[0,1,1]
	v_readlane_b32 s22, v3, 35
	v_readlane_b32 s23, v11, 35
	s_waitcnt vmcnt(30)
	v_pk_fma_f32 v[6:7], v[100:101], s[18:19], v[6:7] op_sel_hi:[0,1,1]
	v_readlane_b32 s16, v3, 36
	v_readlane_b32 s17, v11, 36
	s_waitcnt vmcnt(29)
	v_pk_fma_f32 v[6:7], v[102:103], s[20:21], v[6:7] op_sel_hi:[0,1,1]
	v_readlane_b32 s18, v3, 37
	v_readlane_b32 s19, v11, 37
	s_waitcnt vmcnt(28)
	v_pk_fma_f32 v[6:7], v[104:105], s[22:23], v[6:7] op_sel_hi:[0,1,1]
	v_readlane_b32 s20, v3, 38
	v_readlane_b32 s21, v11, 38
	s_waitcnt vmcnt(27)
	v_pk_fma_f32 v[6:7], v[106:107], s[16:17], v[6:7] op_sel_hi:[0,1,1]
	v_readlane_b32 s22, v3, 39
	v_readlane_b32 s23, v11, 39
	s_waitcnt vmcnt(26)
	v_pk_fma_f32 v[6:7], v[108:109], s[18:19], v[6:7] op_sel_hi:[0,1,1]
	v_readlane_b32 s16, v3, 40
	v_readlane_b32 s17, v11, 40
	s_waitcnt vmcnt(25)
	v_pk_fma_f32 v[6:7], v[110:111], s[20:21], v[6:7] op_sel_hi:[0,1,1]
	v_readlane_b32 s18, v3, 41
	v_readlane_b32 s19, v11, 41
	s_waitcnt vmcnt(24)
	v_pk_fma_f32 v[6:7], v[112:113], s[22:23], v[6:7] op_sel_hi:[0,1,1]
	v_readlane_b32 s20, v3, 42
	v_readlane_b32 s21, v11, 42
	s_waitcnt vmcnt(23)
	v_pk_fma_f32 v[6:7], v[114:115], s[16:17], v[6:7] op_sel_hi:[0,1,1]
	v_readlane_b32 s22, v3, 43
	v_readlane_b32 s23, v11, 43
	s_waitcnt vmcnt(22)
	v_pk_fma_f32 v[6:7], v[116:117], s[18:19], v[6:7] op_sel_hi:[0,1,1]
	v_readlane_b32 s16, v3, 44
	v_readlane_b32 s17, v11, 44
	s_waitcnt vmcnt(21)
	v_pk_fma_f32 v[6:7], v[118:119], s[20:21], v[6:7] op_sel_hi:[0,1,1]
	v_readlane_b32 s18, v3, 45
	v_readlane_b32 s19, v11, 45
	s_waitcnt vmcnt(20)
	v_pk_fma_f32 v[6:7], v[120:121], s[22:23], v[6:7] op_sel_hi:[0,1,1]
	v_readlane_b32 s20, v3, 46
	v_readlane_b32 s21, v11, 46
	s_waitcnt vmcnt(19)
	v_pk_fma_f32 v[6:7], v[122:123], s[16:17], v[6:7] op_sel_hi:[0,1,1]
	v_readlane_b32 s22, v3, 47
	v_readlane_b32 s23, v11, 47
	s_waitcnt vmcnt(18)
	v_pk_fma_f32 v[6:7], v[124:125], s[18:19], v[6:7] op_sel_hi:[0,1,1]
	v_readlane_b32 s16, v3, 48
	v_readlane_b32 s17, v11, 48
	s_waitcnt vmcnt(17)
	v_pk_fma_f32 v[6:7], v[126:127], s[20:21], v[6:7] op_sel_hi:[0,1,1]
	v_readlane_b32 s18, v3, 49
	v_readlane_b32 s19, v11, 49
	s_waitcnt vmcnt(16)
	v_pk_fma_f32 v[6:7], v[128:129], s[22:23], v[6:7] op_sel_hi:[0,1,1]
	v_readlane_b32 s20, v3, 50
	v_readlane_b32 s21, v11, 50
	s_waitcnt vmcnt(15)
	v_pk_fma_f32 v[6:7], v[130:131], s[16:17], v[6:7] op_sel_hi:[0,1,1]
	v_readlane_b32 s22, v3, 51
	v_readlane_b32 s23, v11, 51
	s_waitcnt vmcnt(14)
	v_pk_fma_f32 v[6:7], v[132:133], s[18:19], v[6:7] op_sel_hi:[0,1,1]
	v_readlane_b32 s16, v3, 52
	v_readlane_b32 s17, v11, 52
	s_waitcnt vmcnt(13)
	v_pk_fma_f32 v[6:7], v[134:135], s[20:21], v[6:7] op_sel_hi:[0,1,1]
	v_readlane_b32 s18, v3, 53
	v_readlane_b32 s19, v11, 53
	s_waitcnt vmcnt(12)
	v_pk_fma_f32 v[6:7], v[136:137], s[22:23], v[6:7] op_sel_hi:[0,1,1]
	v_readlane_b32 s20, v3, 54
	v_readlane_b32 s21, v11, 54
	s_waitcnt vmcnt(11)
	v_pk_fma_f32 v[6:7], v[138:139], s[16:17], v[6:7] op_sel_hi:[0,1,1]
	v_readlane_b32 s22, v3, 55
	v_readlane_b32 s23, v11, 55
	s_waitcnt vmcnt(10)
	v_pk_fma_f32 v[6:7], v[140:141], s[18:19], v[6:7] op_sel_hi:[0,1,1]
	v_readlane_b32 s16, v3, 56
	v_readlane_b32 s17, v11, 56
	s_waitcnt vmcnt(9)
	v_pk_fma_f32 v[6:7], v[142:143], s[20:21], v[6:7] op_sel_hi:[0,1,1]
	v_readlane_b32 s18, v3, 57
	v_readlane_b32 s19, v11, 57
	s_waitcnt vmcnt(8)
	v_pk_fma_f32 v[6:7], v[144:145], s[22:23], v[6:7] op_sel_hi:[0,1,1]
	v_readlane_b32 s20, v3, 58
	v_readlane_b32 s21, v11, 58
	s_waitcnt vmcnt(7)
	v_pk_fma_f32 v[6:7], v[146:147], s[16:17], v[6:7] op_sel_hi:[0,1,1]
	v_readlane_b32 s22, v3, 59
	v_readlane_b32 s23, v11, 59
	s_waitcnt vmcnt(6)
	v_pk_fma_f32 v[6:7], v[148:149], s[18:19], v[6:7] op_sel_hi:[0,1,1]
	v_readlane_b32 s16, v3, 60
	v_readlane_b32 s17, v11, 60
	s_waitcnt vmcnt(5)
	v_pk_fma_f32 v[6:7], v[150:151], s[20:21], v[6:7] op_sel_hi:[0,1,1]
	v_readlane_b32 s18, v3, 61
	v_readlane_b32 s19, v11, 61
	s_waitcnt vmcnt(4)
	v_pk_fma_f32 v[6:7], v[152:153], s[22:23], v[6:7] op_sel_hi:[0,1,1]
	v_readlane_b32 s20, v3, 62
	v_readlane_b32 s21, v11, 62
	s_waitcnt vmcnt(3)
	v_pk_fma_f32 v[6:7], v[154:155], s[16:17], v[6:7] op_sel_hi:[0,1,1]
	v_readlane_b32 s22, v3, 63
	v_readlane_b32 s23, v11, 63
	s_waitcnt vmcnt(2)
	v_pk_fma_f32 v[6:7], v[156:157], s[18:19], v[6:7] op_sel_hi:[0,1,1]
	s_waitcnt vmcnt(1)
	v_pk_fma_f32 v[6:7], v[158:159], s[20:21], v[6:7] op_sel_hi:[0,1,1]
	s_waitcnt vmcnt(0)
	v_pk_fma_f32 v[6:7], v[164:165], s[22:23], v[6:7] op_sel_hi:[0,1,1]
	s_mov_b64 s[0:1], 0
	s_cbranch_vccz .LBB0_722
	s_and_saveexec_b64 s[0:1], s[6:7]
	v_readlane_b32 s4, v250, 48
	v_readlane_b32 s5, v250, 49
	s_cbranch_execz .LBB0_720
	v_ashrrev_i32_e32 v3, 31, v2
	v_readlane_b32 s2, v250, 60
	v_lshlrev_b64 v[2:3], 2, v[2:3]
	v_readlane_b32 s3, v250, 61
	s_nop 1
	v_lshl_add_u64 v[4:5], s[2:3], 0, v[2:3]
	v_lshl_add_u64 v[2:3], s[4:5], 0, v[2:3]
	global_atomic_add_f32 v[2:3], v6, off
	global_atomic_add_f32 v[4:5], v7, off
	s_branch .LBB0_720

.LBB0_742:
	v_cndmask_b32_e64 v0, 0, 1, s[0:1]
	v_cmp_ne_u32_e32 vcc, 1, v0
	v_or_b32_e32 v0, s11, v10
	v_lshlrev_b64 v[8:9], 2, v[0:1]
	s_lshl_b32 s90, s11, 10
	v_lshl_add_u64 v[12:13], s[2:3], 0, v[8:9]
	v_lshl_add_u64 v[8:9], s[4:5], 0, v[8:9]
	global_load_dword v3, v[12:13], off
	global_load_dword v11, v[8:9], off
	v_lshl_add_u64 v[8:9], s[90:91], 2, v[4:5]
	s_mov_b32 s14, 0x1000
	s_mov_b32 s15, 0
	global_load_dword v32, v[8:9], off
	v_lshl_add_u64 v[8:9], v[8:9], 0, s[14:15]
	global_load_dword v34, v[8:9], off
	v_lshl_add_u64 v[8:9], v[8:9], 0, s[14:15]
	global_load_dword v36, v[8:9], off
	v_lshl_add_u64 v[8:9], v[8:9], 0, s[14:15]
	global_load_dword v38, v[8:9], off
	v_lshl_add_u64 v[8:9], v[8:9], 0, s[14:15]
	global_load_dword v40, v[8:9], off
	v_lshl_add_u64 v[8:9], v[8:9], 0, s[14:15]
	global_load_dword v42, v[8:9], off
	v_lshl_add_u64 v[8:9], v[8:9], 0, s[14:15]
	global_load_dword v44, v[8:9], off
	v_lshl_add_u64 v[8:9], v[8:9], 0, s[14:15]
	global_load_dword v46, v[8:9], off
	v_lshl_add_u64 v[8:9], v[8:9], 0, s[14:15]
	global_load_dword v48, v[8:9], off
	v_lshl_add_u64 v[8:9], v[8:9], 0, s[14:15]
	global_load_dword v50, v[8:9], off
	v_lshl_add_u64 v[8:9], v[8:9], 0, s[14:15]
	global_load_dword v52, v[8:9], off
	v_lshl_add_u64 v[8:9], v[8:9], 0, s[14:15]
	global_load_dword v54, v[8:9], off
	v_lshl_add_u64 v[8:9], v[8:9], 0, s[14:15]
	global_load_dword v58, v[8:9], off
	v_lshl_add_u64 v[8:9], v[8:9], 0, s[14:15]
	global_load_dword v60, v[8:9], off
	v_lshl_add_u64 v[8:9], v[8:9], 0, s[14:15]
	global_load_dword v62, v[8:9], off
	v_lshl_add_u64 v[8:9], v[8:9], 0, s[14:15]
	global_load_dword v64, v[8:9], off
	v_lshl_add_u64 v[8:9], v[8:9], 0, s[14:15]
	global_load_dword v66, v[8:9], off
	v_lshl_add_u64 v[8:9], v[8:9], 0, s[14:15]
	global_load_dword v68, v[8:9], off
	v_lshl_add_u64 v[8:9], v[8:9], 0, s[14:15]
	global_load_dword v70, v[8:9], off
	v_lshl_add_u64 v[8:9], v[8:9], 0, s[14:15]
	global_load_dword v72, v[8:9], off
	v_lshl_add_u64 v[8:9], v[8:9], 0, s[14:15]
	global_load_dword v74, v[8:9], off
	v_lshl_add_u64 v[8:9], v[8:9], 0, s[14:15]
	global_load_dword v76, v[8:9], off
	v_lshl_add_u64 v[8:9], v[8:9], 0, s[14:15]
	global_load_dword v78, v[8:9], off
	v_lshl_add_u64 v[8:9], v[8:9], 0, s[14:15]
	global_load_dword v80, v[8:9], off
	v_lshl_add_u64 v[8:9], v[8:9], 0, s[14:15]
	global_load_dword v82, v[8:9], off
	v_lshl_add_u64 v[8:9], v[8:9], 0, s[14:15]
	global_load_dword v84, v[8:9], off
	v_lshl_add_u64 v[8:9], v[8:9], 0, s[14:15]
	global_load_dword v86, v[8:9], off
	v_lshl_add_u64 v[8:9], v[8:9], 0, s[14:15]
	global_load_dword v88, v[8:9], off
	v_lshl_add_u64 v[8:9], v[8:9], 0, s[14:15]
	global_load_dword v90, v[8:9], off
	v_lshl_add_u64 v[8:9], v[8:9], 0, s[14:15]
	global_load_dword v92, v[8:9], off
	v_lshl_add_u64 v[8:9], v[8:9], 0, s[14:15]
	global_load_dword v94, v[8:9], off
	v_lshl_add_u64 v[8:9], v[8:9], 0, s[14:15]
	global_load_dword v96, v[8:9], off
	v_lshl_add_u64 v[8:9], v[8:9], 0, s[14:15]
	global_load_dword v98, v[8:9], off
	v_lshl_add_u64 v[8:9], v[8:9], 0, s[14:15]
	global_load_dword v100, v[8:9], off
	v_lshl_add_u64 v[8:9], v[8:9], 0, s[14:15]
	global_load_dword v102, v[8:9], off
	v_lshl_add_u64 v[8:9], v[8:9], 0, s[14:15]
	global_load_dword v104, v[8:9], off
	v_lshl_add_u64 v[8:9], v[8:9], 0, s[14:15]
	global_load_dword v106, v[8:9], off
	v_lshl_add_u64 v[8:9], v[8:9], 0, s[14:15]
	global_load_dword v108, v[8:9], off
	v_lshl_add_u64 v[8:9], v[8:9], 0, s[14:15]
	global_load_dword v110, v[8:9], off
	v_lshl_add_u64 v[8:9], v[8:9], 0, s[14:15]
	global_load_dword v112, v[8:9], off
	v_lshl_add_u64 v[8:9], v[8:9], 0, s[14:15]
	global_load_dword v114, v[8:9], off
	v_lshl_add_u64 v[8:9], v[8:9], 0, s[14:15]
	global_load_dword v116, v[8:9], off
	v_lshl_add_u64 v[8:9], v[8:9], 0, s[14:15]
	global_load_dword v118, v[8:9], off
	v_lshl_add_u64 v[8:9], v[8:9], 0, s[14:15]
	global_load_dword v120, v[8:9], off
	v_lshl_add_u64 v[8:9], v[8:9], 0, s[14:15]
	global_load_dword v122, v[8:9], off
	v_lshl_add_u64 v[8:9], v[8:9], 0, s[14:15]
	global_load_dword v124, v[8:9], off
	v_lshl_add_u64 v[8:9], v[8:9], 0, s[14:15]
	global_load_dword v126, v[8:9], off
	v_lshl_add_u64 v[8:9], v[8:9], 0, s[14:15]
	global_load_dword v128, v[8:9], off
	v_lshl_add_u64 v[8:9], v[8:9], 0, s[14:15]
	global_load_dword v130, v[8:9], off
	v_lshl_add_u64 v[8:9], v[8:9], 0, s[14:15]
	global_load_dword v132, v[8:9], off
	v_lshl_add_u64 v[8:9], v[8:9], 0, s[14:15]
	global_load_dword v134, v[8:9], off
	v_lshl_add_u64 v[8:9], v[8:9], 0, s[14:15]
	global_load_dword v136, v[8:9], off
	v_lshl_add_u64 v[8:9], v[8:9], 0, s[14:15]
	global_load_dword v138, v[8:9], off
	v_lshl_add_u64 v[8:9], v[8:9], 0, s[14:15]
	global_load_dword v140, v[8:9], off
	v_lshl_add_u64 v[8:9], v[8:9], 0, s[14:15]
	global_load_dword v142, v[8:9], off
	v_lshl_add_u64 v[8:9], v[8:9], 0, s[14:15]
	global_load_dword v144, v[8:9], off
	v_lshl_add_u64 v[8:9], v[8:9], 0, s[14:15]
	global_load_dword v146, v[8:9], off
	v_lshl_add_u64 v[8:9], v[8:9], 0, s[14:15]
	global_load_dword v148, v[8:9], off
	v_lshl_add_u64 v[8:9], v[8:9], 0, s[14:15]
	global_load_dword v150, v[8:9], off
	v_lshl_add_u64 v[8:9], v[8:9], 0, s[14:15]
	global_load_dword v152, v[8:9], off
	v_lshl_add_u64 v[8:9], v[8:9], 0, s[14:15]
	global_load_dword v154, v[8:9], off
	v_lshl_add_u64 v[8:9], v[8:9], 0, s[14:15]
	global_load_dword v156, v[8:9], off
	v_lshl_add_u64 v[8:9], v[8:9], 0, s[14:15]
	global_load_dword v158, v[8:9], off
	v_lshl_add_u64 v[8:9], v[8:9], 0, s[14:15]
	global_load_dword v164, v[8:9], off
	s_mov_b32 s11, 64
	s_and_b64 vcc, exec, vcc
	s_waitcnt vmcnt(63)
	v_readlane_b32 s16, v3, 0
	v_readlane_b32 s17, v11, 0
	v_readlane_b32 s18, v3, 1
	v_readlane_b32 s19, v11, 1
	v_readlane_b32 s20, v3, 2
	v_readlane_b32 s21, v11, 2
	v_pk_fma_f32 v[6:7], v[32:33], s[16:17], v[6:7] op_sel_hi:[0,1,1]
	v_readlane_b32 s22, v3, 3
	v_readlane_b32 s23, v11, 3
	s_waitcnt vmcnt(62)
	v_pk_fma_f32 v[6:7], v[34:35], s[18:19], v[6:7] op_sel_hi:[0,1,1]
	v_readlane_b32 s16, v3, 4
	v_readlane_b32 s17, v11, 4
	s_waitcnt vmcnt(61)
	v_pk_fma_f32 v[6:7], v[36:37], s[20:21], v[6:7] op_sel_hi:[0,1,1]
	v_readlane_b32 s18, v3, 5
	v_readlane_b32 s19, v11, 5
	s_waitcnt vmcnt(60)
	v_pk_fma_f32 v[6:7], v[38:39], s[22:23], v[6:7] op_sel_hi:[0,1,1]
	v_readlane_b32 s20, v3, 6
	v_readlane_b32 s21, v11, 6
	s_waitcnt vmcnt(59)
	v_pk_fma_f32 v[6:7], v[40:41], s[16:17], v[6:7] op_sel_hi:[0,1,1]
	v_readlane_b32 s22, v3, 7
	v_readlane_b32 s23, v11, 7
	s_waitcnt vmcnt(58)
	v_pk_fma_f32 v[6:7], v[42:43], s[18:19], v[6:7] op_sel_hi:[0,1,1]
	v_readlane_b32 s16, v3, 8
	v_readlane_b32 s17, v11, 8
	s_waitcnt vmcnt(57)
	v_pk_fma_f32 v[6:7], v[44:45], s[20:21], v[6:7] op_sel_hi:[0,1,1]
	v_readlane_b32 s18, v3, 9
	v_readlane_b32 s19, v11, 9
	s_waitcnt vmcnt(56)
	v_pk_fma_f32 v[6:7], v[46:47], s[22:23], v[6:7] op_sel_hi:[0,1,1]
	v_readlane_b32 s20, v3, 10
	v_readlane_b32 s21, v11, 10
	s_waitcnt vmcnt(55)
	v_pk_fma_f32 v[6:7], v[48:49], s[16:17], v[6:7] op_sel_hi:[0,1,1]
	v_readlane_b32 s22, v3, 11
	v_readlane_b32 s23, v11, 11
	s_waitcnt vmcnt(54)
	v_pk_fma_f32 v[6:7], v[50:51], s[18:19], v[6:7] op_sel_hi:[0,1,1]
	v_readlane_b32 s16, v3, 12
	v_readlane_b32 s17, v11, 12
	s_waitcnt vmcnt(53)
	v_pk_fma_f32 v[6:7], v[52:53], s[20:21], v[6:7] op_sel_hi:[0,1,1]
	v_readlane_b32 s18, v3, 13
	v_readlane_b32 s19, v11, 13
	s_waitcnt vmcnt(52)
	v_pk_fma_f32 v[6:7], v[54:55], s[22:23], v[6:7] op_sel_hi:[0,1,1]
	v_readlane_b32 s20, v3, 14
	v_readlane_b32 s21, v11, 14
	s_waitcnt vmcnt(51)
	v_pk_fma_f32 v[6:7], v[58:59], s[16:17], v[6:7] op_sel_hi:[0,1,1]
	v_readlane_b32 s22, v3, 15
	v_readlane_b32 s23, v11, 15
	s_waitcnt vmcnt(50)
	v_pk_fma_f32 v[6:7], v[60:61], s[18:19], v[6:7] op_sel_hi:[0,1,1]
	v_readlane_b32 s16, v3, 16
	v_readlane_b32 s17, v11, 16
	s_waitcnt vmcnt(49)
	v_pk_fma_f32 v[6:7], v[62:63], s[20:21], v[6:7] op_sel_hi:[0,1,1]
	v_readlane_b32 s18, v3, 17
	v_readlane_b32 s19, v11, 17
	s_waitcnt vmcnt(48)
	v_pk_fma_f32 v[6:7], v[64:65], s[22:23], v[6:7] op_sel_hi:[0,1,1]
	v_readlane_b32 s20, v3, 18
	v_readlane_b32 s21, v11, 18
	s_waitcnt vmcnt(47)
	v_pk_fma_f32 v[6:7], v[66:67], s[16:17], v[6:7] op_sel_hi:[0,1,1]
	v_readlane_b32 s22, v3, 19
	v_readlane_b32 s23, v11, 19
	s_waitcnt vmcnt(46)
	v_pk_fma_f32 v[6:7], v[68:69], s[18:19], v[6:7] op_sel_hi:[0,1,1]
	v_readlane_b32 s16, v3, 20
	v_readlane_b32 s17, v11, 20
	s_waitcnt vmcnt(45)
	v_pk_fma_f32 v[6:7], v[70:71], s[20:21], v[6:7] op_sel_hi:[0,1,1]
	v_readlane_b32 s18, v3, 21
	v_readlane_b32 s19, v11, 21
	s_waitcnt vmcnt(44)
	v_pk_fma_f32 v[6:7], v[72:73], s[22:23], v[6:7] op_sel_hi:[0,1,1]
	v_readlane_b32 s20, v3, 22
	v_readlane_b32 s21, v11, 22
	s_waitcnt vmcnt(43)
	v_pk_fma_f32 v[6:7], v[74:75], s[16:17], v[6:7] op_sel_hi:[0,1,1]
	v_readlane_b32 s22, v3, 23
	v_readlane_b32 s23, v11, 23
	s_waitcnt vmcnt(42)
	v_pk_fma_f32 v[6:7], v[76:77], s[18:19], v[6:7] op_sel_hi:[0,1,1]
	v_readlane_b32 s16, v3, 24
	v_readlane_b32 s17, v11, 24
	s_waitcnt vmcnt(41)
	v_pk_fma_f32 v[6:7], v[78:79], s[20:21], v[6:7] op_sel_hi:[0,1,1]
	v_readlane_b32 s18, v3, 25
	v_readlane_b32 s19, v11, 25
	s_waitcnt vmcnt(40)
	v_pk_fma_f32 v[6:7], v[80:81], s[22:23], v[6:7] op_sel_hi:[0,1,1]
	v_readlane_b32 s20, v3, 26
	v_readlane_b32 s21, v11, 26
	s_waitcnt vmcnt(39)
	v_pk_fma_f32 v[6:7], v[82:83], s[16:17], v[6:7] op_sel_hi:[0,1,1]
	v_readlane_b32 s22, v3, 27
	v_readlane_b32 s23, v11, 27
	s_waitcnt vmcnt(38)
	v_pk_fma_f32 v[6:7], v[84:85], s[18:19], v[6:7] op_sel_hi:[0,1,1]
	v_readlane_b32 s16, v3, 28
	v_readlane_b32 s17, v11, 28
	s_waitcnt vmcnt(37)
	v_pk_fma_f32 v[6:7], v[86:87], s[20:21], v[6:7] op_sel_hi:[0,1,1]
	v_readlane_b32 s18, v3, 29
	v_readlane_b32 s19, v11, 29
	s_waitcnt vmcnt(36)
	v_pk_fma_f32 v[6:7], v[88:89], s[22:23], v[6:7] op_sel_hi:[0,1,1]
	v_readlane_b32 s20, v3, 30
	v_readlane_b32 s21, v11, 30
	s_waitcnt vmcnt(35)
	v_pk_fma_f32 v[6:7], v[90:91], s[16:17], v[6:7] op_sel_hi:[0,1,1]
	v_readlane_b32 s22, v3, 31
	v_readlane_b32 s23, v11, 31
	s_waitcnt vmcnt(34)
	v_pk_fma_f32 v[6:7], v[92:93], s[18:19], v[6:7] op_sel_hi:[0,1,1]
	v_readlane_b32 s16, v3, 32
	v_readlane_b32 s17, v11, 32
	s_waitcnt vmcnt(33)
	v_pk_fma_f32 v[6:7], v[94:95], s[20:21], v[6:7] op_sel_hi:[0,1,1]
	v_readlane_b32 s18, v3, 33
	v_readlane_b32 s19, v11, 33
	s_waitcnt vmcnt(32)
	v_pk_fma_f32 v[6:7], v[96:97], s[22:23], v[6:7] op_sel_hi:[0,1,1]
	v_readlane_b32 s20, v3, 34
	v_readlane_b32 s21, v11, 34
	s_waitcnt vmcnt(31)
	v_pk_fma_f32 v[6:7], v[98:99], s[16:17], v[6:7] op_sel_hi:[0,1,1]
	v_readlane_b32 s22, v3, 35
	v_readlane_b32 s23, v11, 35
	s_waitcnt vmcnt(30)
	v_pk_fma_f32 v[6:7], v[100:101], s[18:19], v[6:7] op_sel_hi:[0,1,1]
	v_readlane_b32 s16, v3, 36
	v_readlane_b32 s17, v11, 36
	s_waitcnt vmcnt(29)
	v_pk_fma_f32 v[6:7], v[102:103], s[20:21], v[6:7] op_sel_hi:[0,1,1]
	v_readlane_b32 s18, v3, 37
	v_readlane_b32 s19, v11, 37
	s_waitcnt vmcnt(28)
	v_pk_fma_f32 v[6:7], v[104:105], s[22:23], v[6:7] op_sel_hi:[0,1,1]
	v_readlane_b32 s20, v3, 38
	v_readlane_b32 s21, v11, 38
	s_waitcnt vmcnt(27)
	v_pk_fma_f32 v[6:7], v[106:107], s[16:17], v[6:7] op_sel_hi:[0,1,1]
	v_readlane_b32 s22, v3, 39
	v_readlane_b32 s23, v11, 39
	s_waitcnt vmcnt(26)
	v_pk_fma_f32 v[6:7], v[108:109], s[18:19], v[6:7] op_sel_hi:[0,1,1]
	v_readlane_b32 s16, v3, 40
	v_readlane_b32 s17, v11, 40
	s_waitcnt vmcnt(25)
	v_pk_fma_f32 v[6:7], v[110:111], s[20:21], v[6:7] op_sel_hi:[0,1,1]
	v_readlane_b32 s18, v3, 41
	v_readlane_b32 s19, v11, 41
	s_waitcnt vmcnt(24)
	v_pk_fma_f32 v[6:7], v[112:113], s[22:23], v[6:7] op_sel_hi:[0,1,1]
	v_readlane_b32 s20, v3, 42
	v_readlane_b32 s21, v11, 42
	s_waitcnt vmcnt(23)
	v_pk_fma_f32 v[6:7], v[114:115], s[16:17], v[6:7] op_sel_hi:[0,1,1]
	v_readlane_b32 s22, v3, 43
	v_readlane_b32 s23, v11, 43
	s_waitcnt vmcnt(22)
	v_pk_fma_f32 v[6:7], v[116:117], s[18:19], v[6:7] op_sel_hi:[0,1,1]
	v_readlane_b32 s16, v3, 44
	v_readlane_b32 s17, v11, 44
	s_waitcnt vmcnt(21)
	v_pk_fma_f32 v[6:7], v[118:119], s[20:21], v[6:7] op_sel_hi:[0,1,1]
	v_readlane_b32 s18, v3, 45
	v_readlane_b32 s19, v11, 45
	s_waitcnt vmcnt(20)
	v_pk_fma_f32 v[6:7], v[120:121], s[22:23], v[6:7] op_sel_hi:[0,1,1]
	v_readlane_b32 s20, v3, 46
	v_readlane_b32 s21, v11, 46
	s_waitcnt vmcnt(19)
	v_pk_fma_f32 v[6:7], v[122:123], s[16:17], v[6:7] op_sel_hi:[0,1,1]
	v_readlane_b32 s22, v3, 47
	v_readlane_b32 s23, v11, 47
	s_waitcnt vmcnt(18)
	v_pk_fma_f32 v[6:7], v[124:125], s[18:19], v[6:7] op_sel_hi:[0,1,1]
	v_readlane_b32 s16, v3, 48
	v_readlane_b32 s17, v11, 48
	s_waitcnt vmcnt(17)
	v_pk_fma_f32 v[6:7], v[126:127], s[20:21], v[6:7] op_sel_hi:[0,1,1]
	v_readlane_b32 s18, v3, 49
	v_readlane_b32 s19, v11, 49
	s_waitcnt vmcnt(16)
	v_pk_fma_f32 v[6:7], v[128:129], s[22:23], v[6:7] op_sel_hi:[0,1,1]
	v_readlane_b32 s20, v3, 50
	v_readlane_b32 s21, v11, 50
	s_waitcnt vmcnt(15)
	v_pk_fma_f32 v[6:7], v[130:131], s[16:17], v[6:7] op_sel_hi:[0,1,1]
	v_readlane_b32 s22, v3, 51
	v_readlane_b32 s23, v11, 51
	s_waitcnt vmcnt(14)
	v_pk_fma_f32 v[6:7], v[132:133], s[18:19], v[6:7] op_sel_hi:[0,1,1]
	v_readlane_b32 s16, v3, 52
	v_readlane_b32 s17, v11, 52
	s_waitcnt vmcnt(13)
	v_pk_fma_f32 v[6:7], v[134:135], s[20:21], v[6:7] op_sel_hi:[0,1,1]
	v_readlane_b32 s18, v3, 53
	v_readlane_b32 s19, v11, 53
	s_waitcnt vmcnt(12)
	v_pk_fma_f32 v[6:7], v[136:137], s[22:23], v[6:7] op_sel_hi:[0,1,1]
	v_readlane_b32 s20, v3, 54
	v_readlane_b32 s21, v11, 54
	s_waitcnt vmcnt(11)
	v_pk_fma_f32 v[6:7], v[138:139], s[16:17], v[6:7] op_sel_hi:[0,1,1]
	v_readlane_b32 s22, v3, 55
	v_readlane_b32 s23, v11, 55
	s_waitcnt vmcnt(10)
	v_pk_fma_f32 v[6:7], v[140:141], s[18:19], v[6:7] op_sel_hi:[0,1,1]
	v_readlane_b32 s16, v3, 56
	v_readlane_b32 s17, v11, 56
	s_waitcnt vmcnt(9)
	v_pk_fma_f32 v[6:7], v[142:143], s[20:21], v[6:7] op_sel_hi:[0,1,1]
	v_readlane_b32 s18, v3, 57
	v_readlane_b32 s19, v11, 57
	s_waitcnt vmcnt(8)
	v_pk_fma_f32 v[6:7], v[144:145], s[22:23], v[6:7] op_sel_hi:[0,1,1]
	v_readlane_b32 s20, v3, 58
	v_readlane_b32 s21, v11, 58
	s_waitcnt vmcnt(7)
	v_pk_fma_f32 v[6:7], v[146:147], s[16:17], v[6:7] op_sel_hi:[0,1,1]
	v_readlane_b32 s22, v3, 59
	v_readlane_b32 s23, v11, 59
	s_waitcnt vmcnt(6)
	v_pk_fma_f32 v[6:7], v[148:149], s[18:19], v[6:7] op_sel_hi:[0,1,1]
	v_readlane_b32 s16, v3, 60
	v_readlane_b32 s17, v11, 60
	s_waitcnt vmcnt(5)
	v_pk_fma_f32 v[6:7], v[150:151], s[20:21], v[6:7] op_sel_hi:[0,1,1]
	v_readlane_b32 s18, v3, 61
	v_readlane_b32 s19, v11, 61
	s_waitcnt vmcnt(4)
	v_pk_fma_f32 v[6:7], v[152:153], s[22:23], v[6:7] op_sel_hi:[0,1,1]
	v_readlane_b32 s20, v3, 62
	v_readlane_b32 s21, v11, 62
	s_waitcnt vmcnt(3)
	v_pk_fma_f32 v[6:7], v[154:155], s[16:17], v[6:7] op_sel_hi:[0,1,1]
	v_readlane_b32 s22, v3, 63
	v_readlane_b32 s23, v11, 63
	s_waitcnt vmcnt(2)
	v_pk_fma_f32 v[6:7], v[156:157], s[18:19], v[6:7] op_sel_hi:[0,1,1]
	s_waitcnt vmcnt(1)
	v_pk_fma_f32 v[6:7], v[158:159], s[20:21], v[6:7] op_sel_hi:[0,1,1]
	s_waitcnt vmcnt(0)
	v_pk_fma_f32 v[6:7], v[164:165], s[22:23], v[6:7] op_sel_hi:[0,1,1]
	s_mov_b64 s[0:1], 0
	s_cbranch_vccz .LBB0_742
	s_and_saveexec_b64 s[0:1], s[6:7]
	s_cbranch_execz .LBB0_740
	v_ashrrev_i32_e32 v3, 31, v2
	v_readlane_b32 s2, v251, 4
	v_lshlrev_b64 v[2:3], 2, v[2:3]
	v_readlane_b32 s3, v251, 5
	s_nop 1
	v_lshl_add_u64 v[4:5], s[2:3], 0, v[2:3]
	v_readlane_b32 s2, v250, 62
	v_readlane_b32 s3, v250, 63
	s_nop 1
	v_lshl_add_u64 v[2:3], s[2:3], 0, v[2:3]
	global_atomic_add_f32 v[2:3], v6, off
	global_atomic_add_f32 v[4:5], v7, off
	s_branch .LBB0_740

.LBB0_749:
	v_cndmask_b32_e64 v0, 0, 1, s[0:1]
	v_cmp_ne_u32_e32 vcc, 1, v0
	v_or_b32_e32 v0, s11, v10
	v_lshlrev_b64 v[8:9], 2, v[0:1]
	s_lshl_b32 s90, s11, 10
	v_lshl_add_u64 v[12:13], s[2:3], 0, v[8:9]
	v_lshl_add_u64 v[8:9], s[4:5], 0, v[8:9]
	global_load_dword v3, v[12:13], off
	global_load_dword v11, v[8:9], off
	v_lshl_add_u64 v[8:9], s[90:91], 2, v[4:5]
	s_mov_b32 s14, 0x1000
	s_mov_b32 s15, 0
	global_load_dword v32, v[8:9], off
	v_lshl_add_u64 v[8:9], v[8:9], 0, s[14:15]
	global_load_dword v34, v[8:9], off
	v_lshl_add_u64 v[8:9], v[8:9], 0, s[14:15]
	global_load_dword v36, v[8:9], off
	v_lshl_add_u64 v[8:9], v[8:9], 0, s[14:15]
	global_load_dword v38, v[8:9], off
	v_lshl_add_u64 v[8:9], v[8:9], 0, s[14:15]
	global_load_dword v40, v[8:9], off
	v_lshl_add_u64 v[8:9], v[8:9], 0, s[14:15]
	global_load_dword v42, v[8:9], off
	v_lshl_add_u64 v[8:9], v[8:9], 0, s[14:15]
	global_load_dword v44, v[8:9], off
	v_lshl_add_u64 v[8:9], v[8:9], 0, s[14:15]
	global_load_dword v46, v[8:9], off
	v_lshl_add_u64 v[8:9], v[8:9], 0, s[14:15]
	global_load_dword v48, v[8:9], off
	v_lshl_add_u64 v[8:9], v[8:9], 0, s[14:15]
	global_load_dword v50, v[8:9], off
	v_lshl_add_u64 v[8:9], v[8:9], 0, s[14:15]
	global_load_dword v52, v[8:9], off
	v_lshl_add_u64 v[8:9], v[8:9], 0, s[14:15]
	global_load_dword v54, v[8:9], off
	v_lshl_add_u64 v[8:9], v[8:9], 0, s[14:15]
	global_load_dword v58, v[8:9], off
	v_lshl_add_u64 v[8:9], v[8:9], 0, s[14:15]
	global_load_dword v60, v[8:9], off
	v_lshl_add_u64 v[8:9], v[8:9], 0, s[14:15]
	global_load_dword v62, v[8:9], off
	v_lshl_add_u64 v[8:9], v[8:9], 0, s[14:15]
	global_load_dword v64, v[8:9], off
	v_lshl_add_u64 v[8:9], v[8:9], 0, s[14:15]
	global_load_dword v66, v[8:9], off
	v_lshl_add_u64 v[8:9], v[8:9], 0, s[14:15]
	global_load_dword v68, v[8:9], off
	v_lshl_add_u64 v[8:9], v[8:9], 0, s[14:15]
	global_load_dword v70, v[8:9], off
	v_lshl_add_u64 v[8:9], v[8:9], 0, s[14:15]
	global_load_dword v72, v[8:9], off
	v_lshl_add_u64 v[8:9], v[8:9], 0, s[14:15]
	global_load_dword v74, v[8:9], off
	v_lshl_add_u64 v[8:9], v[8:9], 0, s[14:15]
	global_load_dword v76, v[8:9], off
	v_lshl_add_u64 v[8:9], v[8:9], 0, s[14:15]
	global_load_dword v78, v[8:9], off
	v_lshl_add_u64 v[8:9], v[8:9], 0, s[14:15]
	global_load_dword v80, v[8:9], off
	v_lshl_add_u64 v[8:9], v[8:9], 0, s[14:15]
	global_load_dword v82, v[8:9], off
	v_lshl_add_u64 v[8:9], v[8:9], 0, s[14:15]
	global_load_dword v84, v[8:9], off
	v_lshl_add_u64 v[8:9], v[8:9], 0, s[14:15]
	global_load_dword v86, v[8:9], off
	v_lshl_add_u64 v[8:9], v[8:9], 0, s[14:15]
	global_load_dword v88, v[8:9], off
	v_lshl_add_u64 v[8:9], v[8:9], 0, s[14:15]
	global_load_dword v90, v[8:9], off
	v_lshl_add_u64 v[8:9], v[8:9], 0, s[14:15]
	global_load_dword v92, v[8:9], off
	v_lshl_add_u64 v[8:9], v[8:9], 0, s[14:15]
	global_load_dword v94, v[8:9], off
	v_lshl_add_u64 v[8:9], v[8:9], 0, s[14:15]
	global_load_dword v96, v[8:9], off
	v_lshl_add_u64 v[8:9], v[8:9], 0, s[14:15]
	global_load_dword v98, v[8:9], off
	v_lshl_add_u64 v[8:9], v[8:9], 0, s[14:15]
	global_load_dword v100, v[8:9], off
	v_lshl_add_u64 v[8:9], v[8:9], 0, s[14:15]
	global_load_dword v102, v[8:9], off
	v_lshl_add_u64 v[8:9], v[8:9], 0, s[14:15]
	global_load_dword v104, v[8:9], off
	v_lshl_add_u64 v[8:9], v[8:9], 0, s[14:15]
	global_load_dword v106, v[8:9], off
	v_lshl_add_u64 v[8:9], v[8:9], 0, s[14:15]
	global_load_dword v108, v[8:9], off
	v_lshl_add_u64 v[8:9], v[8:9], 0, s[14:15]
	global_load_dword v110, v[8:9], off
	v_lshl_add_u64 v[8:9], v[8:9], 0, s[14:15]
	global_load_dword v112, v[8:9], off
	v_lshl_add_u64 v[8:9], v[8:9], 0, s[14:15]
	global_load_dword v114, v[8:9], off
	v_lshl_add_u64 v[8:9], v[8:9], 0, s[14:15]
	global_load_dword v116, v[8:9], off
	v_lshl_add_u64 v[8:9], v[8:9], 0, s[14:15]
	global_load_dword v118, v[8:9], off
	v_lshl_add_u64 v[8:9], v[8:9], 0, s[14:15]
	global_load_dword v120, v[8:9], off
	v_lshl_add_u64 v[8:9], v[8:9], 0, s[14:15]
	global_load_dword v122, v[8:9], off
	v_lshl_add_u64 v[8:9], v[8:9], 0, s[14:15]
	global_load_dword v124, v[8:9], off
	v_lshl_add_u64 v[8:9], v[8:9], 0, s[14:15]
	global_load_dword v126, v[8:9], off
	v_lshl_add_u64 v[8:9], v[8:9], 0, s[14:15]
	global_load_dword v128, v[8:9], off
	v_lshl_add_u64 v[8:9], v[8:9], 0, s[14:15]
	global_load_dword v130, v[8:9], off
	v_lshl_add_u64 v[8:9], v[8:9], 0, s[14:15]
	global_load_dword v132, v[8:9], off
	v_lshl_add_u64 v[8:9], v[8:9], 0, s[14:15]
	global_load_dword v134, v[8:9], off
	v_lshl_add_u64 v[8:9], v[8:9], 0, s[14:15]
	global_load_dword v136, v[8:9], off
	v_lshl_add_u64 v[8:9], v[8:9], 0, s[14:15]
	global_load_dword v138, v[8:9], off
	v_lshl_add_u64 v[8:9], v[8:9], 0, s[14:15]
	global_load_dword v140, v[8:9], off
	v_lshl_add_u64 v[8:9], v[8:9], 0, s[14:15]
	global_load_dword v142, v[8:9], off
	v_lshl_add_u64 v[8:9], v[8:9], 0, s[14:15]
	global_load_dword v144, v[8:9], off
	v_lshl_add_u64 v[8:9], v[8:9], 0, s[14:15]
	global_load_dword v146, v[8:9], off
	v_lshl_add_u64 v[8:9], v[8:9], 0, s[14:15]
	global_load_dword v148, v[8:9], off
	v_lshl_add_u64 v[8:9], v[8:9], 0, s[14:15]
	global_load_dword v150, v[8:9], off
	v_lshl_add_u64 v[8:9], v[8:9], 0, s[14:15]
	global_load_dword v152, v[8:9], off
	v_lshl_add_u64 v[8:9], v[8:9], 0, s[14:15]
	global_load_dword v154, v[8:9], off
	v_lshl_add_u64 v[8:9], v[8:9], 0, s[14:15]
	global_load_dword v156, v[8:9], off
	v_lshl_add_u64 v[8:9], v[8:9], 0, s[14:15]
	global_load_dword v158, v[8:9], off
	v_lshl_add_u64 v[8:9], v[8:9], 0, s[14:15]
	global_load_dword v164, v[8:9], off
	s_mov_b32 s11, 64
	s_and_b64 vcc, exec, vcc
	s_waitcnt vmcnt(63)
	v_readlane_b32 s16, v3, 0
	v_readlane_b32 s17, v11, 0
	v_readlane_b32 s18, v3, 1
	v_readlane_b32 s19, v11, 1
	v_readlane_b32 s20, v3, 2
	v_readlane_b32 s21, v11, 2
	v_pk_fma_f32 v[6:7], v[32:33], s[16:17], v[6:7] op_sel_hi:[0,1,1]
	v_readlane_b32 s22, v3, 3
	v_readlane_b32 s23, v11, 3
	s_waitcnt vmcnt(62)
	v_pk_fma_f32 v[6:7], v[34:35], s[18:19], v[6:7] op_sel_hi:[0,1,1]
	v_readlane_b32 s16, v3, 4
	v_readlane_b32 s17, v11, 4
	s_waitcnt vmcnt(61)
	v_pk_fma_f32 v[6:7], v[36:37], s[20:21], v[6:7] op_sel_hi:[0,1,1]
	v_readlane_b32 s18, v3, 5
	v_readlane_b32 s19, v11, 5
	s_waitcnt vmcnt(60)
	v_pk_fma_f32 v[6:7], v[38:39], s[22:23], v[6:7] op_sel_hi:[0,1,1]
	v_readlane_b32 s20, v3, 6
	v_readlane_b32 s21, v11, 6
	s_waitcnt vmcnt(59)
	v_pk_fma_f32 v[6:7], v[40:41], s[16:17], v[6:7] op_sel_hi:[0,1,1]
	v_readlane_b32 s22, v3, 7
	v_readlane_b32 s23, v11, 7
	s_waitcnt vmcnt(58)
	v_pk_fma_f32 v[6:7], v[42:43], s[18:19], v[6:7] op_sel_hi:[0,1,1]
	v_readlane_b32 s16, v3, 8
	v_readlane_b32 s17, v11, 8
	s_waitcnt vmcnt(57)
	v_pk_fma_f32 v[6:7], v[44:45], s[20:21], v[6:7] op_sel_hi:[0,1,1]
	v_readlane_b32 s18, v3, 9
	v_readlane_b32 s19, v11, 9
	s_waitcnt vmcnt(56)
	v_pk_fma_f32 v[6:7], v[46:47], s[22:23], v[6:7] op_sel_hi:[0,1,1]
	v_readlane_b32 s20, v3, 10
	v_readlane_b32 s21, v11, 10
	s_waitcnt vmcnt(55)
	v_pk_fma_f32 v[6:7], v[48:49], s[16:17], v[6:7] op_sel_hi:[0,1,1]
	v_readlane_b32 s22, v3, 11
	v_readlane_b32 s23, v11, 11
	s_waitcnt vmcnt(54)
	v_pk_fma_f32 v[6:7], v[50:51], s[18:19], v[6:7] op_sel_hi:[0,1,1]
	v_readlane_b32 s16, v3, 12
	v_readlane_b32 s17, v11, 12
	s_waitcnt vmcnt(53)
	v_pk_fma_f32 v[6:7], v[52:53], s[20:21], v[6:7] op_sel_hi:[0,1,1]
	v_readlane_b32 s18, v3, 13
	v_readlane_b32 s19, v11, 13
	s_waitcnt vmcnt(52)
	v_pk_fma_f32 v[6:7], v[54:55], s[22:23], v[6:7] op_sel_hi:[0,1,1]
	v_readlane_b32 s20, v3, 14
	v_readlane_b32 s21, v11, 14
	s_waitcnt vmcnt(51)
	v_pk_fma_f32 v[6:7], v[58:59], s[16:17], v[6:7] op_sel_hi:[0,1,1]
	v_readlane_b32 s22, v3, 15
	v_readlane_b32 s23, v11, 15
	s_waitcnt vmcnt(50)
	v_pk_fma_f32 v[6:7], v[60:61], s[18:19], v[6:7] op_sel_hi:[0,1,1]
	v_readlane_b32 s16, v3, 16
	v_readlane_b32 s17, v11, 16
	s_waitcnt vmcnt(49)
	v_pk_fma_f32 v[6:7], v[62:63], s[20:21], v[6:7] op_sel_hi:[0,1,1]
	v_readlane_b32 s18, v3, 17
	v_readlane_b32 s19, v11, 17
	s_waitcnt vmcnt(48)
	v_pk_fma_f32 v[6:7], v[64:65], s[22:23], v[6:7] op_sel_hi:[0,1,1]
	v_readlane_b32 s20, v3, 18
	v_readlane_b32 s21, v11, 18
	s_waitcnt vmcnt(47)
	v_pk_fma_f32 v[6:7], v[66:67], s[16:17], v[6:7] op_sel_hi:[0,1,1]
	v_readlane_b32 s22, v3, 19
	v_readlane_b32 s23, v11, 19
	s_waitcnt vmcnt(46)
	v_pk_fma_f32 v[6:7], v[68:69], s[18:19], v[6:7] op_sel_hi:[0,1,1]
	v_readlane_b32 s16, v3, 20
	v_readlane_b32 s17, v11, 20
	s_waitcnt vmcnt(45)
	v_pk_fma_f32 v[6:7], v[70:71], s[20:21], v[6:7] op_sel_hi:[0,1,1]
	v_readlane_b32 s18, v3, 21
	v_readlane_b32 s19, v11, 21
	s_waitcnt vmcnt(44)
	v_pk_fma_f32 v[6:7], v[72:73], s[22:23], v[6:7] op_sel_hi:[0,1,1]
	v_readlane_b32 s20, v3, 22
	v_readlane_b32 s21, v11, 22
	s_waitcnt vmcnt(43)
	v_pk_fma_f32 v[6:7], v[74:75], s[16:17], v[6:7] op_sel_hi:[0,1,1]
	v_readlane_b32 s22, v3, 23
	v_readlane_b32 s23, v11, 23
	s_waitcnt vmcnt(42)
	v_pk_fma_f32 v[6:7], v[76:77], s[18:19], v[6:7] op_sel_hi:[0,1,1]
	v_readlane_b32 s16, v3, 24
	v_readlane_b32 s17, v11, 24
	s_waitcnt vmcnt(41)
	v_pk_fma_f32 v[6:7], v[78:79], s[20:21], v[6:7] op_sel_hi:[0,1,1]
	v_readlane_b32 s18, v3, 25
	v_readlane_b32 s19, v11, 25
	s_waitcnt vmcnt(40)
	v_pk_fma_f32 v[6:7], v[80:81], s[22:23], v[6:7] op_sel_hi:[0,1,1]
	v_readlane_b32 s20, v3, 26
	v_readlane_b32 s21, v11, 26
	s_waitcnt vmcnt(39)
	v_pk_fma_f32 v[6:7], v[82:83], s[16:17], v[6:7] op_sel_hi:[0,1,1]
	v_readlane_b32 s22, v3, 27
	v_readlane_b32 s23, v11, 27
	s_waitcnt vmcnt(38)
	v_pk_fma_f32 v[6:7], v[84:85], s[18:19], v[6:7] op_sel_hi:[0,1,1]
	v_readlane_b32 s16, v3, 28
	v_readlane_b32 s17, v11, 28
	s_waitcnt vmcnt(37)
	v_pk_fma_f32 v[6:7], v[86:87], s[20:21], v[6:7] op_sel_hi:[0,1,1]
	v_readlane_b32 s18, v3, 29
	v_readlane_b32 s19, v11, 29
	s_waitcnt vmcnt(36)
	v_pk_fma_f32 v[6:7], v[88:89], s[22:23], v[6:7] op_sel_hi:[0,1,1]
	v_readlane_b32 s20, v3, 30
	v_readlane_b32 s21, v11, 30
	s_waitcnt vmcnt(35)
	v_pk_fma_f32 v[6:7], v[90:91], s[16:17], v[6:7] op_sel_hi:[0,1,1]
	v_readlane_b32 s22, v3, 31
	v_readlane_b32 s23, v11, 31
	s_waitcnt vmcnt(34)
	v_pk_fma_f32 v[6:7], v[92:93], s[18:19], v[6:7] op_sel_hi:[0,1,1]
	v_readlane_b32 s16, v3, 32
	v_readlane_b32 s17, v11, 32
	s_waitcnt vmcnt(33)
	v_pk_fma_f32 v[6:7], v[94:95], s[20:21], v[6:7] op_sel_hi:[0,1,1]
	v_readlane_b32 s18, v3, 33
	v_readlane_b32 s19, v11, 33
	s_waitcnt vmcnt(32)
	v_pk_fma_f32 v[6:7], v[96:97], s[22:23], v[6:7] op_sel_hi:[0,1,1]
	v_readlane_b32 s20, v3, 34
	v_readlane_b32 s21, v11, 34
	s_waitcnt vmcnt(31)
	v_pk_fma_f32 v[6:7], v[98:99], s[16:17], v[6:7] op_sel_hi:[0,1,1]
	v_readlane_b32 s22, v3, 35
	v_readlane_b32 s23, v11, 35
	s_waitcnt vmcnt(30)
	v_pk_fma_f32 v[6:7], v[100:101], s[18:19], v[6:7] op_sel_hi:[0,1,1]
	v_readlane_b32 s16, v3, 36
	v_readlane_b32 s17, v11, 36
	s_waitcnt vmcnt(29)
	v_pk_fma_f32 v[6:7], v[102:103], s[20:21], v[6:7] op_sel_hi:[0,1,1]
	v_readlane_b32 s18, v3, 37
	v_readlane_b32 s19, v11, 37
	s_waitcnt vmcnt(28)
	v_pk_fma_f32 v[6:7], v[104:105], s[22:23], v[6:7] op_sel_hi:[0,1,1]
	v_readlane_b32 s20, v3, 38
	v_readlane_b32 s21, v11, 38
	s_waitcnt vmcnt(27)
	v_pk_fma_f32 v[6:7], v[106:107], s[16:17], v[6:7] op_sel_hi:[0,1,1]
	v_readlane_b32 s22, v3, 39
	v_readlane_b32 s23, v11, 39
	s_waitcnt vmcnt(26)
	v_pk_fma_f32 v[6:7], v[108:109], s[18:19], v[6:7] op_sel_hi:[0,1,1]
	v_readlane_b32 s16, v3, 40
	v_readlane_b32 s17, v11, 40
	s_waitcnt vmcnt(25)
	v_pk_fma_f32 v[6:7], v[110:111], s[20:21], v[6:7] op_sel_hi:[0,1,1]
	v_readlane_b32 s18, v3, 41
	v_readlane_b32 s19, v11, 41
	s_waitcnt vmcnt(24)
	v_pk_fma_f32 v[6:7], v[112:113], s[22:23], v[6:7] op_sel_hi:[0,1,1]
	v_readlane_b32 s20, v3, 42
	v_readlane_b32 s21, v11, 42
	s_waitcnt vmcnt(23)
	v_pk_fma_f32 v[6:7], v[114:115], s[16:17], v[6:7] op_sel_hi:[0,1,1]
	v_readlane_b32 s22, v3, 43
	v_readlane_b32 s23, v11, 43
	s_waitcnt vmcnt(22)
	v_pk_fma_f32 v[6:7], v[116:117], s[18:19], v[6:7] op_sel_hi:[0,1,1]
	v_readlane_b32 s16, v3, 44
	v_readlane_b32 s17, v11, 44
	s_waitcnt vmcnt(21)
	v_pk_fma_f32 v[6:7], v[118:119], s[20:21], v[6:7] op_sel_hi:[0,1,1]
	v_readlane_b32 s18, v3, 45
	v_readlane_b32 s19, v11, 45
	s_waitcnt vmcnt(20)
	v_pk_fma_f32 v[6:7], v[120:121], s[22:23], v[6:7] op_sel_hi:[0,1,1]
	v_readlane_b32 s20, v3, 46
	v_readlane_b32 s21, v11, 46
	s_waitcnt vmcnt(19)
	v_pk_fma_f32 v[6:7], v[122:123], s[16:17], v[6:7] op_sel_hi:[0,1,1]
	v_readlane_b32 s22, v3, 47
	v_readlane_b32 s23, v11, 47
	s_waitcnt vmcnt(18)
	v_pk_fma_f32 v[6:7], v[124:125], s[18:19], v[6:7] op_sel_hi:[0,1,1]
	v_readlane_b32 s16, v3, 48
	v_readlane_b32 s17, v11, 48
	s_waitcnt vmcnt(17)
	v_pk_fma_f32 v[6:7], v[126:127], s[20:21], v[6:7] op_sel_hi:[0,1,1]
	v_readlane_b32 s18, v3, 49
	v_readlane_b32 s19, v11, 49
	s_waitcnt vmcnt(16)
	v_pk_fma_f32 v[6:7], v[128:129], s[22:23], v[6:7] op_sel_hi:[0,1,1]
	v_readlane_b32 s20, v3, 50
	v_readlane_b32 s21, v11, 50
	s_waitcnt vmcnt(15)
	v_pk_fma_f32 v[6:7], v[130:131], s[16:17], v[6:7] op_sel_hi:[0,1,1]
	v_readlane_b32 s22, v3, 51
	v_readlane_b32 s23, v11, 51
	s_waitcnt vmcnt(14)
	v_pk_fma_f32 v[6:7], v[132:133], s[18:19], v[6:7] op_sel_hi:[0,1,1]
	v_readlane_b32 s16, v3, 52
	v_readlane_b32 s17, v11, 52
	s_waitcnt vmcnt(13)
	v_pk_fma_f32 v[6:7], v[134:135], s[20:21], v[6:7] op_sel_hi:[0,1,1]
	v_readlane_b32 s18, v3, 53
	v_readlane_b32 s19, v11, 53
	s_waitcnt vmcnt(12)
	v_pk_fma_f32 v[6:7], v[136:137], s[22:23], v[6:7] op_sel_hi:[0,1,1]
	v_readlane_b32 s20, v3, 54
	v_readlane_b32 s21, v11, 54
	s_waitcnt vmcnt(11)
	v_pk_fma_f32 v[6:7], v[138:139], s[16:17], v[6:7] op_sel_hi:[0,1,1]
	v_readlane_b32 s22, v3, 55
	v_readlane_b32 s23, v11, 55
	s_waitcnt vmcnt(10)
	v_pk_fma_f32 v[6:7], v[140:141], s[18:19], v[6:7] op_sel_hi:[0,1,1]
	v_readlane_b32 s16, v3, 56
	v_readlane_b32 s17, v11, 56
	s_waitcnt vmcnt(9)
	v_pk_fma_f32 v[6:7], v[142:143], s[20:21], v[6:7] op_sel_hi:[0,1,1]
	v_readlane_b32 s18, v3, 57
	v_readlane_b32 s19, v11, 57
	s_waitcnt vmcnt(8)
	v_pk_fma_f32 v[6:7], v[144:145], s[22:23], v[6:7] op_sel_hi:[0,1,1]
	v_readlane_b32 s20, v3, 58
	v_readlane_b32 s21, v11, 58
	s_waitcnt vmcnt(7)
	v_pk_fma_f32 v[6:7], v[146:147], s[16:17], v[6:7] op_sel_hi:[0,1,1]
	v_readlane_b32 s22, v3, 59
	v_readlane_b32 s23, v11, 59
	s_waitcnt vmcnt(6)
	v_pk_fma_f32 v[6:7], v[148:149], s[18:19], v[6:7] op_sel_hi:[0,1,1]
	v_readlane_b32 s16, v3, 60
	v_readlane_b32 s17, v11, 60
	s_waitcnt vmcnt(5)
	v_pk_fma_f32 v[6:7], v[150:151], s[20:21], v[6:7] op_sel_hi:[0,1,1]
	v_readlane_b32 s18, v3, 61
	v_readlane_b32 s19, v11, 61
	s_waitcnt vmcnt(4)
	v_pk_fma_f32 v[6:7], v[152:153], s[22:23], v[6:7] op_sel_hi:[0,1,1]
	v_readlane_b32 s20, v3, 62
	v_readlane_b32 s21, v11, 62
	s_waitcnt vmcnt(3)
	v_pk_fma_f32 v[6:7], v[154:155], s[16:17], v[6:7] op_sel_hi:[0,1,1]
	v_readlane_b32 s22, v3, 63
	v_readlane_b32 s23, v11, 63
	s_waitcnt vmcnt(2)
	v_pk_fma_f32 v[6:7], v[156:157], s[18:19], v[6:7] op_sel_hi:[0,1,1]
	s_waitcnt vmcnt(1)
	v_pk_fma_f32 v[6:7], v[158:159], s[20:21], v[6:7] op_sel_hi:[0,1,1]
	s_waitcnt vmcnt(0)
	v_pk_fma_f32 v[6:7], v[164:165], s[22:23], v[6:7] op_sel_hi:[0,1,1]
	s_mov_b64 s[0:1], 0
	s_cbranch_vccz .LBB0_749
	s_and_saveexec_b64 s[0:1], s[6:7]
	s_cbranch_execz .LBB0_747
	v_ashrrev_i32_e32 v3, 31, v2
	v_readlane_b32 s2, v251, 12
	v_lshlrev_b64 v[2:3], 2, v[2:3]
	v_readlane_b32 s3, v251, 13
	s_nop 1
	v_lshl_add_u64 v[4:5], s[2:3], 0, v[2:3]
	v_readlane_b32 s2, v251, 6
	v_readlane_b32 s3, v251, 7
	s_nop 1
	v_lshl_add_u64 v[2:3], s[2:3], 0, v[2:3]
	global_atomic_add_f32 v[2:3], v6, off
	global_atomic_add_f32 v[4:5], v7, off
	s_branch .LBB0_747

.LBB0_756:
	v_cndmask_b32_e64 v0, 0, 1, s[0:1]
	v_cmp_ne_u32_e32 vcc, 1, v0
	v_or_b32_e32 v0, s11, v10
	v_lshlrev_b64 v[8:9], 2, v[0:1]
	s_lshl_b32 s90, s11, 10
	v_lshl_add_u64 v[12:13], s[2:3], 0, v[8:9]
	v_lshl_add_u64 v[8:9], s[4:5], 0, v[8:9]
	global_load_dword v3, v[12:13], off
	global_load_dword v11, v[8:9], off
	v_lshl_add_u64 v[8:9], s[90:91], 2, v[4:5]
	s_mov_b32 s14, 0x1000
	s_mov_b32 s15, 0
	global_load_dword v32, v[8:9], off
	v_lshl_add_u64 v[8:9], v[8:9], 0, s[14:15]
	global_load_dword v34, v[8:9], off
	v_lshl_add_u64 v[8:9], v[8:9], 0, s[14:15]
	global_load_dword v36, v[8:9], off
	v_lshl_add_u64 v[8:9], v[8:9], 0, s[14:15]
	global_load_dword v38, v[8:9], off
	v_lshl_add_u64 v[8:9], v[8:9], 0, s[14:15]
	global_load_dword v40, v[8:9], off
	v_lshl_add_u64 v[8:9], v[8:9], 0, s[14:15]
	global_load_dword v42, v[8:9], off
	v_lshl_add_u64 v[8:9], v[8:9], 0, s[14:15]
	global_load_dword v44, v[8:9], off
	v_lshl_add_u64 v[8:9], v[8:9], 0, s[14:15]
	global_load_dword v46, v[8:9], off
	v_lshl_add_u64 v[8:9], v[8:9], 0, s[14:15]
	global_load_dword v48, v[8:9], off
	v_lshl_add_u64 v[8:9], v[8:9], 0, s[14:15]
	global_load_dword v50, v[8:9], off
	v_lshl_add_u64 v[8:9], v[8:9], 0, s[14:15]
	global_load_dword v52, v[8:9], off
	v_lshl_add_u64 v[8:9], v[8:9], 0, s[14:15]
	global_load_dword v54, v[8:9], off
	v_lshl_add_u64 v[8:9], v[8:9], 0, s[14:15]
	global_load_dword v58, v[8:9], off
	v_lshl_add_u64 v[8:9], v[8:9], 0, s[14:15]
	global_load_dword v60, v[8:9], off
	v_lshl_add_u64 v[8:9], v[8:9], 0, s[14:15]
	global_load_dword v62, v[8:9], off
	v_lshl_add_u64 v[8:9], v[8:9], 0, s[14:15]
	global_load_dword v64, v[8:9], off
	v_lshl_add_u64 v[8:9], v[8:9], 0, s[14:15]
	global_load_dword v66, v[8:9], off
	v_lshl_add_u64 v[8:9], v[8:9], 0, s[14:15]
	global_load_dword v68, v[8:9], off
	v_lshl_add_u64 v[8:9], v[8:9], 0, s[14:15]
	global_load_dword v70, v[8:9], off
	v_lshl_add_u64 v[8:9], v[8:9], 0, s[14:15]
	global_load_dword v72, v[8:9], off
	v_lshl_add_u64 v[8:9], v[8:9], 0, s[14:15]
	global_load_dword v74, v[8:9], off
	v_lshl_add_u64 v[8:9], v[8:9], 0, s[14:15]
	global_load_dword v76, v[8:9], off
	v_lshl_add_u64 v[8:9], v[8:9], 0, s[14:15]
	global_load_dword v78, v[8:9], off
	v_lshl_add_u64 v[8:9], v[8:9], 0, s[14:15]
	global_load_dword v80, v[8:9], off
	v_lshl_add_u64 v[8:9], v[8:9], 0, s[14:15]
	global_load_dword v82, v[8:9], off
	v_lshl_add_u64 v[8:9], v[8:9], 0, s[14:15]
	global_load_dword v84, v[8:9], off
	v_lshl_add_u64 v[8:9], v[8:9], 0, s[14:15]
	global_load_dword v86, v[8:9], off
	v_lshl_add_u64 v[8:9], v[8:9], 0, s[14:15]
	global_load_dword v88, v[8:9], off
	v_lshl_add_u64 v[8:9], v[8:9], 0, s[14:15]
	global_load_dword v90, v[8:9], off
	v_lshl_add_u64 v[8:9], v[8:9], 0, s[14:15]
	global_load_dword v92, v[8:9], off
	v_lshl_add_u64 v[8:9], v[8:9], 0, s[14:15]
	global_load_dword v94, v[8:9], off
	v_lshl_add_u64 v[8:9], v[8:9], 0, s[14:15]
	global_load_dword v96, v[8:9], off
	v_lshl_add_u64 v[8:9], v[8:9], 0, s[14:15]
	global_load_dword v98, v[8:9], off
	v_lshl_add_u64 v[8:9], v[8:9], 0, s[14:15]
	global_load_dword v100, v[8:9], off
	v_lshl_add_u64 v[8:9], v[8:9], 0, s[14:15]
	global_load_dword v102, v[8:9], off
	v_lshl_add_u64 v[8:9], v[8:9], 0, s[14:15]
	global_load_dword v104, v[8:9], off
	v_lshl_add_u64 v[8:9], v[8:9], 0, s[14:15]
	global_load_dword v106, v[8:9], off
	v_lshl_add_u64 v[8:9], v[8:9], 0, s[14:15]
	global_load_dword v108, v[8:9], off
	v_lshl_add_u64 v[8:9], v[8:9], 0, s[14:15]
	global_load_dword v110, v[8:9], off
	v_lshl_add_u64 v[8:9], v[8:9], 0, s[14:15]
	global_load_dword v112, v[8:9], off
	v_lshl_add_u64 v[8:9], v[8:9], 0, s[14:15]
	global_load_dword v114, v[8:9], off
	v_lshl_add_u64 v[8:9], v[8:9], 0, s[14:15]
	global_load_dword v116, v[8:9], off
	v_lshl_add_u64 v[8:9], v[8:9], 0, s[14:15]
	global_load_dword v118, v[8:9], off
	v_lshl_add_u64 v[8:9], v[8:9], 0, s[14:15]
	global_load_dword v120, v[8:9], off
	v_lshl_add_u64 v[8:9], v[8:9], 0, s[14:15]
	global_load_dword v122, v[8:9], off
	v_lshl_add_u64 v[8:9], v[8:9], 0, s[14:15]
	global_load_dword v124, v[8:9], off
	v_lshl_add_u64 v[8:9], v[8:9], 0, s[14:15]
	global_load_dword v126, v[8:9], off
	v_lshl_add_u64 v[8:9], v[8:9], 0, s[14:15]
	global_load_dword v128, v[8:9], off
	v_lshl_add_u64 v[8:9], v[8:9], 0, s[14:15]
	global_load_dword v130, v[8:9], off
	v_lshl_add_u64 v[8:9], v[8:9], 0, s[14:15]
	global_load_dword v132, v[8:9], off
	v_lshl_add_u64 v[8:9], v[8:9], 0, s[14:15]
	global_load_dword v134, v[8:9], off
	v_lshl_add_u64 v[8:9], v[8:9], 0, s[14:15]
	global_load_dword v136, v[8:9], off
	v_lshl_add_u64 v[8:9], v[8:9], 0, s[14:15]
	global_load_dword v138, v[8:9], off
	v_lshl_add_u64 v[8:9], v[8:9], 0, s[14:15]
	global_load_dword v140, v[8:9], off
	v_lshl_add_u64 v[8:9], v[8:9], 0, s[14:15]
	global_load_dword v142, v[8:9], off
	v_lshl_add_u64 v[8:9], v[8:9], 0, s[14:15]
	global_load_dword v144, v[8:9], off
	v_lshl_add_u64 v[8:9], v[8:9], 0, s[14:15]
	global_load_dword v146, v[8:9], off
	v_lshl_add_u64 v[8:9], v[8:9], 0, s[14:15]
	global_load_dword v148, v[8:9], off
	v_lshl_add_u64 v[8:9], v[8:9], 0, s[14:15]
	global_load_dword v150, v[8:9], off
	v_lshl_add_u64 v[8:9], v[8:9], 0, s[14:15]
	global_load_dword v152, v[8:9], off
	v_lshl_add_u64 v[8:9], v[8:9], 0, s[14:15]
	global_load_dword v154, v[8:9], off
	v_lshl_add_u64 v[8:9], v[8:9], 0, s[14:15]
	global_load_dword v156, v[8:9], off
	v_lshl_add_u64 v[8:9], v[8:9], 0, s[14:15]
	global_load_dword v158, v[8:9], off
	v_lshl_add_u64 v[8:9], v[8:9], 0, s[14:15]
	global_load_dword v164, v[8:9], off
	s_mov_b32 s11, 64
	s_and_b64 vcc, exec, vcc
	s_waitcnt vmcnt(63)
	v_readlane_b32 s16, v3, 0
	v_readlane_b32 s17, v11, 0
	v_readlane_b32 s18, v3, 1
	v_readlane_b32 s19, v11, 1
	v_readlane_b32 s20, v3, 2
	v_readlane_b32 s21, v11, 2
	v_pk_fma_f32 v[6:7], v[32:33], s[16:17], v[6:7] op_sel_hi:[0,1,1]
	v_readlane_b32 s22, v3, 3
	v_readlane_b32 s23, v11, 3
	s_waitcnt vmcnt(62)
	v_pk_fma_f32 v[6:7], v[34:35], s[18:19], v[6:7] op_sel_hi:[0,1,1]
	v_readlane_b32 s16, v3, 4
	v_readlane_b32 s17, v11, 4
	s_waitcnt vmcnt(61)
	v_pk_fma_f32 v[6:7], v[36:37], s[20:21], v[6:7] op_sel_hi:[0,1,1]
	v_readlane_b32 s18, v3, 5
	v_readlane_b32 s19, v11, 5
	s_waitcnt vmcnt(60)
	v_pk_fma_f32 v[6:7], v[38:39], s[22:23], v[6:7] op_sel_hi:[0,1,1]
	v_readlane_b32 s20, v3, 6
	v_readlane_b32 s21, v11, 6
	s_waitcnt vmcnt(59)
	v_pk_fma_f32 v[6:7], v[40:41], s[16:17], v[6:7] op_sel_hi:[0,1,1]
	v_readlane_b32 s22, v3, 7
	v_readlane_b32 s23, v11, 7
	s_waitcnt vmcnt(58)
	v_pk_fma_f32 v[6:7], v[42:43], s[18:19], v[6:7] op_sel_hi:[0,1,1]
	v_readlane_b32 s16, v3, 8
	v_readlane_b32 s17, v11, 8
	s_waitcnt vmcnt(57)
	v_pk_fma_f32 v[6:7], v[44:45], s[20:21], v[6:7] op_sel_hi:[0,1,1]
	v_readlane_b32 s18, v3, 9
	v_readlane_b32 s19, v11, 9
	s_waitcnt vmcnt(56)
	v_pk_fma_f32 v[6:7], v[46:47], s[22:23], v[6:7] op_sel_hi:[0,1,1]
	v_readlane_b32 s20, v3, 10
	v_readlane_b32 s21, v11, 10
	s_waitcnt vmcnt(55)
	v_pk_fma_f32 v[6:7], v[48:49], s[16:17], v[6:7] op_sel_hi:[0,1,1]
	v_readlane_b32 s22, v3, 11
	v_readlane_b32 s23, v11, 11
	s_waitcnt vmcnt(54)
	v_pk_fma_f32 v[6:7], v[50:51], s[18:19], v[6:7] op_sel_hi:[0,1,1]
	v_readlane_b32 s16, v3, 12
	v_readlane_b32 s17, v11, 12
	s_waitcnt vmcnt(53)
	v_pk_fma_f32 v[6:7], v[52:53], s[20:21], v[6:7] op_sel_hi:[0,1,1]
	v_readlane_b32 s18, v3, 13
	v_readlane_b32 s19, v11, 13
	s_waitcnt vmcnt(52)
	v_pk_fma_f32 v[6:7], v[54:55], s[22:23], v[6:7] op_sel_hi:[0,1,1]
	v_readlane_b32 s20, v3, 14
	v_readlane_b32 s21, v11, 14
	s_waitcnt vmcnt(51)
	v_pk_fma_f32 v[6:7], v[58:59], s[16:17], v[6:7] op_sel_hi:[0,1,1]
	v_readlane_b32 s22, v3, 15
	v_readlane_b32 s23, v11, 15
	s_waitcnt vmcnt(50)
	v_pk_fma_f32 v[6:7], v[60:61], s[18:19], v[6:7] op_sel_hi:[0,1,1]
	v_readlane_b32 s16, v3, 16
	v_readlane_b32 s17, v11, 16
	s_waitcnt vmcnt(49)
	v_pk_fma_f32 v[6:7], v[62:63], s[20:21], v[6:7] op_sel_hi:[0,1,1]
	v_readlane_b32 s18, v3, 17
	v_readlane_b32 s19, v11, 17
	s_waitcnt vmcnt(48)
	v_pk_fma_f32 v[6:7], v[64:65], s[22:23], v[6:7] op_sel_hi:[0,1,1]
	v_readlane_b32 s20, v3, 18
	v_readlane_b32 s21, v11, 18
	s_waitcnt vmcnt(47)
	v_pk_fma_f32 v[6:7], v[66:67], s[16:17], v[6:7] op_sel_hi:[0,1,1]
	v_readlane_b32 s22, v3, 19
	v_readlane_b32 s23, v11, 19
	s_waitcnt vmcnt(46)
	v_pk_fma_f32 v[6:7], v[68:69], s[18:19], v[6:7] op_sel_hi:[0,1,1]
	v_readlane_b32 s16, v3, 20
	v_readlane_b32 s17, v11, 20
	s_waitcnt vmcnt(45)
	v_pk_fma_f32 v[6:7], v[70:71], s[20:21], v[6:7] op_sel_hi:[0,1,1]
	v_readlane_b32 s18, v3, 21
	v_readlane_b32 s19, v11, 21
	s_waitcnt vmcnt(44)
	v_pk_fma_f32 v[6:7], v[72:73], s[22:23], v[6:7] op_sel_hi:[0,1,1]
	v_readlane_b32 s20, v3, 22
	v_readlane_b32 s21, v11, 22
	s_waitcnt vmcnt(43)
	v_pk_fma_f32 v[6:7], v[74:75], s[16:17], v[6:7] op_sel_hi:[0,1,1]
	v_readlane_b32 s22, v3, 23
	v_readlane_b32 s23, v11, 23
	s_waitcnt vmcnt(42)
	v_pk_fma_f32 v[6:7], v[76:77], s[18:19], v[6:7] op_sel_hi:[0,1,1]
	v_readlane_b32 s16, v3, 24
	v_readlane_b32 s17, v11, 24
	s_waitcnt vmcnt(41)
	v_pk_fma_f32 v[6:7], v[78:79], s[20:21], v[6:7] op_sel_hi:[0,1,1]
	v_readlane_b32 s18, v3, 25
	v_readlane_b32 s19, v11, 25
	s_waitcnt vmcnt(40)
	v_pk_fma_f32 v[6:7], v[80:81], s[22:23], v[6:7] op_sel_hi:[0,1,1]
	v_readlane_b32 s20, v3, 26
	v_readlane_b32 s21, v11, 26
	s_waitcnt vmcnt(39)
	v_pk_fma_f32 v[6:7], v[82:83], s[16:17], v[6:7] op_sel_hi:[0,1,1]
	v_readlane_b32 s22, v3, 27
	v_readlane_b32 s23, v11, 27
	s_waitcnt vmcnt(38)
	v_pk_fma_f32 v[6:7], v[84:85], s[18:19], v[6:7] op_sel_hi:[0,1,1]
	v_readlane_b32 s16, v3, 28
	v_readlane_b32 s17, v11, 28
	s_waitcnt vmcnt(37)
	v_pk_fma_f32 v[6:7], v[86:87], s[20:21], v[6:7] op_sel_hi:[0,1,1]
	v_readlane_b32 s18, v3, 29
	v_readlane_b32 s19, v11, 29
	s_waitcnt vmcnt(36)
	v_pk_fma_f32 v[6:7], v[88:89], s[22:23], v[6:7] op_sel_hi:[0,1,1]
	v_readlane_b32 s20, v3, 30
	v_readlane_b32 s21, v11, 30
	s_waitcnt vmcnt(35)
	v_pk_fma_f32 v[6:7], v[90:91], s[16:17], v[6:7] op_sel_hi:[0,1,1]
	v_readlane_b32 s22, v3, 31
	v_readlane_b32 s23, v11, 31
	s_waitcnt vmcnt(34)
	v_pk_fma_f32 v[6:7], v[92:93], s[18:19], v[6:7] op_sel_hi:[0,1,1]
	v_readlane_b32 s16, v3, 32
	v_readlane_b32 s17, v11, 32
	s_waitcnt vmcnt(33)
	v_pk_fma_f32 v[6:7], v[94:95], s[20:21], v[6:7] op_sel_hi:[0,1,1]
	v_readlane_b32 s18, v3, 33
	v_readlane_b32 s19, v11, 33
	s_waitcnt vmcnt(32)
	v_pk_fma_f32 v[6:7], v[96:97], s[22:23], v[6:7] op_sel_hi:[0,1,1]
	v_readlane_b32 s20, v3, 34
	v_readlane_b32 s21, v11, 34
	s_waitcnt vmcnt(31)
	v_pk_fma_f32 v[6:7], v[98:99], s[16:17], v[6:7] op_sel_hi:[0,1,1]
	v_readlane_b32 s22, v3, 35
	v_readlane_b32 s23, v11, 35
	s_waitcnt vmcnt(30)
	v_pk_fma_f32 v[6:7], v[100:101], s[18:19], v[6:7] op_sel_hi:[0,1,1]
	v_readlane_b32 s16, v3, 36
	v_readlane_b32 s17, v11, 36
	s_waitcnt vmcnt(29)
	v_pk_fma_f32 v[6:7], v[102:103], s[20:21], v[6:7] op_sel_hi:[0,1,1]
	v_readlane_b32 s18, v3, 37
	v_readlane_b32 s19, v11, 37
	s_waitcnt vmcnt(28)
	v_pk_fma_f32 v[6:7], v[104:105], s[22:23], v[6:7] op_sel_hi:[0,1,1]
	v_readlane_b32 s20, v3, 38
	v_readlane_b32 s21, v11, 38
	s_waitcnt vmcnt(27)
	v_pk_fma_f32 v[6:7], v[106:107], s[16:17], v[6:7] op_sel_hi:[0,1,1]
	v_readlane_b32 s22, v3, 39
	v_readlane_b32 s23, v11, 39
	s_waitcnt vmcnt(26)
	v_pk_fma_f32 v[6:7], v[108:109], s[18:19], v[6:7] op_sel_hi:[0,1,1]
	v_readlane_b32 s16, v3, 40
	v_readlane_b32 s17, v11, 40
	s_waitcnt vmcnt(25)
	v_pk_fma_f32 v[6:7], v[110:111], s[20:21], v[6:7] op_sel_hi:[0,1,1]
	v_readlane_b32 s18, v3, 41
	v_readlane_b32 s19, v11, 41
	s_waitcnt vmcnt(24)
	v_pk_fma_f32 v[6:7], v[112:113], s[22:23], v[6:7] op_sel_hi:[0,1,1]
	v_readlane_b32 s20, v3, 42
	v_readlane_b32 s21, v11, 42
	s_waitcnt vmcnt(23)
	v_pk_fma_f32 v[6:7], v[114:115], s[16:17], v[6:7] op_sel_hi:[0,1,1]
	v_readlane_b32 s22, v3, 43
	v_readlane_b32 s23, v11, 43
	s_waitcnt vmcnt(22)
	v_pk_fma_f32 v[6:7], v[116:117], s[18:19], v[6:7] op_sel_hi:[0,1,1]
	v_readlane_b32 s16, v3, 44
	v_readlane_b32 s17, v11, 44
	s_waitcnt vmcnt(21)
	v_pk_fma_f32 v[6:7], v[118:119], s[20:21], v[6:7] op_sel_hi:[0,1,1]
	v_readlane_b32 s18, v3, 45
	v_readlane_b32 s19, v11, 45
	s_waitcnt vmcnt(20)
	v_pk_fma_f32 v[6:7], v[120:121], s[22:23], v[6:7] op_sel_hi:[0,1,1]
	v_readlane_b32 s20, v3, 46
	v_readlane_b32 s21, v11, 46
	s_waitcnt vmcnt(19)
	v_pk_fma_f32 v[6:7], v[122:123], s[16:17], v[6:7] op_sel_hi:[0,1,1]
	v_readlane_b32 s22, v3, 47
	v_readlane_b32 s23, v11, 47
	s_waitcnt vmcnt(18)
	v_pk_fma_f32 v[6:7], v[124:125], s[18:19], v[6:7] op_sel_hi:[0,1,1]
	v_readlane_b32 s16, v3, 48
	v_readlane_b32 s17, v11, 48
	s_waitcnt vmcnt(17)
	v_pk_fma_f32 v[6:7], v[126:127], s[20:21], v[6:7] op_sel_hi:[0,1,1]
	v_readlane_b32 s18, v3, 49
	v_readlane_b32 s19, v11, 49
	s_waitcnt vmcnt(16)
	v_pk_fma_f32 v[6:7], v[128:129], s[22:23], v[6:7] op_sel_hi:[0,1,1]
	v_readlane_b32 s20, v3, 50
	v_readlane_b32 s21, v11, 50
	s_waitcnt vmcnt(15)
	v_pk_fma_f32 v[6:7], v[130:131], s[16:17], v[6:7] op_sel_hi:[0,1,1]
	v_readlane_b32 s22, v3, 51
	v_readlane_b32 s23, v11, 51
	s_waitcnt vmcnt(14)
	v_pk_fma_f32 v[6:7], v[132:133], s[18:19], v[6:7] op_sel_hi:[0,1,1]
	v_readlane_b32 s16, v3, 52
	v_readlane_b32 s17, v11, 52
	s_waitcnt vmcnt(13)
	v_pk_fma_f32 v[6:7], v[134:135], s[20:21], v[6:7] op_sel_hi:[0,1,1]
	v_readlane_b32 s18, v3, 53
	v_readlane_b32 s19, v11, 53
	s_waitcnt vmcnt(12)
	v_pk_fma_f32 v[6:7], v[136:137], s[22:23], v[6:7] op_sel_hi:[0,1,1]
	v_readlane_b32 s20, v3, 54
	v_readlane_b32 s21, v11, 54
	s_waitcnt vmcnt(11)
	v_pk_fma_f32 v[6:7], v[138:139], s[16:17], v[6:7] op_sel_hi:[0,1,1]
	v_readlane_b32 s22, v3, 55
	v_readlane_b32 s23, v11, 55
	s_waitcnt vmcnt(10)
	v_pk_fma_f32 v[6:7], v[140:141], s[18:19], v[6:7] op_sel_hi:[0,1,1]
	v_readlane_b32 s16, v3, 56
	v_readlane_b32 s17, v11, 56
	s_waitcnt vmcnt(9)
	v_pk_fma_f32 v[6:7], v[142:143], s[20:21], v[6:7] op_sel_hi:[0,1,1]
	v_readlane_b32 s18, v3, 57
	v_readlane_b32 s19, v11, 57
	s_waitcnt vmcnt(8)
	v_pk_fma_f32 v[6:7], v[144:145], s[22:23], v[6:7] op_sel_hi:[0,1,1]
	v_readlane_b32 s20, v3, 58
	v_readlane_b32 s21, v11, 58
	s_waitcnt vmcnt(7)
	v_pk_fma_f32 v[6:7], v[146:147], s[16:17], v[6:7] op_sel_hi:[0,1,1]
	v_readlane_b32 s22, v3, 59
	v_readlane_b32 s23, v11, 59
	s_waitcnt vmcnt(6)
	v_pk_fma_f32 v[6:7], v[148:149], s[18:19], v[6:7] op_sel_hi:[0,1,1]
	v_readlane_b32 s16, v3, 60
	v_readlane_b32 s17, v11, 60
	s_waitcnt vmcnt(5)
	v_pk_fma_f32 v[6:7], v[150:151], s[20:21], v[6:7] op_sel_hi:[0,1,1]
	v_readlane_b32 s18, v3, 61
	v_readlane_b32 s19, v11, 61
	s_waitcnt vmcnt(4)
	v_pk_fma_f32 v[6:7], v[152:153], s[22:23], v[6:7] op_sel_hi:[0,1,1]
	v_readlane_b32 s20, v3, 62
	v_readlane_b32 s21, v11, 62
	s_waitcnt vmcnt(3)
	v_pk_fma_f32 v[6:7], v[154:155], s[16:17], v[6:7] op_sel_hi:[0,1,1]
	v_readlane_b32 s22, v3, 63
	v_readlane_b32 s23, v11, 63
	s_waitcnt vmcnt(2)
	v_pk_fma_f32 v[6:7], v[156:157], s[18:19], v[6:7] op_sel_hi:[0,1,1]
	s_waitcnt vmcnt(1)
	v_pk_fma_f32 v[6:7], v[158:159], s[20:21], v[6:7] op_sel_hi:[0,1,1]
	s_waitcnt vmcnt(0)
	v_pk_fma_f32 v[6:7], v[164:165], s[22:23], v[6:7] op_sel_hi:[0,1,1]
	s_mov_b64 s[0:1], 0
	s_cbranch_vccz .LBB0_756
	s_and_saveexec_b64 s[0:1], s[6:7]
	s_cbranch_execz .LBB0_754
	v_ashrrev_i32_e32 v3, 31, v2
	v_readlane_b32 s2, v251, 20
	v_lshlrev_b64 v[2:3], 2, v[2:3]
	v_readlane_b32 s3, v251, 21
	s_nop 1
	v_lshl_add_u64 v[4:5], s[2:3], 0, v[2:3]
	v_readlane_b32 s2, v251, 14
	v_readlane_b32 s3, v251, 15
	s_nop 1
	v_lshl_add_u64 v[2:3], s[2:3], 0, v[2:3]
	global_atomic_add_f32 v[2:3], v6, off
	global_atomic_add_f32 v[4:5], v7, off
	s_branch .LBB0_754

.LBB0_825:
	v_cndmask_b32_e64 v0, 0, 1, s[0:1]
	v_cmp_ne_u32_e32 vcc, 1, v0
	v_or_b32_e32 v0, s3, v10
	v_lshlrev_b64 v[8:9], 2, v[0:1]
	v_lshl_add_u64 v[12:13], s[8:9], 0, v[8:9]
	v_lshl_add_u64 v[8:9], s[10:11], 0, v[8:9]
	s_mul_i32 s90, s3, 0x3830
	global_load_dword v3, v[12:13], off
	global_load_dword v11, v[8:9], off
	v_lshl_add_u64 v[8:9], s[90:91], 2, v[4:5]
	s_mov_b32 s14, 0xe0c0
	s_mov_b32 s15, 0
	global_load_dword v32, v[8:9], off
	v_lshl_add_u64 v[8:9], v[8:9], 0, s[14:15]
	global_load_dword v34, v[8:9], off
	v_lshl_add_u64 v[8:9], v[8:9], 0, s[14:15]
	global_load_dword v36, v[8:9], off
	v_lshl_add_u64 v[8:9], v[8:9], 0, s[14:15]
	global_load_dword v38, v[8:9], off
	v_lshl_add_u64 v[8:9], v[8:9], 0, s[14:15]
	global_load_dword v40, v[8:9], off
	v_lshl_add_u64 v[8:9], v[8:9], 0, s[14:15]
	global_load_dword v42, v[8:9], off
	v_lshl_add_u64 v[8:9], v[8:9], 0, s[14:15]
	global_load_dword v44, v[8:9], off
	v_lshl_add_u64 v[8:9], v[8:9], 0, s[14:15]
	global_load_dword v46, v[8:9], off
	v_lshl_add_u64 v[8:9], v[8:9], 0, s[14:15]
	global_load_dword v48, v[8:9], off
	v_lshl_add_u64 v[8:9], v[8:9], 0, s[14:15]
	global_load_dword v50, v[8:9], off
	v_lshl_add_u64 v[8:9], v[8:9], 0, s[14:15]
	global_load_dword v52, v[8:9], off
	v_lshl_add_u64 v[8:9], v[8:9], 0, s[14:15]
	global_load_dword v54, v[8:9], off
	v_lshl_add_u64 v[8:9], v[8:9], 0, s[14:15]
	global_load_dword v58, v[8:9], off
	v_lshl_add_u64 v[8:9], v[8:9], 0, s[14:15]
	global_load_dword v60, v[8:9], off
	v_lshl_add_u64 v[8:9], v[8:9], 0, s[14:15]
	global_load_dword v62, v[8:9], off
	v_lshl_add_u64 v[8:9], v[8:9], 0, s[14:15]
	global_load_dword v64, v[8:9], off
	v_lshl_add_u64 v[8:9], v[8:9], 0, s[14:15]
	global_load_dword v66, v[8:9], off
	v_lshl_add_u64 v[8:9], v[8:9], 0, s[14:15]
	global_load_dword v68, v[8:9], off
	v_lshl_add_u64 v[8:9], v[8:9], 0, s[14:15]
	global_load_dword v70, v[8:9], off
	v_lshl_add_u64 v[8:9], v[8:9], 0, s[14:15]
	global_load_dword v72, v[8:9], off
	v_lshl_add_u64 v[8:9], v[8:9], 0, s[14:15]
	global_load_dword v74, v[8:9], off
	v_lshl_add_u64 v[8:9], v[8:9], 0, s[14:15]
	global_load_dword v76, v[8:9], off
	v_lshl_add_u64 v[8:9], v[8:9], 0, s[14:15]
	global_load_dword v78, v[8:9], off
	v_lshl_add_u64 v[8:9], v[8:9], 0, s[14:15]
	global_load_dword v80, v[8:9], off
	v_lshl_add_u64 v[8:9], v[8:9], 0, s[14:15]
	global_load_dword v82, v[8:9], off
	v_lshl_add_u64 v[8:9], v[8:9], 0, s[14:15]
	global_load_dword v84, v[8:9], off
	v_lshl_add_u64 v[8:9], v[8:9], 0, s[14:15]
	global_load_dword v86, v[8:9], off
	v_lshl_add_u64 v[8:9], v[8:9], 0, s[14:15]
	global_load_dword v88, v[8:9], off
	v_lshl_add_u64 v[8:9], v[8:9], 0, s[14:15]
	global_load_dword v90, v[8:9], off
	v_lshl_add_u64 v[8:9], v[8:9], 0, s[14:15]
	global_load_dword v92, v[8:9], off
	v_lshl_add_u64 v[8:9], v[8:9], 0, s[14:15]
	global_load_dword v94, v[8:9], off
	v_lshl_add_u64 v[8:9], v[8:9], 0, s[14:15]
	global_load_dword v96, v[8:9], off
	v_lshl_add_u64 v[8:9], v[8:9], 0, s[14:15]
	global_load_dword v98, v[8:9], off
	v_lshl_add_u64 v[8:9], v[8:9], 0, s[14:15]
	global_load_dword v100, v[8:9], off
	v_lshl_add_u64 v[8:9], v[8:9], 0, s[14:15]
	global_load_dword v102, v[8:9], off
	v_lshl_add_u64 v[8:9], v[8:9], 0, s[14:15]
	global_load_dword v104, v[8:9], off
	v_lshl_add_u64 v[8:9], v[8:9], 0, s[14:15]
	global_load_dword v106, v[8:9], off
	v_lshl_add_u64 v[8:9], v[8:9], 0, s[14:15]
	global_load_dword v108, v[8:9], off
	v_lshl_add_u64 v[8:9], v[8:9], 0, s[14:15]
	global_load_dword v110, v[8:9], off
	v_lshl_add_u64 v[8:9], v[8:9], 0, s[14:15]
	global_load_dword v112, v[8:9], off
	v_lshl_add_u64 v[8:9], v[8:9], 0, s[14:15]
	global_load_dword v114, v[8:9], off
	v_lshl_add_u64 v[8:9], v[8:9], 0, s[14:15]
	global_load_dword v116, v[8:9], off
	v_lshl_add_u64 v[8:9], v[8:9], 0, s[14:15]
	global_load_dword v118, v[8:9], off
	v_lshl_add_u64 v[8:9], v[8:9], 0, s[14:15]
	global_load_dword v120, v[8:9], off
	v_lshl_add_u64 v[8:9], v[8:9], 0, s[14:15]
	global_load_dword v122, v[8:9], off
	v_lshl_add_u64 v[8:9], v[8:9], 0, s[14:15]
	global_load_dword v124, v[8:9], off
	v_lshl_add_u64 v[8:9], v[8:9], 0, s[14:15]
	global_load_dword v126, v[8:9], off
	v_lshl_add_u64 v[8:9], v[8:9], 0, s[14:15]
	global_load_dword v128, v[8:9], off
	v_lshl_add_u64 v[8:9], v[8:9], 0, s[14:15]
	global_load_dword v130, v[8:9], off
	v_lshl_add_u64 v[8:9], v[8:9], 0, s[14:15]
	global_load_dword v132, v[8:9], off
	v_lshl_add_u64 v[8:9], v[8:9], 0, s[14:15]
	global_load_dword v134, v[8:9], off
	v_lshl_add_u64 v[8:9], v[8:9], 0, s[14:15]
	global_load_dword v136, v[8:9], off
	v_lshl_add_u64 v[8:9], v[8:9], 0, s[14:15]
	global_load_dword v138, v[8:9], off
	v_lshl_add_u64 v[8:9], v[8:9], 0, s[14:15]
	global_load_dword v140, v[8:9], off
	v_lshl_add_u64 v[8:9], v[8:9], 0, s[14:15]
	global_load_dword v142, v[8:9], off
	v_lshl_add_u64 v[8:9], v[8:9], 0, s[14:15]
	global_load_dword v144, v[8:9], off
	v_lshl_add_u64 v[8:9], v[8:9], 0, s[14:15]
	global_load_dword v146, v[8:9], off
	v_lshl_add_u64 v[8:9], v[8:9], 0, s[14:15]
	global_load_dword v148, v[8:9], off
	v_lshl_add_u64 v[8:9], v[8:9], 0, s[14:15]
	global_load_dword v150, v[8:9], off
	v_lshl_add_u64 v[8:9], v[8:9], 0, s[14:15]
	global_load_dword v152, v[8:9], off
	v_lshl_add_u64 v[8:9], v[8:9], 0, s[14:15]
	global_load_dword v154, v[8:9], off
	v_lshl_add_u64 v[8:9], v[8:9], 0, s[14:15]
	global_load_dword v156, v[8:9], off
	v_lshl_add_u64 v[8:9], v[8:9], 0, s[14:15]
	global_load_dword v158, v[8:9], off
	v_lshl_add_u64 v[8:9], v[8:9], 0, s[14:15]
	global_load_dword v164, v[8:9], off
	s_and_b64 vcc, exec, vcc
	s_mov_b32 s3, 64
	s_waitcnt vmcnt(63)
	v_readlane_b32 s16, v3, 0
	v_readlane_b32 s17, v11, 0
	v_readlane_b32 s18, v3, 1
	v_readlane_b32 s19, v11, 1
	v_readlane_b32 s20, v3, 2
	v_readlane_b32 s21, v11, 2
	v_pk_fma_f32 v[6:7], v[32:33], s[16:17], v[6:7] op_sel_hi:[0,1,1]
	v_readlane_b32 s22, v3, 3
	v_readlane_b32 s23, v11, 3
	s_waitcnt vmcnt(62)
	v_pk_fma_f32 v[6:7], v[34:35], s[18:19], v[6:7] op_sel_hi:[0,1,1]
	v_readlane_b32 s16, v3, 4
	v_readlane_b32 s17, v11, 4
	s_waitcnt vmcnt(61)
	v_pk_fma_f32 v[6:7], v[36:37], s[20:21], v[6:7] op_sel_hi:[0,1,1]
	v_readlane_b32 s18, v3, 5
	v_readlane_b32 s19, v11, 5
	s_waitcnt vmcnt(60)
	v_pk_fma_f32 v[6:7], v[38:39], s[22:23], v[6:7] op_sel_hi:[0,1,1]
	v_readlane_b32 s20, v3, 6
	v_readlane_b32 s21, v11, 6
	s_waitcnt vmcnt(59)
	v_pk_fma_f32 v[6:7], v[40:41], s[16:17], v[6:7] op_sel_hi:[0,1,1]
	v_readlane_b32 s22, v3, 7
	v_readlane_b32 s23, v11, 7
	s_waitcnt vmcnt(58)
	v_pk_fma_f32 v[6:7], v[42:43], s[18:19], v[6:7] op_sel_hi:[0,1,1]
	v_readlane_b32 s16, v3, 8
	v_readlane_b32 s17, v11, 8
	s_waitcnt vmcnt(57)
	v_pk_fma_f32 v[6:7], v[44:45], s[20:21], v[6:7] op_sel_hi:[0,1,1]
	v_readlane_b32 s18, v3, 9
	v_readlane_b32 s19, v11, 9
	s_waitcnt vmcnt(56)
	v_pk_fma_f32 v[6:7], v[46:47], s[22:23], v[6:7] op_sel_hi:[0,1,1]
	v_readlane_b32 s20, v3, 10
	v_readlane_b32 s21, v11, 10
	s_waitcnt vmcnt(55)
	v_pk_fma_f32 v[6:7], v[48:49], s[16:17], v[6:7] op_sel_hi:[0,1,1]
	v_readlane_b32 s22, v3, 11
	v_readlane_b32 s23, v11, 11
	s_waitcnt vmcnt(54)
	v_pk_fma_f32 v[6:7], v[50:51], s[18:19], v[6:7] op_sel_hi:[0,1,1]
	v_readlane_b32 s16, v3, 12
	v_readlane_b32 s17, v11, 12
	s_waitcnt vmcnt(53)
	v_pk_fma_f32 v[6:7], v[52:53], s[20:21], v[6:7] op_sel_hi:[0,1,1]
	v_readlane_b32 s18, v3, 13
	v_readlane_b32 s19, v11, 13
	s_waitcnt vmcnt(52)
	v_pk_fma_f32 v[6:7], v[54:55], s[22:23], v[6:7] op_sel_hi:[0,1,1]
	v_readlane_b32 s20, v3, 14
	v_readlane_b32 s21, v11, 14
	s_waitcnt vmcnt(51)
	v_pk_fma_f32 v[6:7], v[58:59], s[16:17], v[6:7] op_sel_hi:[0,1,1]
	v_readlane_b32 s22, v3, 15
	v_readlane_b32 s23, v11, 15
	s_waitcnt vmcnt(50)
	v_pk_fma_f32 v[6:7], v[60:61], s[18:19], v[6:7] op_sel_hi:[0,1,1]
	v_readlane_b32 s16, v3, 16
	v_readlane_b32 s17, v11, 16
	s_waitcnt vmcnt(49)
	v_pk_fma_f32 v[6:7], v[62:63], s[20:21], v[6:7] op_sel_hi:[0,1,1]
	v_readlane_b32 s18, v3, 17
	v_readlane_b32 s19, v11, 17
	s_waitcnt vmcnt(48)
	v_pk_fma_f32 v[6:7], v[64:65], s[22:23], v[6:7] op_sel_hi:[0,1,1]
	v_readlane_b32 s20, v3, 18
	v_readlane_b32 s21, v11, 18
	s_waitcnt vmcnt(47)
	v_pk_fma_f32 v[6:7], v[66:67], s[16:17], v[6:7] op_sel_hi:[0,1,1]
	v_readlane_b32 s22, v3, 19
	v_readlane_b32 s23, v11, 19
	s_waitcnt vmcnt(46)
	v_pk_fma_f32 v[6:7], v[68:69], s[18:19], v[6:7] op_sel_hi:[0,1,1]
	v_readlane_b32 s16, v3, 20
	v_readlane_b32 s17, v11, 20
	s_waitcnt vmcnt(45)
	v_pk_fma_f32 v[6:7], v[70:71], s[20:21], v[6:7] op_sel_hi:[0,1,1]
	v_readlane_b32 s18, v3, 21
	v_readlane_b32 s19, v11, 21
	s_waitcnt vmcnt(44)
	v_pk_fma_f32 v[6:7], v[72:73], s[22:23], v[6:7] op_sel_hi:[0,1,1]
	v_readlane_b32 s20, v3, 22
	v_readlane_b32 s21, v11, 22
	s_waitcnt vmcnt(43)
	v_pk_fma_f32 v[6:7], v[74:75], s[16:17], v[6:7] op_sel_hi:[0,1,1]
	v_readlane_b32 s22, v3, 23
	v_readlane_b32 s23, v11, 23
	s_waitcnt vmcnt(42)
	v_pk_fma_f32 v[6:7], v[76:77], s[18:19], v[6:7] op_sel_hi:[0,1,1]
	v_readlane_b32 s16, v3, 24
	v_readlane_b32 s17, v11, 24
	s_waitcnt vmcnt(41)
	v_pk_fma_f32 v[6:7], v[78:79], s[20:21], v[6:7] op_sel_hi:[0,1,1]
	v_readlane_b32 s18, v3, 25
	v_readlane_b32 s19, v11, 25
	s_waitcnt vmcnt(40)
	v_pk_fma_f32 v[6:7], v[80:81], s[22:23], v[6:7] op_sel_hi:[0,1,1]
	v_readlane_b32 s20, v3, 26
	v_readlane_b32 s21, v11, 26
	s_waitcnt vmcnt(39)
	v_pk_fma_f32 v[6:7], v[82:83], s[16:17], v[6:7] op_sel_hi:[0,1,1]
	v_readlane_b32 s22, v3, 27
	v_readlane_b32 s23, v11, 27
	s_waitcnt vmcnt(38)
	v_pk_fma_f32 v[6:7], v[84:85], s[18:19], v[6:7] op_sel_hi:[0,1,1]
	v_readlane_b32 s16, v3, 28
	v_readlane_b32 s17, v11, 28
	s_waitcnt vmcnt(37)
	v_pk_fma_f32 v[6:7], v[86:87], s[20:21], v[6:7] op_sel_hi:[0,1,1]
	v_readlane_b32 s18, v3, 29
	v_readlane_b32 s19, v11, 29
	s_waitcnt vmcnt(36)
	v_pk_fma_f32 v[6:7], v[88:89], s[22:23], v[6:7] op_sel_hi:[0,1,1]
	v_readlane_b32 s20, v3, 30
	v_readlane_b32 s21, v11, 30
	s_waitcnt vmcnt(35)
	v_pk_fma_f32 v[6:7], v[90:91], s[16:17], v[6:7] op_sel_hi:[0,1,1]
	v_readlane_b32 s22, v3, 31
	v_readlane_b32 s23, v11, 31
	s_waitcnt vmcnt(34)
	v_pk_fma_f32 v[6:7], v[92:93], s[18:19], v[6:7] op_sel_hi:[0,1,1]
	v_readlane_b32 s16, v3, 32
	v_readlane_b32 s17, v11, 32
	s_waitcnt vmcnt(33)
	v_pk_fma_f32 v[6:7], v[94:95], s[20:21], v[6:7] op_sel_hi:[0,1,1]
	v_readlane_b32 s18, v3, 33
	v_readlane_b32 s19, v11, 33
	s_waitcnt vmcnt(32)
	v_pk_fma_f32 v[6:7], v[96:97], s[22:23], v[6:7] op_sel_hi:[0,1,1]
	v_readlane_b32 s20, v3, 34
	v_readlane_b32 s21, v11, 34
	s_waitcnt vmcnt(31)
	v_pk_fma_f32 v[6:7], v[98:99], s[16:17], v[6:7] op_sel_hi:[0,1,1]
	v_readlane_b32 s22, v3, 35
	v_readlane_b32 s23, v11, 35
	s_waitcnt vmcnt(30)
	v_pk_fma_f32 v[6:7], v[100:101], s[18:19], v[6:7] op_sel_hi:[0,1,1]
	v_readlane_b32 s16, v3, 36
	v_readlane_b32 s17, v11, 36
	s_waitcnt vmcnt(29)
	v_pk_fma_f32 v[6:7], v[102:103], s[20:21], v[6:7] op_sel_hi:[0,1,1]
	v_readlane_b32 s18, v3, 37
	v_readlane_b32 s19, v11, 37
	s_waitcnt vmcnt(28)
	v_pk_fma_f32 v[6:7], v[104:105], s[22:23], v[6:7] op_sel_hi:[0,1,1]
	v_readlane_b32 s20, v3, 38
	v_readlane_b32 s21, v11, 38
	s_waitcnt vmcnt(27)
	v_pk_fma_f32 v[6:7], v[106:107], s[16:17], v[6:7] op_sel_hi:[0,1,1]
	v_readlane_b32 s22, v3, 39
	v_readlane_b32 s23, v11, 39
	s_waitcnt vmcnt(26)
	v_pk_fma_f32 v[6:7], v[108:109], s[18:19], v[6:7] op_sel_hi:[0,1,1]
	v_readlane_b32 s16, v3, 40
	v_readlane_b32 s17, v11, 40
	s_waitcnt vmcnt(25)
	v_pk_fma_f32 v[6:7], v[110:111], s[20:21], v[6:7] op_sel_hi:[0,1,1]
	v_readlane_b32 s18, v3, 41
	v_readlane_b32 s19, v11, 41
	s_waitcnt vmcnt(24)
	v_pk_fma_f32 v[6:7], v[112:113], s[22:23], v[6:7] op_sel_hi:[0,1,1]
	v_readlane_b32 s20, v3, 42
	v_readlane_b32 s21, v11, 42
	s_waitcnt vmcnt(23)
	v_pk_fma_f32 v[6:7], v[114:115], s[16:17], v[6:7] op_sel_hi:[0,1,1]
	v_readlane_b32 s22, v3, 43
	v_readlane_b32 s23, v11, 43
	s_waitcnt vmcnt(22)
	v_pk_fma_f32 v[6:7], v[116:117], s[18:19], v[6:7] op_sel_hi:[0,1,1]
	v_readlane_b32 s16, v3, 44
	v_readlane_b32 s17, v11, 44
	s_waitcnt vmcnt(21)
	v_pk_fma_f32 v[6:7], v[118:119], s[20:21], v[6:7] op_sel_hi:[0,1,1]
	v_readlane_b32 s18, v3, 45
	v_readlane_b32 s19, v11, 45
	s_waitcnt vmcnt(20)
	v_pk_fma_f32 v[6:7], v[120:121], s[22:23], v[6:7] op_sel_hi:[0,1,1]
	v_readlane_b32 s20, v3, 46
	v_readlane_b32 s21, v11, 46
	s_waitcnt vmcnt(19)
	v_pk_fma_f32 v[6:7], v[122:123], s[16:17], v[6:7] op_sel_hi:[0,1,1]
	v_readlane_b32 s22, v3, 47
	v_readlane_b32 s23, v11, 47
	s_waitcnt vmcnt(18)
	v_pk_fma_f32 v[6:7], v[124:125], s[18:19], v[6:7] op_sel_hi:[0,1,1]
	v_readlane_b32 s16, v3, 48
	v_readlane_b32 s17, v11, 48
	s_waitcnt vmcnt(17)
	v_pk_fma_f32 v[6:7], v[126:127], s[20:21], v[6:7] op_sel_hi:[0,1,1]
	v_readlane_b32 s18, v3, 49
	v_readlane_b32 s19, v11, 49
	s_waitcnt vmcnt(16)
	v_pk_fma_f32 v[6:7], v[128:129], s[22:23], v[6:7] op_sel_hi:[0,1,1]
	v_readlane_b32 s20, v3, 50
	v_readlane_b32 s21, v11, 50
	s_waitcnt vmcnt(15)
	v_pk_fma_f32 v[6:7], v[130:131], s[16:17], v[6:7] op_sel_hi:[0,1,1]
	v_readlane_b32 s22, v3, 51
	v_readlane_b32 s23, v11, 51
	s_waitcnt vmcnt(14)
	v_pk_fma_f32 v[6:7], v[132:133], s[18:19], v[6:7] op_sel_hi:[0,1,1]
	v_readlane_b32 s16, v3, 52
	v_readlane_b32 s17, v11, 52
	s_waitcnt vmcnt(13)
	v_pk_fma_f32 v[6:7], v[134:135], s[20:21], v[6:7] op_sel_hi:[0,1,1]
	v_readlane_b32 s18, v3, 53
	v_readlane_b32 s19, v11, 53
	s_waitcnt vmcnt(12)
	v_pk_fma_f32 v[6:7], v[136:137], s[22:23], v[6:7] op_sel_hi:[0,1,1]
	v_readlane_b32 s20, v3, 54
	v_readlane_b32 s21, v11, 54
	s_waitcnt vmcnt(11)
	v_pk_fma_f32 v[6:7], v[138:139], s[16:17], v[6:7] op_sel_hi:[0,1,1]
	v_readlane_b32 s22, v3, 55
	v_readlane_b32 s23, v11, 55
	s_waitcnt vmcnt(10)
	v_pk_fma_f32 v[6:7], v[140:141], s[18:19], v[6:7] op_sel_hi:[0,1,1]
	v_readlane_b32 s16, v3, 56
	v_readlane_b32 s17, v11, 56
	s_waitcnt vmcnt(9)
	v_pk_fma_f32 v[6:7], v[142:143], s[20:21], v[6:7] op_sel_hi:[0,1,1]
	v_readlane_b32 s18, v3, 57
	v_readlane_b32 s19, v11, 57
	s_waitcnt vmcnt(8)
	v_pk_fma_f32 v[6:7], v[144:145], s[22:23], v[6:7] op_sel_hi:[0,1,1]
	v_readlane_b32 s20, v3, 58
	v_readlane_b32 s21, v11, 58
	s_waitcnt vmcnt(7)
	v_pk_fma_f32 v[6:7], v[146:147], s[16:17], v[6:7] op_sel_hi:[0,1,1]
	v_readlane_b32 s22, v3, 59
	v_readlane_b32 s23, v11, 59
	s_waitcnt vmcnt(6)
	v_pk_fma_f32 v[6:7], v[148:149], s[18:19], v[6:7] op_sel_hi:[0,1,1]
	v_readlane_b32 s16, v3, 60
	v_readlane_b32 s17, v11, 60
	s_waitcnt vmcnt(5)
	v_pk_fma_f32 v[6:7], v[150:151], s[20:21], v[6:7] op_sel_hi:[0,1,1]
	v_readlane_b32 s18, v3, 61
	v_readlane_b32 s19, v11, 61
	s_waitcnt vmcnt(4)
	v_pk_fma_f32 v[6:7], v[152:153], s[22:23], v[6:7] op_sel_hi:[0,1,1]
	v_readlane_b32 s20, v3, 62
	v_readlane_b32 s21, v11, 62
	s_waitcnt vmcnt(3)
	v_pk_fma_f32 v[6:7], v[154:155], s[16:17], v[6:7] op_sel_hi:[0,1,1]
	v_readlane_b32 s22, v3, 63
	v_readlane_b32 s23, v11, 63
	s_waitcnt vmcnt(2)
	v_pk_fma_f32 v[6:7], v[156:157], s[18:19], v[6:7] op_sel_hi:[0,1,1]
	s_waitcnt vmcnt(1)
	v_pk_fma_f32 v[6:7], v[158:159], s[20:21], v[6:7] op_sel_hi:[0,1,1]
	s_waitcnt vmcnt(0)
	v_pk_fma_f32 v[6:7], v[164:165], s[22:23], v[6:7] op_sel_hi:[0,1,1]
	s_mov_b64 s[0:1], 0
	s_cbranch_vccz .LBB0_825
	v_readlane_b32 s2, v254, 51
	v_readlane_b32 s3, v254, 52
	s_and_saveexec_b64 s[0:1], s[2:3]
	v_readlane_b32 s62, v254, 0
	v_readlane_b32 s63, v254, 1
	s_cbranch_execz .LBB0_823
	v_ashrrev_i32_e32 v3, 31, v2
	v_readlane_b32 s4, v251, 34
	v_lshlrev_b64 v[2:3], 2, v[2:3]
	v_readlane_b32 s5, v251, 35
	s_nop 1
	v_lshl_add_u64 v[4:5], s[4:5], 0, v[2:3]
	v_lshl_add_u64 v[2:3], s[62:63], 0, v[2:3]
	global_atomic_add_f32 v[2:3], v6, off
	global_atomic_add_f32 v[4:5], v7, off
	s_branch .LBB0_823
